# speedup vs baseline: 1.0151x; 1.0049x over previous
; #define PG8_STAGE(bufoff, gbase, voff) do { _Pragma("unroll") for (int _i = 0; _i < 2; ++_i) \
;         __builtin_amdgcn_global_load_lds((const unsigned*)((const char*)(gbase) + (voff)[_i]), (PG8_LAS unsigned*)(lds + (bufoff) + ldsw + _i * 8192), 16, 0, 0); } while (0)
; #define PG8_LDA(dst, b, h) do { _Pragma("unroll") for (int m = 0; m < 4; ++m) _Pragma("unroll") for (int k = 0; k < 2; ++k) dst[m][k] = *(const PG8_LAS bf16x8*)(lds + PG8_SA(b, h) + aoff + m * 2048 + k * 1024); } while (0)
; #define PG8_LDB(dst, b, h) do { _Pragma("unroll") for (int n = 0; n < 2; ++n) _Pragma("unroll") for (int k = 0; k < 2; ++k) dst[n][k] = *(const PG8_LAS bf16x8*)(lds + PG8_SB(b, h) + boff + n * 2048 + k * 1024); } while (0)
; #define PG8_MMA(ai, bj, At, Bt) do { __builtin_amdgcn_s_setprio(1); _Pragma("unroll") for (int m = 0; m < 4; ++m) _Pragma("unroll") for (int n = 0; n < 2; ++n) _Pragma("unroll") for (int k = 0; k < 2; ++k) \
;         acc[ai][bj][m][n] = __builtin_amdgcn_mfma_f32_16x16x32_bf16(Bt[n][k], At[m][k], acc[ai][bj][m][n], 0, 0, 0); __builtin_amdgcn_s_setprio(0); } while (0)
; #define PG8_WAIT_V(n) asm volatile("s_waitcnt vmcnt(" #n ")" ::: "memory")
; #define PG8_WAIT_L(n) asm volatile("s_waitcnt lgkmcnt(" #n ")" ::: "memory")
; #define PG8_BAR __builtin_amdgcn_s_barrier()
; #define PG8_SCHED __builtin_amdgcn_sched_barrier(0)
; template <class Epi, class Sched, bool ALIGN_EPI = false, bool SP2 = false>
; __device__ __forceinline__ void gemm_phase(PG8_LAS unsigned char* lds, const Gemm g, const Sched& S, const Epi& E, int wid_s_) {
;     ...
;             PG8_LDB(B0, 0, 0); PG8_LDB(B1, 0, 1); PG8_SCHED; PG8_LDA(At, 0, 0); PG8_STAGE(PG8_SA(1, 1), a1 + hstep, voffA);
;             PG8_WAIT_V(8); PG8_WAIT_L(0); PG8_BAR; PG8_MMA(0, 0, At, B0); PG8_MMA(0, 1, At, B1); PG8_BAR; PG8_SCHED;
;             PG8_LDA(At, 0, 1); PG8_STAGE(PG8_SB(0, 0), b2, voffB); PG8_STAGE(PG8_SB(0, 1), b2 + hstep, voffB); PG8_STAGE(PG8_SA(0, 0), a2, voffA);
;             PG8_WAIT_V(8); PG8_WAIT_L(0); PG8_BAR; PG8_MMA(1, 0, At, B0); PG8_MMA(1, 1, At, B1); PG8_BAR; PG8_SCHED;
.LBB0_262:
	s_add_i32 s91, s24, 2
	s_add_u32 s14, s2, 0x80
	s_addc_u32 s25, s3, 0
	s_add_i32 s41, 16, 0x10000
	s_cmp_eq_u32 s88, s24
	s_cselect_b32 s25, s21, s25
	s_cselect_b32 s24, s20, s14
	v_add_u32_e32 v96, s41, v147
	s_cselect_b32 s79, s23, vcc_hi
	s_cselect_b32 s78, s22, vcc_lo
	s_add_i32 s14, 16, 0x14000
	ds_read_b128 v[132:135], v96
	ds_read_b128 v[136:139], v96 offset:1024
	ds_read_b128 v[160:163], v96 offset:2048
	ds_read_b128 v[164:167], v96 offset:3072
	v_add_u32_e32 v96, s14, v147
	ds_read_b128 v[168:171], v96
	ds_read_b128 v[172:175], v96 offset:1024
	ds_read_b128 v[176:179], v96 offset:2048
	ds_read_b128 v[180:183], v96 offset:3072
	s_add_i32 m0, s51, 0xc000
	ds_read_b128 v[194:197], v149
	ds_read_b128 v[198:201], v149 offset:1024
	ds_read_b128 v[202:205], v149 offset:2048
	ds_read_b128 v[206:209], v149 offset:3072
	ds_read_b128 v[210:213], v149 offset:4096
	ds_read_b128 v[214:217], v149 offset:5120
	ds_read_b128 v[218:221], v149 offset:6144
	ds_read_b128 v[222:225], v149 offset:7168
	global_load_lds_dwordx4 v156, s[2:3]
	s_add_i32 m0, s51, 0xe000
	s_nop 0
	global_load_lds_dwordx4 v154, s[2:3]
	s_waitcnt vmcnt(8)
	s_waitcnt lgkmcnt(0)
	s_barrier
	s_setprio 1
	s_waitcnt lgkmcnt(0)
	v_mfma_f32_16x16x32_bf16 v[128:131], v[132:135], v[194:197], v[128:131]
	v_mfma_f32_16x16x32_bf16 v[124:127], v[160:163], v[194:197], v[124:127]
	v_mfma_f32_16x16x32_bf16 v[120:123], v[132:135], v[202:205], v[120:123]
	v_mfma_f32_16x16x32_bf16 v[112:115], v[160:163], v[202:205], v[112:115]
	v_mfma_f32_16x16x32_bf16 v[104:107], v[132:135], v[210:213], v[104:107]
	v_mfma_f32_16x16x32_bf16 v[92:95], v[160:163], v[210:213], v[92:95]
	v_mfma_f32_16x16x32_bf16 v[84:87], v[132:135], v[218:221], v[84:87]
	v_mfma_f32_16x16x32_bf16 v[76:79], v[160:163], v[218:221], v[76:79]
	v_mfma_f32_16x16x32_bf16 v[128:131], v[136:139], v[198:201], v[128:131]
	v_mfma_f32_16x16x32_bf16 v[124:127], v[164:167], v[198:201], v[124:127]
	v_mfma_f32_16x16x32_bf16 v[120:123], v[136:139], v[206:209], v[120:123]
	v_mfma_f32_16x16x32_bf16 v[112:115], v[164:167], v[206:209], v[112:115]
	v_mfma_f32_16x16x32_bf16 v[104:107], v[136:139], v[214:217], v[104:107]
	v_mfma_f32_16x16x32_bf16 v[92:95], v[164:167], v[214:217], v[92:95]
	v_mfma_f32_16x16x32_bf16 v[84:87], v[136:139], v[222:225], v[84:87]
	v_mfma_f32_16x16x32_bf16 v[76:79], v[164:167], v[222:225], v[76:79]
	v_mfma_f32_16x16x32_bf16 v[116:119], v[168:171], v[194:197], v[116:119]
	v_mfma_f32_16x16x32_bf16 v[108:111], v[176:179], v[194:197], v[108:111]
	v_mfma_f32_16x16x32_bf16 v[98:101], v[168:171], v[202:205], v[100:103]
	v_mfma_f32_16x16x32_bf16 v[88:91], v[176:179], v[202:205], v[88:91]
	v_mfma_f32_16x16x32_bf16 v[80:83], v[168:171], v[210:213], v[80:83]
	v_mfma_f32_16x16x32_bf16 v[72:75], v[176:179], v[210:213], v[72:75]
	v_mfma_f32_16x16x32_bf16 v[68:71], v[168:171], v[218:221], v[68:71]
	v_mfma_f32_16x16x32_bf16 v[64:67], v[176:179], v[218:221], v[64:67]
	v_mfma_f32_16x16x32_bf16 v[116:119], v[172:175], v[198:201], v[116:119]
	v_mfma_f32_16x16x32_bf16 v[108:111], v[180:183], v[198:201], v[108:111]
	v_mfma_f32_16x16x32_bf16 v[98:101], v[172:175], v[206:209], v[98:101]
	v_mfma_f32_16x16x32_bf16 v[88:91], v[180:183], v[206:209], v[88:91]
	v_mfma_f32_16x16x32_bf16 v[80:83], v[172:175], v[214:217], v[80:83]
	v_mfma_f32_16x16x32_bf16 v[72:75], v[180:183], v[214:217], v[72:75]
	v_mfma_f32_16x16x32_bf16 v[68:71], v[172:175], v[222:225], v[68:71]
	v_mfma_f32_16x16x32_bf16 v[64:67], v[180:183], v[222:225], v[64:67]
	s_setprio 0
	s_barrier
	s_add_i32 s41, s41, s50
	s_mov_b32 m0, s41
	ds_read_b128 v[194:197], v149 offset:16384
	ds_read_b128 v[198:201], v149 offset:17408
	ds_read_b128 v[202:205], v149 offset:18432
	ds_read_b128 v[206:209], v149 offset:19456
	ds_read_b128 v[210:213], v149 offset:20480
	ds_read_b128 v[214:217], v149 offset:21504
	ds_read_b128 v[218:221], v149 offset:22528
	ds_read_b128 v[222:225], v149 offset:23552
	global_load_lds_dwordx4 v142, s[78:79]
	s_add_i32 m0, s41, 0x2000
	s_add_i32 s14, s14, s50
	global_load_lds_dwordx4 v152, s[78:79]
	s_mov_b32 m0, s14
	s_nop 0
	global_load_lds_dwordx4 v150, s[78:79]
	s_add_i32 m0, s14, 0x2000
	s_nop 0
	global_load_lds_dwordx4 v151, s[78:79]
	s_mov_b32 m0, s51
	s_nop 0
	global_load_lds_dwordx4 v140, s[24:25]
	s_mov_b32 m0, s80
	s_nop 0
	global_load_lds_dwordx4 v144, s[24:25]
	s_waitcnt vmcnt(8)
	s_waitcnt lgkmcnt(0)
	s_barrier
	s_setprio 1
	s_waitcnt lgkmcnt(0)
	v_mfma_f32_16x16x32_bf16 v[60:63], v[132:135], v[194:197], v[60:63]
	v_mfma_f32_16x16x32_bf16 v[56:59], v[160:163], v[194:197], v[56:59]
	v_mfma_f32_16x16x32_bf16 v[52:55], v[132:135], v[202:205], v[52:55]
	v_mfma_f32_16x16x32_bf16 v[48:51], v[160:163], v[202:205], v[48:51]
	v_mfma_f32_16x16x32_bf16 v[36:39], v[132:135], v[210:213], v[36:39]
	v_mfma_f32_16x16x32_bf16 v[32:35], v[160:163], v[210:213], v[32:35]
	v_mfma_f32_16x16x32_bf16 v[20:23], v[132:135], v[218:221], v[20:23]
	v_mfma_f32_16x16x32_bf16 v[16:19], v[160:163], v[218:221], v[16:19]
	v_mfma_f32_16x16x32_bf16 v[60:63], v[136:139], v[198:201], v[60:63]
	v_mfma_f32_16x16x32_bf16 v[56:59], v[164:167], v[198:201], v[56:59]
	v_mfma_f32_16x16x32_bf16 v[52:55], v[136:139], v[206:209], v[52:55]
	v_mfma_f32_16x16x32_bf16 v[48:51], v[164:167], v[206:209], v[48:51]
	v_mfma_f32_16x16x32_bf16 v[36:39], v[136:139], v[214:217], v[36:39]
	v_mfma_f32_16x16x32_bf16 v[32:35], v[164:167], v[214:217], v[32:35]
	v_mfma_f32_16x16x32_bf16 v[20:23], v[136:139], v[222:225], v[20:23]
	v_mfma_f32_16x16x32_bf16 v[16:19], v[164:167], v[222:225], v[16:19]
	v_mfma_f32_16x16x32_bf16 v[44:47], v[168:171], v[194:197], v[44:47]
	v_mfma_f32_16x16x32_bf16 v[40:43], v[176:179], v[194:197], v[40:43]
	v_mfma_f32_16x16x32_bf16 v[28:31], v[168:171], v[202:205], v[28:31]
	v_mfma_f32_16x16x32_bf16 v[24:27], v[176:179], v[202:205], v[24:27]
	v_mfma_f32_16x16x32_bf16 v[12:15], v[168:171], v[210:213], v[12:15]
	v_mfma_f32_16x16x32_bf16 v[8:11], v[176:179], v[210:213], v[8:11]
	v_mfma_f32_16x16x32_bf16 v[4:7], v[168:171], v[218:221], v[4:7]
	v_mfma_f32_16x16x32_bf16 v[0:3], v[176:179], v[218:221], v[0:3]
	v_mfma_f32_16x16x32_bf16 v[44:47], v[172:175], v[198:201], v[44:47]
	v_mfma_f32_16x16x32_bf16 v[40:43], v[180:183], v[198:201], v[40:43]
	v_mfma_f32_16x16x32_bf16 v[28:31], v[172:175], v[206:209], v[28:31]
	v_mfma_f32_16x16x32_bf16 v[24:27], v[180:183], v[206:209], v[24:27]
	v_mfma_f32_16x16x32_bf16 v[12:15], v[172:175], v[214:217], v[12:15]
	v_mfma_f32_16x16x32_bf16 v[8:11], v[180:183], v[214:217], v[8:11]
	v_mfma_f32_16x16x32_bf16 v[4:7], v[172:175], v[222:225], v[4:7]
	v_mfma_f32_16x16x32_bf16 v[0:3], v[180:183], v[222:225], v[0:3]
	s_setprio 0
	s_barrier
; #define PG8_STAGE(bufoff, gbase, voff) do { _Pragma("unroll") for (int _i = 0; _i < 2; ++_i) \
;         __builtin_amdgcn_global_load_lds((const unsigned*)((const char*)(gbase) + (voff)[_i]), (PG8_LAS unsigned*)(lds + (bufoff) + ldsw + _i * 8192), 16, 0, 0); } while (0)
; #define PG8_LDA(dst, b, h) do { _Pragma("unroll") for (int m = 0; m < 4; ++m) _Pragma("unroll") for (int k = 0; k < 2; ++k) dst[m][k] = *(const PG8_LAS bf16x8*)(lds + PG8_SA(b, h) + aoff + m * 2048 + k * 1024); } while (0)
; #define PG8_LDB(dst, b, h) do { _Pragma("unroll") for (int n = 0; n < 2; ++n) _Pragma("unroll") for (int k = 0; k < 2; ++k) dst[n][k] = *(const PG8_LAS bf16x8*)(lds + PG8_SB(b, h) + boff + n * 2048 + k * 1024); } while (0)
; #define PG8_MMA(ai, bj, At, Bt) do { __builtin_amdgcn_s_setprio(1); _Pragma("unroll") for (int m = 0; m < 4; ++m) _Pragma("unroll") for (int n = 0; n < 2; ++n) _Pragma("unroll") for (int k = 0; k < 2; ++k) \
;         acc[ai][bj][m][n] = __builtin_amdgcn_mfma_f32_16x16x32_bf16(Bt[n][k], At[m][k], acc[ai][bj][m][n], 0, 0, 0); __builtin_amdgcn_s_setprio(0); } while (0)
; #define PG8_WAIT_V(n) asm volatile("s_waitcnt vmcnt(" #n ")" ::: "memory")
; #define PG8_WAIT_L(n) asm volatile("s_waitcnt lgkmcnt(" #n ")" ::: "memory")
; #define PG8_BAR __builtin_amdgcn_s_barrier()
; #define PG8_SCHED __builtin_amdgcn_sched_barrier(0)
; template <class Epi, class Sched, bool ALIGN_EPI = false, bool SP2 = false>
; __device__ __forceinline__ void gemm_phase(PG8_LAS unsigned char* lds, const Gemm g, const Sched& S, const Epi& E, int wid_s_) {
;     ...
;         for (int t = 0; t < nt; t += 2) {
;             const bool last = (t == nt - 2);
;             const char* a1 = cA + (size_t)(t + 1) * kstep;
;             const char* a2 = last ? nA : cA + (size_t)(t + 2) * kstep; const char* b2 = last ? nB : cB + (size_t)(t + 2) * kstep;
;     ...
;             PG8_LDB(B0, 1, 0); PG8_LDB(B1, 1, 1); PG8_SCHED; PG8_LDA(At, 1, 0); PG8_STAGE(PG8_SA(0, 1), a2 + hstep, voffA);
;             PG8_WAIT_V(8); PG8_WAIT_L(0); PG8_BAR; PG8_MMA(0, 0, At, B0); PG8_MMA(0, 1, At, B1); PG8_BAR; PG8_SCHED;
;             PG8_LDA(At, 1, 1); PG8_STAGE(PG8_SB(1, 0), b3, voffB); PG8_STAGE(PG8_SB(1, 1), b3 + hstep, voffB); PG8_STAGE(PG8_SA(1, 0), a3, voffA);
;             PG8_WAIT_V(8); PG8_WAIT_L(0); PG8_BAR; PG8_MMA(1, 0, At, B0); PG8_MMA(1, 1, At, B1); PG8_BAR; PG8_SCHED;
	s_add_i32 s14, 16, 0x18000
	v_add_u32_e32 v96, s14, v147
	s_add_i32 s41, 16, 0x1c000
	ds_read_b128 v[132:135], v96
	ds_read_b128 v[136:139], v96 offset:1024
	ds_read_b128 v[160:163], v96 offset:2048
	ds_read_b128 v[164:167], v96 offset:3072
	v_add_u32_e32 v96, s41, v147
	ds_read_b128 v[168:171], v96
	ds_read_b128 v[172:175], v96 offset:1024
	ds_read_b128 v[176:179], v96 offset:2048
	ds_read_b128 v[180:183], v96 offset:3072
	s_mov_b32 m0, s81
	ds_read_b128 v[194:197], v149 offset:32768
	ds_read_b128 v[198:201], v149 offset:33792
	ds_read_b128 v[202:205], v149 offset:34816
	ds_read_b128 v[206:209], v149 offset:35840
	ds_read_b128 v[210:213], v149 offset:36864
	ds_read_b128 v[214:217], v149 offset:37888
	ds_read_b128 v[218:221], v149 offset:38912
	ds_read_b128 v[222:225], v149 offset:39936
	global_load_lds_dwordx4 v158, s[24:25]
	s_mov_b32 m0, s82
	s_nop 0
	global_load_lds_dwordx4 v159, s[24:25]
	s_waitcnt vmcnt(8)
	s_waitcnt lgkmcnt(0)
	s_barrier
	s_setprio 1
	s_waitcnt lgkmcnt(0)
	v_mfma_f32_16x16x32_bf16 v[128:131], v[132:135], v[194:197], v[128:131]
	v_mfma_f32_16x16x32_bf16 v[124:127], v[160:163], v[194:197], v[124:127]
	v_mfma_f32_16x16x32_bf16 v[120:123], v[132:135], v[202:205], v[120:123]
	v_mfma_f32_16x16x32_bf16 v[112:115], v[160:163], v[202:205], v[112:115]
	v_mfma_f32_16x16x32_bf16 v[102:105], v[132:135], v[210:213], v[104:107]
	v_mfma_f32_16x16x32_bf16 v[92:95], v[160:163], v[210:213], v[92:95]
	v_mfma_f32_16x16x32_bf16 v[84:87], v[132:135], v[218:221], v[84:87]
	v_mfma_f32_16x16x32_bf16 v[76:79], v[160:163], v[218:221], v[76:79]
	v_mfma_f32_16x16x32_bf16 v[128:131], v[136:139], v[198:201], v[128:131]
	v_mfma_f32_16x16x32_bf16 v[124:127], v[164:167], v[198:201], v[124:127]
	v_mfma_f32_16x16x32_bf16 v[120:123], v[136:139], v[206:209], v[120:123]
	v_mfma_f32_16x16x32_bf16 v[112:115], v[164:167], v[206:209], v[112:115]
	v_mfma_f32_16x16x32_bf16 v[104:107], v[136:139], v[214:217], v[102:105]
	v_mfma_f32_16x16x32_bf16 v[92:95], v[164:167], v[214:217], v[92:95]
	v_mfma_f32_16x16x32_bf16 v[84:87], v[136:139], v[222:225], v[84:87]
	v_mfma_f32_16x16x32_bf16 v[76:79], v[164:167], v[222:225], v[76:79]
	v_mfma_f32_16x16x32_bf16 v[116:119], v[168:171], v[194:197], v[116:119]
	v_mfma_f32_16x16x32_bf16 v[108:111], v[176:179], v[194:197], v[108:111]
	v_mfma_f32_16x16x32_bf16 v[98:101], v[168:171], v[202:205], v[98:101]
	v_mfma_f32_16x16x32_bf16 v[88:91], v[176:179], v[202:205], v[88:91]
	v_mfma_f32_16x16x32_bf16 v[80:83], v[168:171], v[210:213], v[80:83]
	v_mfma_f32_16x16x32_bf16 v[72:75], v[176:179], v[210:213], v[72:75]
	v_mfma_f32_16x16x32_bf16 v[68:71], v[168:171], v[218:221], v[68:71]
	v_mfma_f32_16x16x32_bf16 v[64:67], v[176:179], v[218:221], v[64:67]
	v_mfma_f32_16x16x32_bf16 v[116:119], v[172:175], v[198:201], v[116:119]
	v_mfma_f32_16x16x32_bf16 v[108:111], v[180:183], v[198:201], v[108:111]
	v_mfma_f32_16x16x32_bf16 v[100:103], v[172:175], v[206:209], v[98:101]
	v_mfma_f32_16x16x32_bf16 v[88:91], v[180:183], v[206:209], v[88:91]
	v_mfma_f32_16x16x32_bf16 v[80:83], v[172:175], v[214:217], v[80:83]
	v_mfma_f32_16x16x32_bf16 v[72:75], v[180:183], v[214:217], v[72:75]
	v_mfma_f32_16x16x32_bf16 v[68:71], v[172:175], v[222:225], v[68:71]
	v_mfma_f32_16x16x32_bf16 v[64:67], v[180:183], v[222:225], v[64:67]
	s_setprio 0
	s_barrier
	s_add_i32 s14, s14, s50
	s_mov_b32 m0, s14
	ds_read_b128 v[194:197], v149 offset:49152
	ds_read_b128 v[198:201], v149 offset:50176
	ds_read_b128 v[202:205], v149 offset:51200
	ds_read_b128 v[206:209], v149 offset:52224
	ds_read_b128 v[210:213], v149 offset:53248
	ds_read_b128 v[214:217], v149 offset:54272
	ds_read_b128 v[218:221], v149 offset:55296
	ds_read_b128 v[222:225], v149 offset:56320
	global_load_lds_dwordx4 v188, s[78:79]
	s_add_i32 m0, s14, 0x2000
	s_add_i32 s14, s41, s50
	global_load_lds_dwordx4 v189, s[78:79]
	s_mov_b32 m0, s14
	s_nop 0
	global_load_lds_dwordx4 v192, s[78:79]
	s_add_i32 m0, s14, 0x2000
	s_nop 0
	global_load_lds_dwordx4 v193, s[78:79]
	s_mov_b32 m0, s85
	s_nop 0
	global_load_lds_dwordx4 v226, s[24:25]
	s_mov_b32 m0, s86
	s_nop 0
	global_load_lds_dwordx4 v227, s[24:25]
	s_waitcnt vmcnt(8)
	s_waitcnt lgkmcnt(0)
	s_barrier
	s_setprio 1
	s_waitcnt lgkmcnt(0)
	v_mfma_f32_16x16x32_bf16 v[60:63], v[132:135], v[194:197], v[60:63]
	v_mfma_f32_16x16x32_bf16 v[56:59], v[160:163], v[194:197], v[56:59]
	v_mfma_f32_16x16x32_bf16 v[52:55], v[132:135], v[202:205], v[52:55]
	v_mfma_f32_16x16x32_bf16 v[48:51], v[160:163], v[202:205], v[48:51]
	v_mfma_f32_16x16x32_bf16 v[36:39], v[132:135], v[210:213], v[36:39]
	v_mfma_f32_16x16x32_bf16 v[32:35], v[160:163], v[210:213], v[32:35]
	v_mfma_f32_16x16x32_bf16 v[20:23], v[132:135], v[218:221], v[20:23]
	v_mfma_f32_16x16x32_bf16 v[16:19], v[160:163], v[218:221], v[16:19]
	v_mfma_f32_16x16x32_bf16 v[60:63], v[136:139], v[198:201], v[60:63]
	v_mfma_f32_16x16x32_bf16 v[56:59], v[164:167], v[198:201], v[56:59]
	v_mfma_f32_16x16x32_bf16 v[52:55], v[136:139], v[206:209], v[52:55]
	v_mfma_f32_16x16x32_bf16 v[48:51], v[164:167], v[206:209], v[48:51]
	v_mfma_f32_16x16x32_bf16 v[36:39], v[136:139], v[214:217], v[36:39]
	v_mfma_f32_16x16x32_bf16 v[32:35], v[164:167], v[214:217], v[32:35]
	v_mfma_f32_16x16x32_bf16 v[20:23], v[136:139], v[222:225], v[20:23]
	v_mfma_f32_16x16x32_bf16 v[16:19], v[164:167], v[222:225], v[16:19]
	v_mfma_f32_16x16x32_bf16 v[44:47], v[168:171], v[194:197], v[44:47]
	v_mfma_f32_16x16x32_bf16 v[40:43], v[176:179], v[194:197], v[40:43]
	v_mfma_f32_16x16x32_bf16 v[28:31], v[168:171], v[202:205], v[28:31]
	v_mfma_f32_16x16x32_bf16 v[24:27], v[176:179], v[202:205], v[24:27]
	v_mfma_f32_16x16x32_bf16 v[12:15], v[168:171], v[210:213], v[12:15]
	v_mfma_f32_16x16x32_bf16 v[8:11], v[176:179], v[210:213], v[8:11]
	v_mfma_f32_16x16x32_bf16 v[4:7], v[168:171], v[218:221], v[4:7]
	v_mfma_f32_16x16x32_bf16 v[0:3], v[176:179], v[218:221], v[0:3]
	v_mfma_f32_16x16x32_bf16 v[44:47], v[172:175], v[198:201], v[44:47]
	v_mfma_f32_16x16x32_bf16 v[40:43], v[180:183], v[198:201], v[40:43]
	v_mfma_f32_16x16x32_bf16 v[28:31], v[172:175], v[206:209], v[28:31]
	v_mfma_f32_16x16x32_bf16 v[24:27], v[180:183], v[206:209], v[24:27]
	v_mfma_f32_16x16x32_bf16 v[12:15], v[172:175], v[214:217], v[12:15]
	v_mfma_f32_16x16x32_bf16 v[8:11], v[180:183], v[214:217], v[8:11]
	v_mfma_f32_16x16x32_bf16 v[4:7], v[172:175], v[222:225], v[4:7]
	v_mfma_f32_16x16x32_bf16 v[0:3], v[180:183], v[222:225], v[0:3]
	s_setprio 0
	s_barrier
	s_add_u32 vcc_lo, vcc_lo, 0x100
	s_addc_u32 vcc_hi, vcc_hi, 0
	s_add_u32 s2, s2, 0x100
	s_addc_u32 s3, s3, 0
	s_cmp_ge_i32 s91, s87
	s_mov_b32 s24, s91
	s_cbranch_scc0 .LBB0_262
	v_add_u32_e32 v192, 64, v191
	s_and_b64 vcc, exec, s[18:19]
	s_cbranch_vccnz .LBB0_267
	s_branch .LBB0_268

; #define PG8_STAGE(bufoff, gbase, voff) do { _Pragma("unroll") for (int _i = 0; _i < 2; ++_i) \
;         __builtin_amdgcn_global_load_lds((const unsigned*)((const char*)(gbase) + (voff)[_i]), (PG8_LAS unsigned*)(lds + (bufoff) + ldsw + _i * 8192), 16, 0, 0); } while (0)
; #define PG8_LDA(dst, b, h) do { _Pragma("unroll") for (int m = 0; m < 4; ++m) _Pragma("unroll") for (int k = 0; k < 2; ++k) dst[m][k] = *(const PG8_LAS bf16x8*)(lds + PG8_SA(b, h) + aoff + m * 2048 + k * 1024); } while (0)
; #define PG8_LDB(dst, b, h) do { _Pragma("unroll") for (int n = 0; n < 2; ++n) _Pragma("unroll") for (int k = 0; k < 2; ++k) dst[n][k] = *(const PG8_LAS bf16x8*)(lds + PG8_SB(b, h) + boff + n * 2048 + k * 1024); } while (0)
; #define PG8_MMA(ai, bj, At, Bt) do { __builtin_amdgcn_s_setprio(1); _Pragma("unroll") for (int m = 0; m < 4; ++m) _Pragma("unroll") for (int n = 0; n < 2; ++n) _Pragma("unroll") for (int k = 0; k < 2; ++k) \
;         acc[ai][bj][m][n] = __builtin_amdgcn_mfma_f32_16x16x32_bf16(Bt[n][k], At[m][k], acc[ai][bj][m][n], 0, 0, 0); __builtin_amdgcn_s_setprio(0); } while (0)
; #define PG8_WAIT_V(n) asm volatile("s_waitcnt vmcnt(" #n ")" ::: "memory")
; #define PG8_WAIT_L(n) asm volatile("s_waitcnt lgkmcnt(" #n ")" ::: "memory")
; template <class Epi, class Sched, bool ALIGN_EPI = false, bool SP2 = false>
; __device__ __forceinline__ void gemm_phase(PG8_LAS unsigned char* lds, const Gemm g, const Sched& S, const Epi& E, int wid_s_) {
;     ...
;             const bool last = (t == nt - 2);
;             const char* a1 = cA + (size_t)(t + 1) * kstep;
;             const char* a2 = last ? nA : cA + (size_t)(t + 2) * kstep; const char* b2 = last ? nB : cB + (size_t)(t + 2) * kstep;
;             const char* a3 = a2 + kstep; const char* b3 = b2 + kstep;
;             if (last && has_next) S.a_ready(nxt);
;             if constexpr (SP2) {
;             PG8_LDB(B0, 0, 0); PG8_LDB(B1, 0, 1); PG8_SCHED; PG8_LDA(At, 0, 0); PG8_STAGE(PG8_SA(1, 1), a1 + hstep, voffA);
;             PG8_WAIT_V(8); PG8_WAIT_L(0); PG8_BAR; PG8_MMA(0, 0, At, B0); PG8_MMA(0, 1, At, B1); PG8_BAR; PG8_SCHED;
;             PG8_LDA(At, 0, 1); PG8_STAGE(PG8_SB(0, 0), b2, voffB); PG8_STAGE(PG8_SB(0, 1), b2 + hstep, voffB); PG8_STAGE(PG8_SA(0, 0), a2, voffA);
;             PG8_WAIT_V(8); PG8_WAIT_L(0); PG8_BAR; PG8_MMA(1, 0, At, B0); PG8_MMA(1, 1, At, B1); PG8_BAR; PG8_SCHED;
.LBB0_384:
	s_add_i32 vcc_lo, s48, 2
	s_add_u32 s78, s24, 0x80
	s_addc_u32 s49, s25, 0
	s_add_i32 vcc_hi, 16, 0x10000
	s_cmp_eq_u32 s87, s48
	s_cselect_b32 s49, s3, s49
	s_cselect_b32 s48, s2, s78
	v_add_u32_e32 v96, vcc_hi, v147
	s_cselect_b32 s79, s23, s81
	s_cselect_b32 s78, s22, s80
	s_add_i32 s40, 16, 0x14000
	ds_read_b128 v[130:133], v96
	ds_read_b128 v[134:137], v96 offset:1024
	ds_read_b128 v[138:141], v96 offset:2048
	ds_read_b128 v[142:145], v96 offset:3072
	v_add_u32_e32 v96, s40, v147
	ds_read_b128 v[168:171], v96
	ds_read_b128 v[172:175], v96 offset:1024
	ds_read_b128 v[176:179], v96 offset:2048
	ds_read_b128 v[180:183], v96 offset:3072
	v_lshl_add_u64 v[150:151], s[24:25], 0, v[166:167]
	s_add_i32 m0, s51, 0xc000
	ds_read_b128 v[194:197], v148
	ds_read_b128 v[198:201], v148 offset:1024
	ds_read_b128 v[202:205], v148 offset:2048
	ds_read_b128 v[206:209], v148 offset:3072
	ds_read_b128 v[210:213], v148 offset:4096
	ds_read_b128 v[214:217], v148 offset:5120
	ds_read_b128 v[218:221], v148 offset:6144
	ds_read_b128 v[222:225], v148 offset:7168
	global_load_lds_dwordx4 v[150:151], off
	v_lshl_add_u64 v[150:151], s[24:25], 0, v[164:165]
	s_add_i32 m0, s51, 0xe000
	s_nop 0
	global_load_lds_dwordx4 v[150:151], off
	s_waitcnt vmcnt(8)
	s_waitcnt lgkmcnt(0)
	s_barrier
	s_setprio 1
	s_waitcnt lgkmcnt(0)
	v_mfma_f32_16x16x32_bf16 v[122:125], v[130:133], v[194:197], v[122:125]
	v_mfma_f32_16x16x32_bf16 v[118:121], v[138:141], v[194:197], v[118:121]
	v_mfma_f32_16x16x32_bf16 v[92:95], v[130:133], v[202:205], v[92:95]
	v_mfma_f32_16x16x32_bf16 v[84:87], v[138:141], v[202:205], v[84:87]
	v_mfma_f32_16x16x32_bf16 v[60:63], v[130:133], v[210:213], v[60:63]
	v_mfma_f32_16x16x32_bf16 v[52:55], v[138:141], v[210:213], v[52:55]
	v_mfma_f32_16x16x32_bf16 v[28:31], v[130:133], v[218:221], v[28:31]
	v_mfma_f32_16x16x32_bf16 v[20:23], v[138:141], v[218:221], v[20:23]
	v_mfma_f32_16x16x32_bf16 v[122:125], v[134:137], v[198:201], v[122:125]
	v_mfma_f32_16x16x32_bf16 v[118:121], v[142:145], v[198:201], v[118:121]
	v_mfma_f32_16x16x32_bf16 v[92:95], v[134:137], v[206:209], v[92:95]
	v_mfma_f32_16x16x32_bf16 v[84:87], v[142:145], v[206:209], v[84:87]
	v_mfma_f32_16x16x32_bf16 v[60:63], v[134:137], v[214:217], v[60:63]
	v_mfma_f32_16x16x32_bf16 v[52:55], v[142:145], v[214:217], v[52:55]
	v_mfma_f32_16x16x32_bf16 v[28:31], v[134:137], v[222:225], v[28:31]
	v_mfma_f32_16x16x32_bf16 v[20:23], v[142:145], v[222:225], v[20:23]
	v_mfma_f32_16x16x32_bf16 v[110:113], v[168:171], v[194:197], v[110:113]
	v_mfma_f32_16x16x32_bf16 v[102:105], v[176:179], v[194:197], v[102:105]
	v_mfma_f32_16x16x32_bf16 v[76:79], v[168:171], v[202:205], v[76:79]
	v_mfma_f32_16x16x32_bf16 v[68:71], v[176:179], v[202:205], v[68:71]
	v_mfma_f32_16x16x32_bf16 v[44:47], v[168:171], v[210:213], v[44:47]
	v_mfma_f32_16x16x32_bf16 v[36:39], v[176:179], v[210:213], v[36:39]
	v_mfma_f32_16x16x32_bf16 v[12:15], v[168:171], v[218:221], v[12:15]
	v_mfma_f32_16x16x32_bf16 v[4:7], v[176:179], v[218:221], v[4:7]
	v_mfma_f32_16x16x32_bf16 v[110:113], v[172:175], v[198:201], v[110:113]
	v_mfma_f32_16x16x32_bf16 v[102:105], v[180:183], v[198:201], v[102:105]
	v_mfma_f32_16x16x32_bf16 v[76:79], v[172:175], v[206:209], v[76:79]
	v_mfma_f32_16x16x32_bf16 v[68:71], v[180:183], v[206:209], v[68:71]
	v_mfma_f32_16x16x32_bf16 v[44:47], v[172:175], v[214:217], v[44:47]
	v_mfma_f32_16x16x32_bf16 v[36:39], v[180:183], v[214:217], v[36:39]
	v_mfma_f32_16x16x32_bf16 v[12:15], v[172:175], v[222:225], v[12:15]
	v_mfma_f32_16x16x32_bf16 v[4:7], v[180:183], v[222:225], v[4:7]
	s_setprio 0
	s_barrier
	s_add_i32 vcc_hi, vcc_hi, s50
	v_lshl_add_u64 v[150:151], s[78:79], 0, v[154:155]
	s_mov_b32 m0, vcc_hi
	ds_read_b128 v[194:197], v148 offset:16384
	ds_read_b128 v[198:201], v148 offset:17408
	ds_read_b128 v[202:205], v148 offset:18432
	ds_read_b128 v[206:209], v148 offset:19456
	ds_read_b128 v[210:213], v148 offset:20480
	ds_read_b128 v[214:217], v148 offset:21504
	ds_read_b128 v[218:221], v148 offset:22528
	ds_read_b128 v[222:225], v148 offset:23552
	global_load_lds_dwordx4 v[150:151], off
	s_add_i32 m0, vcc_hi, 0x2000
	v_lshl_add_u64 v[188:189], s[78:79], 0, v[158:159]
	s_add_u32 s78, s78, s10
	s_addc_u32 s79, s79, s11
	s_add_i32 s40, s40, s50
	global_load_lds_dwordx4 v[188:189], off
	v_lshl_add_u64 v[192:193], s[78:79], 0, v[154:155]
	s_mov_b32 m0, s40
	v_lshl_add_u64 v[226:227], s[78:79], 0, v[158:159]
	global_load_lds_dwordx4 v[192:193], off
	s_add_i32 m0, s40, 0x2000
	v_lshl_add_u64 v[228:229], s[48:49], 0, v[152:153]
	global_load_lds_dwordx4 v[226:227], off
	s_mov_b32 m0, s51
	v_lshl_add_u64 v[230:231], s[48:49], 0, v[156:157]
	global_load_lds_dwordx4 v[228:229], off
	s_mov_b32 m0, s82
	s_nop 0
	global_load_lds_dwordx4 v[230:231], off
	s_waitcnt vmcnt(8)
	s_waitcnt lgkmcnt(0)
	s_barrier
; #define PG8_STAGE(bufoff, gbase, voff) do { _Pragma("unroll") for (int _i = 0; _i < 2; ++_i) \
;         __builtin_amdgcn_global_load_lds((const unsigned*)((const char*)(gbase) + (voff)[_i]), (PG8_LAS unsigned*)(lds + (bufoff) + ldsw + _i * 8192), 16, 0, 0); } while (0)
; #define PG8_LDA(dst, b, h) do { _Pragma("unroll") for (int m = 0; m < 4; ++m) _Pragma("unroll") for (int k = 0; k < 2; ++k) dst[m][k] = *(const PG8_LAS bf16x8*)(lds + PG8_SA(b, h) + aoff + m * 2048 + k * 1024); } while (0)
; #define PG8_LDB(dst, b, h) do { _Pragma("unroll") for (int n = 0; n < 2; ++n) _Pragma("unroll") for (int k = 0; k < 2; ++k) dst[n][k] = *(const PG8_LAS bf16x8*)(lds + PG8_SB(b, h) + boff + n * 2048 + k * 1024); } while (0)
; #define PG8_MMA(ai, bj, At, Bt) do { __builtin_amdgcn_s_setprio(1); _Pragma("unroll") for (int m = 0; m < 4; ++m) _Pragma("unroll") for (int n = 0; n < 2; ++n) _Pragma("unroll") for (int k = 0; k < 2; ++k) \
;         acc[ai][bj][m][n] = __builtin_amdgcn_mfma_f32_16x16x32_bf16(Bt[n][k], At[m][k], acc[ai][bj][m][n], 0, 0, 0); __builtin_amdgcn_s_setprio(0); } while (0)
; #define PG8_WAIT_V(n) asm volatile("s_waitcnt vmcnt(" #n ")" ::: "memory")
; #define PG8_WAIT_L(n) asm volatile("s_waitcnt lgkmcnt(" #n ")" ::: "memory")
; #define PG8_BAR __builtin_amdgcn_s_barrier()
; #define PG8_SCHED __builtin_amdgcn_sched_barrier(0)
; template <class Epi, class Sched, bool ALIGN_EPI = false, bool SP2 = false>
; __device__ __forceinline__ void gemm_phase(PG8_LAS unsigned char* lds, const Gemm g, const Sched& S, const Epi& E, int wid_s_) {
;     ...
;             PG8_WAIT_V(8); PG8_WAIT_L(0); PG8_BAR; PG8_MMA(1, 0, At, B0); PG8_MMA(1, 1, At, B1); PG8_BAR; PG8_SCHED;
;             PG8_LDB(B0, 1, 0); PG8_LDB(B1, 1, 1); PG8_SCHED; PG8_LDA(At, 1, 0); PG8_STAGE(PG8_SA(0, 1), a2 + hstep, voffA);
;             PG8_WAIT_V(8); PG8_WAIT_L(0); PG8_BAR; PG8_MMA(0, 0, At, B0); PG8_MMA(0, 1, At, B1); PG8_BAR; PG8_SCHED;
	s_setprio 1
	s_waitcnt lgkmcnt(0)
	v_mfma_f32_16x16x32_bf16 v[126:129], v[130:133], v[194:197], v[126:129]
	v_mfma_f32_16x16x32_bf16 v[114:117], v[138:141], v[194:197], v[114:117]
	v_mfma_f32_16x16x32_bf16 v[88:91], v[130:133], v[202:205], v[88:91]
	v_mfma_f32_16x16x32_bf16 v[80:83], v[138:141], v[202:205], v[80:83]
	v_mfma_f32_16x16x32_bf16 v[56:59], v[130:133], v[210:213], v[56:59]
	v_mfma_f32_16x16x32_bf16 v[48:51], v[138:141], v[210:213], v[48:51]
	v_mfma_f32_16x16x32_bf16 v[24:27], v[130:133], v[218:221], v[24:27]
	v_mfma_f32_16x16x32_bf16 v[16:19], v[138:141], v[218:221], v[16:19]
	v_mfma_f32_16x16x32_bf16 v[126:129], v[134:137], v[198:201], v[126:129]
	v_mfma_f32_16x16x32_bf16 v[114:117], v[142:145], v[198:201], v[114:117]
	v_mfma_f32_16x16x32_bf16 v[88:91], v[134:137], v[206:209], v[88:91]
	v_mfma_f32_16x16x32_bf16 v[80:83], v[142:145], v[206:209], v[80:83]
	v_mfma_f32_16x16x32_bf16 v[56:59], v[134:137], v[214:217], v[56:59]
	v_mfma_f32_16x16x32_bf16 v[48:51], v[142:145], v[214:217], v[48:51]
	v_mfma_f32_16x16x32_bf16 v[24:27], v[134:137], v[222:225], v[24:27]
	v_mfma_f32_16x16x32_bf16 v[16:19], v[142:145], v[222:225], v[16:19]
	v_mfma_f32_16x16x32_bf16 v[106:109], v[168:171], v[194:197], v[106:109]
	v_mfma_f32_16x16x32_bf16 v[98:101], v[176:179], v[194:197], v[98:101]
	v_mfma_f32_16x16x32_bf16 v[72:75], v[168:171], v[202:205], v[72:75]
	v_mfma_f32_16x16x32_bf16 v[64:67], v[176:179], v[202:205], v[64:67]
	v_mfma_f32_16x16x32_bf16 v[40:43], v[168:171], v[210:213], v[40:43]
	v_mfma_f32_16x16x32_bf16 v[32:35], v[176:179], v[210:213], v[32:35]
	v_mfma_f32_16x16x32_bf16 v[8:11], v[168:171], v[218:221], v[8:11]
	v_mfma_f32_16x16x32_bf16 v[0:3], v[176:179], v[218:221], v[0:3]
	v_mfma_f32_16x16x32_bf16 v[106:109], v[172:175], v[198:201], v[106:109]
	v_mfma_f32_16x16x32_bf16 v[98:101], v[180:183], v[198:201], v[98:101]
	v_mfma_f32_16x16x32_bf16 v[72:75], v[172:175], v[206:209], v[72:75]
	v_mfma_f32_16x16x32_bf16 v[64:67], v[180:183], v[206:209], v[64:67]
	v_mfma_f32_16x16x32_bf16 v[40:43], v[172:175], v[214:217], v[40:43]
	v_mfma_f32_16x16x32_bf16 v[32:35], v[180:183], v[214:217], v[32:35]
	v_mfma_f32_16x16x32_bf16 v[8:11], v[172:175], v[222:225], v[8:11]
	v_mfma_f32_16x16x32_bf16 v[0:3], v[180:183], v[222:225], v[0:3]
	s_setprio 0
	s_barrier
	s_add_i32 s40, 16, 0x18000
	v_add_u32_e32 v96, s40, v147
	s_add_i32 s78, 16, 0x1c000
	ds_read_b128 v[130:133], v96
	ds_read_b128 v[134:137], v96 offset:1024
	ds_read_b128 v[138:141], v96 offset:2048
	ds_read_b128 v[142:145], v96 offset:3072
	v_add_u32_e32 v96, s78, v147
	ds_read_b128 v[168:171], v96
	ds_read_b128 v[172:175], v96 offset:1024
	ds_read_b128 v[176:179], v96 offset:2048
	ds_read_b128 v[180:183], v96 offset:3072
	s_add_u32 s48, s48, s10
	s_addc_u32 s49, s49, s11
	s_mov_b32 m0, s83
	v_lshl_add_u64 v[232:233], s[48:49], 0, v[152:153]
	ds_read_b128 v[194:197], v148 offset:32768
	ds_read_b128 v[198:201], v148 offset:33792
	ds_read_b128 v[202:205], v148 offset:34816
	ds_read_b128 v[206:209], v148 offset:35840
	ds_read_b128 v[210:213], v148 offset:36864
	ds_read_b128 v[214:217], v148 offset:37888
	ds_read_b128 v[218:221], v148 offset:38912
	ds_read_b128 v[222:225], v148 offset:39936
	global_load_lds_dwordx4 v[232:233], off
	v_lshl_add_u64 v[232:233], s[48:49], 0, v[156:157]
	s_mov_b32 m0, s84
	s_nop 0
	global_load_lds_dwordx4 v[232:233], off
	s_waitcnt vmcnt(8)
	s_waitcnt lgkmcnt(0)
	s_barrier
	s_setprio 1
	s_waitcnt lgkmcnt(0)
	v_mfma_f32_16x16x32_bf16 v[122:125], v[130:133], v[194:197], v[122:125]
	v_mfma_f32_16x16x32_bf16 v[118:121], v[138:141], v[194:197], v[118:121]
	v_mfma_f32_16x16x32_bf16 v[92:95], v[130:133], v[202:205], v[92:95]
	v_mfma_f32_16x16x32_bf16 v[84:87], v[138:141], v[202:205], v[84:87]
	v_mfma_f32_16x16x32_bf16 v[60:63], v[130:133], v[210:213], v[60:63]
	v_mfma_f32_16x16x32_bf16 v[52:55], v[138:141], v[210:213], v[52:55]
	v_mfma_f32_16x16x32_bf16 v[28:31], v[130:133], v[218:221], v[28:31]
	v_mfma_f32_16x16x32_bf16 v[20:23], v[138:141], v[218:221], v[20:23]
	v_mfma_f32_16x16x32_bf16 v[122:125], v[134:137], v[198:201], v[122:125]
	v_mfma_f32_16x16x32_bf16 v[118:121], v[142:145], v[198:201], v[118:121]
	v_mfma_f32_16x16x32_bf16 v[92:95], v[134:137], v[206:209], v[92:95]
	v_mfma_f32_16x16x32_bf16 v[84:87], v[142:145], v[206:209], v[84:87]
	v_mfma_f32_16x16x32_bf16 v[60:63], v[134:137], v[214:217], v[60:63]
	v_mfma_f32_16x16x32_bf16 v[52:55], v[142:145], v[214:217], v[52:55]
	v_mfma_f32_16x16x32_bf16 v[28:31], v[134:137], v[222:225], v[28:31]
	v_mfma_f32_16x16x32_bf16 v[20:23], v[142:145], v[222:225], v[20:23]
	v_mfma_f32_16x16x32_bf16 v[110:113], v[168:171], v[194:197], v[110:113]
	v_mfma_f32_16x16x32_bf16 v[102:105], v[176:179], v[194:197], v[102:105]
	v_mfma_f32_16x16x32_bf16 v[76:79], v[168:171], v[202:205], v[76:79]
	v_mfma_f32_16x16x32_bf16 v[68:71], v[176:179], v[202:205], v[68:71]
	v_mfma_f32_16x16x32_bf16 v[44:47], v[168:171], v[210:213], v[44:47]
	v_mfma_f32_16x16x32_bf16 v[36:39], v[176:179], v[210:213], v[36:39]
	v_mfma_f32_16x16x32_bf16 v[12:15], v[168:171], v[218:221], v[12:15]
	v_mfma_f32_16x16x32_bf16 v[4:7], v[176:179], v[218:221], v[4:7]
	v_mfma_f32_16x16x32_bf16 v[110:113], v[172:175], v[198:201], v[110:113]
	v_mfma_f32_16x16x32_bf16 v[102:105], v[180:183], v[198:201], v[102:105]
	v_mfma_f32_16x16x32_bf16 v[76:79], v[172:175], v[206:209], v[76:79]
	v_mfma_f32_16x16x32_bf16 v[68:71], v[180:183], v[206:209], v[68:71]
	v_mfma_f32_16x16x32_bf16 v[44:47], v[172:175], v[214:217], v[44:47]
	v_mfma_f32_16x16x32_bf16 v[36:39], v[180:183], v[214:217], v[36:39]
	v_mfma_f32_16x16x32_bf16 v[12:15], v[172:175], v[222:225], v[12:15]
	v_mfma_f32_16x16x32_bf16 v[4:7], v[180:183], v[222:225], v[4:7]
	s_setprio 0
	s_barrier
; #define PG8_STAGE(bufoff, gbase, voff) do { _Pragma("unroll") for (int _i = 0; _i < 2; ++_i) \
;         __builtin_amdgcn_global_load_lds((const unsigned*)((const char*)(gbase) + (voff)[_i]), (PG8_LAS unsigned*)(lds + (bufoff) + ldsw + _i * 8192), 16, 0, 0); } while (0)
; #define PG8_LDA(dst, b, h) do { _Pragma("unroll") for (int m = 0; m < 4; ++m) _Pragma("unroll") for (int k = 0; k < 2; ++k) dst[m][k] = *(const PG8_LAS bf16x8*)(lds + PG8_SA(b, h) + aoff + m * 2048 + k * 1024); } while (0)
; #define PG8_MMA(ai, bj, At, Bt) do { __builtin_amdgcn_s_setprio(1); _Pragma("unroll") for (int m = 0; m < 4; ++m) _Pragma("unroll") for (int n = 0; n < 2; ++n) _Pragma("unroll") for (int k = 0; k < 2; ++k) \
;         acc[ai][bj][m][n] = __builtin_amdgcn_mfma_f32_16x16x32_bf16(Bt[n][k], At[m][k], acc[ai][bj][m][n], 0, 0, 0); __builtin_amdgcn_s_setprio(0); } while (0)
; #define PG8_WAIT_V(n) asm volatile("s_waitcnt vmcnt(" #n ")" ::: "memory")
; #define PG8_WAIT_L(n) asm volatile("s_waitcnt lgkmcnt(" #n ")" ::: "memory")
; #define PG8_BAR __builtin_amdgcn_s_barrier()
; #define PG8_SCHED __builtin_amdgcn_sched_barrier(0)
; template <class Epi, class Sched, bool ALIGN_EPI = false, bool SP2 = false>
; __device__ __forceinline__ void gemm_phase(PG8_LAS unsigned char* lds, const Gemm g, const Sched& S, const Epi& E, int wid_s_) {
;     ...
;             PG8_LDA(At, 1, 1); PG8_STAGE(PG8_SB(1, 0), b3, voffB); PG8_STAGE(PG8_SB(1, 1), b3 + hstep, voffB); PG8_STAGE(PG8_SA(1, 0), a3, voffA);
;             PG8_WAIT_V(8); PG8_WAIT_L(0); PG8_BAR; PG8_MMA(1, 0, At, B0); PG8_MMA(1, 1, At, B1); PG8_BAR; PG8_SCHED;
	s_add_i32 s40, s40, s50
	v_lshl_add_u64 v[150:151], v[150:151], 0, s[42:43]
	s_mov_b32 m0, s40
	ds_read_b128 v[194:197], v148 offset:49152
	ds_read_b128 v[198:201], v148 offset:50176
	ds_read_b128 v[202:205], v148 offset:51200
	ds_read_b128 v[206:209], v148 offset:52224
	ds_read_b128 v[210:213], v148 offset:53248
	ds_read_b128 v[214:217], v148 offset:54272
	ds_read_b128 v[218:221], v148 offset:55296
	ds_read_b128 v[222:225], v148 offset:56320
	global_load_lds_dwordx4 v[150:151], off
	v_lshl_add_u64 v[150:151], v[188:189], 0, s[42:43]
	s_add_i32 m0, s40, 0x2000
	s_add_i32 s40, s78, s50
	global_load_lds_dwordx4 v[150:151], off
	v_lshl_add_u64 v[150:151], v[192:193], 0, s[42:43]
	s_mov_b32 m0, s40
	s_nop 0
	global_load_lds_dwordx4 v[150:151], off
	v_lshl_add_u64 v[150:151], v[226:227], 0, s[42:43]
	s_add_i32 m0, s40, 0x2000
	s_nop 0
	global_load_lds_dwordx4 v[150:151], off
	v_lshl_add_u64 v[150:151], v[228:229], 0, s[42:43]
	s_mov_b32 m0, s85
	s_nop 0
	global_load_lds_dwordx4 v[150:151], off
	v_lshl_add_u64 v[150:151], v[230:231], 0, s[42:43]
	s_mov_b32 m0, s86
	s_nop 0
	global_load_lds_dwordx4 v[150:151], off
	s_waitcnt vmcnt(8)
	s_waitcnt lgkmcnt(0)
	s_barrier
	s_setprio 1
	s_waitcnt lgkmcnt(0)
	v_mfma_f32_16x16x32_bf16 v[126:129], v[130:133], v[194:197], v[126:129]
	v_mfma_f32_16x16x32_bf16 v[114:117], v[138:141], v[194:197], v[114:117]
	v_mfma_f32_16x16x32_bf16 v[88:91], v[130:133], v[202:205], v[88:91]
	v_mfma_f32_16x16x32_bf16 v[80:83], v[138:141], v[202:205], v[80:83]
	v_mfma_f32_16x16x32_bf16 v[56:59], v[130:133], v[210:213], v[56:59]
	v_mfma_f32_16x16x32_bf16 v[48:51], v[138:141], v[210:213], v[48:51]
	v_mfma_f32_16x16x32_bf16 v[24:27], v[130:133], v[218:221], v[24:27]
	v_mfma_f32_16x16x32_bf16 v[16:19], v[138:141], v[218:221], v[16:19]
	v_mfma_f32_16x16x32_bf16 v[126:129], v[134:137], v[198:201], v[126:129]
	v_mfma_f32_16x16x32_bf16 v[114:117], v[142:145], v[198:201], v[114:117]
	v_mfma_f32_16x16x32_bf16 v[88:91], v[134:137], v[206:209], v[88:91]
	v_mfma_f32_16x16x32_bf16 v[80:83], v[142:145], v[206:209], v[80:83]
	v_mfma_f32_16x16x32_bf16 v[56:59], v[134:137], v[214:217], v[56:59]
	v_mfma_f32_16x16x32_bf16 v[48:51], v[142:145], v[214:217], v[48:51]
	v_mfma_f32_16x16x32_bf16 v[24:27], v[134:137], v[222:225], v[24:27]
	v_mfma_f32_16x16x32_bf16 v[16:19], v[142:145], v[222:225], v[16:19]
	v_mfma_f32_16x16x32_bf16 v[106:109], v[168:171], v[194:197], v[106:109]
	v_mfma_f32_16x16x32_bf16 v[98:101], v[176:179], v[194:197], v[98:101]
	v_mfma_f32_16x16x32_bf16 v[72:75], v[168:171], v[202:205], v[72:75]
	v_mfma_f32_16x16x32_bf16 v[64:67], v[176:179], v[202:205], v[64:67]
	v_mfma_f32_16x16x32_bf16 v[40:43], v[168:171], v[210:213], v[40:43]
	v_mfma_f32_16x16x32_bf16 v[32:35], v[176:179], v[210:213], v[32:35]
	v_mfma_f32_16x16x32_bf16 v[8:11], v[168:171], v[218:221], v[8:11]
	v_mfma_f32_16x16x32_bf16 v[0:3], v[176:179], v[218:221], v[0:3]
	v_mfma_f32_16x16x32_bf16 v[106:109], v[172:175], v[198:201], v[106:109]
	v_mfma_f32_16x16x32_bf16 v[98:101], v[180:183], v[198:201], v[98:101]
	v_mfma_f32_16x16x32_bf16 v[72:75], v[172:175], v[206:209], v[72:75]
	v_mfma_f32_16x16x32_bf16 v[64:67], v[180:183], v[206:209], v[64:67]
	v_mfma_f32_16x16x32_bf16 v[40:43], v[172:175], v[214:217], v[40:43]
	v_mfma_f32_16x16x32_bf16 v[32:35], v[180:183], v[214:217], v[32:35]
	v_mfma_f32_16x16x32_bf16 v[8:11], v[172:175], v[222:225], v[8:11]
	v_mfma_f32_16x16x32_bf16 v[0:3], v[180:183], v[222:225], v[0:3]
	s_setprio 0
	s_barrier
	s_add_u32 s80, s80, 0x100
	s_addc_u32 s81, s81, 0
	s_add_u32 s24, s24, 0x100
	s_addc_u32 s25, s25, 0
	s_cmp_ge_i32 vcc_lo, s4
	s_mov_b32 s48, vcc_lo
	s_cbranch_scc0 .LBB0_384
	s_movk_i32 s80, 0x4000
	v_add_u32_e32 v192, 64, v191

; #define PG8_STAGE(bufoff, gbase, voff) do { _Pragma("unroll") for (int _i = 0; _i < 2; ++_i) \
;         __builtin_amdgcn_global_load_lds((const unsigned*)((const char*)(gbase) + (voff)[_i]), (PG8_LAS unsigned*)(lds + (bufoff) + ldsw + _i * 8192), 16, 0, 0); } while (0)
; #define PG8_LDA(dst, b, h) do { _Pragma("unroll") for (int m = 0; m < 4; ++m) _Pragma("unroll") for (int k = 0; k < 2; ++k) dst[m][k] = *(const PG8_LAS bf16x8*)(lds + PG8_SA(b, h) + aoff + m * 2048 + k * 1024); } while (0)
; #define PG8_LDB(dst, b, h) do { _Pragma("unroll") for (int n = 0; n < 2; ++n) _Pragma("unroll") for (int k = 0; k < 2; ++k) dst[n][k] = *(const PG8_LAS bf16x8*)(lds + PG8_SB(b, h) + boff + n * 2048 + k * 1024); } while (0)
; #define PG8_MMA(ai, bj, At, Bt) do { __builtin_amdgcn_s_setprio(1); _Pragma("unroll") for (int m = 0; m < 4; ++m) _Pragma("unroll") for (int n = 0; n < 2; ++n) _Pragma("unroll") for (int k = 0; k < 2; ++k) \
;         acc[ai][bj][m][n] = __builtin_amdgcn_mfma_f32_16x16x32_bf16(Bt[n][k], At[m][k], acc[ai][bj][m][n], 0, 0, 0); __builtin_amdgcn_s_setprio(0); } while (0)
; #define PG8_WAIT_V(n) asm volatile("s_waitcnt vmcnt(" #n ")" ::: "memory")
; #define PG8_WAIT_L(n) asm volatile("s_waitcnt lgkmcnt(" #n ")" ::: "memory")
; template <class Epi, class Sched, bool ALIGN_EPI = false, bool SP2 = false>
; __device__ __forceinline__ void gemm_phase(PG8_LAS unsigned char* lds, const Gemm g, const Sched& S, const Epi& E, int wid_s_) {
;     ...
;             const bool last = (t == nt - 2);
;             const char* a1 = cA + (size_t)(t + 1) * kstep;
;             const char* a2 = last ? nA : cA + (size_t)(t + 2) * kstep; const char* b2 = last ? nB : cB + (size_t)(t + 2) * kstep;
;             const char* a3 = a2 + kstep; const char* b3 = b2 + kstep;
;             if (last && has_next) S.a_ready(nxt);
;             if constexpr (SP2) {
;             PG8_LDB(B0, 0, 0); PG8_LDB(B1, 0, 1); PG8_SCHED; PG8_LDA(At, 0, 0); PG8_STAGE(PG8_SA(1, 1), a1 + hstep, voffA);
;             PG8_WAIT_V(8); PG8_WAIT_L(0); PG8_BAR; PG8_MMA(0, 0, At, B0); PG8_MMA(0, 1, At, B1); PG8_BAR; PG8_SCHED;
;             PG8_LDA(At, 0, 1); PG8_STAGE(PG8_SB(0, 0), b2, voffB); PG8_STAGE(PG8_SB(0, 1), b2 + hstep, voffB); PG8_STAGE(PG8_SA(0, 0), a2, voffA);
;             PG8_WAIT_V(8); PG8_WAIT_L(0); PG8_BAR; PG8_MMA(1, 0, At, B0); PG8_MMA(1, 1, At, B1); PG8_BAR; PG8_SCHED;
.LBB0_466:
	s_add_i32 vcc_hi, s48, 2
	s_add_u32 s78, s24, 0x80
	s_addc_u32 s49, s25, 0
	s_add_i32 s26, 16, 0x10000
	s_cmp_eq_u32 s85, s48
	s_cselect_b32 s49, s3, s49
	s_cselect_b32 s48, s2, s78
	v_add_u32_e32 v96, s26, v146
	s_cselect_b32 s79, s23, vcc_lo
	s_cselect_b32 s78, s22, s91
	s_add_i32 s37, 16, 0x14000
	ds_read_b128 v[156:159], v96
	ds_read_b128 v[160:163], v96 offset:1024
	ds_read_b128 v[164:167], v96 offset:2048
	ds_read_b128 v[168:171], v96 offset:3072
	v_add_u32_e32 v96, s37, v146
	ds_read_b128 v[172:175], v96
	ds_read_b128 v[176:179], v96 offset:1024
	ds_read_b128 v[180:183], v96 offset:2048
	ds_read_b128 v[194:197], v96 offset:3072
	s_add_i32 m0, s50, 0xc000
	ds_read_b128 v[198:201], v148
	ds_read_b128 v[202:205], v148 offset:1024
	ds_read_b128 v[206:209], v148 offset:2048
	ds_read_b128 v[210:213], v148 offset:3072
	ds_read_b128 v[214:217], v148 offset:4096
	ds_read_b128 v[218:221], v148 offset:5120
	ds_read_b128 v[222:225], v148 offset:6144
	ds_read_b128 v[226:229], v148 offset:7168
	global_load_lds_dwordx4 v154, s[24:25]
	s_add_i32 m0, s50, 0xe000
	s_nop 0
	global_load_lds_dwordx4 v152, s[24:25]
	s_waitcnt vmcnt(8)
	s_waitcnt lgkmcnt(0)
	s_barrier
	s_setprio 1
	s_waitcnt lgkmcnt(0)
	v_mfma_f32_16x16x32_bf16 v[122:125], v[156:159], v[198:201], v[122:125]
	v_mfma_f32_16x16x32_bf16 v[126:129], v[164:167], v[198:201], v[126:129]
	v_mfma_f32_16x16x32_bf16 v[118:121], v[156:159], v[206:209], v[118:121]
	v_mfma_f32_16x16x32_bf16 v[114:117], v[164:167], v[206:209], v[114:117]
	v_mfma_f32_16x16x32_bf16 v[110:113], v[156:159], v[214:217], v[110:113]
	v_mfma_f32_16x16x32_bf16 v[106:109], v[164:167], v[214:217], v[106:109]
	v_mfma_f32_16x16x32_bf16 v[102:105], v[156:159], v[222:225], v[102:105]
	v_mfma_f32_16x16x32_bf16 v[98:101], v[164:167], v[222:225], v[98:101]
	v_mfma_f32_16x16x32_bf16 v[122:125], v[160:163], v[202:205], v[122:125]
	v_mfma_f32_16x16x32_bf16 v[126:129], v[168:171], v[202:205], v[126:129]
	v_mfma_f32_16x16x32_bf16 v[118:121], v[160:163], v[210:213], v[118:121]
	v_mfma_f32_16x16x32_bf16 v[114:117], v[168:171], v[210:213], v[114:117]
	v_mfma_f32_16x16x32_bf16 v[110:113], v[160:163], v[218:221], v[110:113]
	v_mfma_f32_16x16x32_bf16 v[106:109], v[168:171], v[218:221], v[106:109]
	v_mfma_f32_16x16x32_bf16 v[102:105], v[160:163], v[226:229], v[102:105]
	v_mfma_f32_16x16x32_bf16 v[98:101], v[168:171], v[226:229], v[98:101]
	v_mfma_f32_16x16x32_bf16 v[60:63], v[172:175], v[198:201], v[60:63]
	v_mfma_f32_16x16x32_bf16 v[56:59], v[180:183], v[198:201], v[56:59]
	v_mfma_f32_16x16x32_bf16 v[52:55], v[172:175], v[206:209], v[52:55]
	v_mfma_f32_16x16x32_bf16 v[48:51], v[180:183], v[206:209], v[48:51]
	v_mfma_f32_16x16x32_bf16 v[44:47], v[172:175], v[214:217], v[44:47]
	v_mfma_f32_16x16x32_bf16 v[40:43], v[180:183], v[214:217], v[40:43]
	v_mfma_f32_16x16x32_bf16 v[36:39], v[172:175], v[222:225], v[36:39]
	v_mfma_f32_16x16x32_bf16 v[32:35], v[180:183], v[222:225], v[32:35]
	v_mfma_f32_16x16x32_bf16 v[60:63], v[176:179], v[202:205], v[60:63]
	v_mfma_f32_16x16x32_bf16 v[56:59], v[194:197], v[202:205], v[56:59]
	v_mfma_f32_16x16x32_bf16 v[52:55], v[176:179], v[210:213], v[52:55]
	v_mfma_f32_16x16x32_bf16 v[48:51], v[194:197], v[210:213], v[48:51]
	v_mfma_f32_16x16x32_bf16 v[44:47], v[176:179], v[218:221], v[44:47]
	v_mfma_f32_16x16x32_bf16 v[40:43], v[194:197], v[218:221], v[40:43]
	v_mfma_f32_16x16x32_bf16 v[36:39], v[176:179], v[226:229], v[36:39]
	v_mfma_f32_16x16x32_bf16 v[32:35], v[194:197], v[226:229], v[32:35]
	s_setprio 0
	s_barrier
	s_add_i32 s26, s26, s40
	s_mov_b32 m0, s26
	ds_read_b128 v[198:201], v148 offset:16384
	ds_read_b128 v[202:205], v148 offset:17408
	ds_read_b128 v[206:209], v148 offset:18432
	ds_read_b128 v[210:213], v148 offset:19456
	ds_read_b128 v[214:217], v148 offset:20480
	ds_read_b128 v[218:221], v148 offset:21504
	ds_read_b128 v[222:225], v148 offset:22528
	ds_read_b128 v[226:229], v148 offset:23552
	global_load_lds_dwordx4 v134, s[78:79]
	s_add_i32 m0, s26, 0x2000
	s_add_i32 s26, s37, s40
	global_load_lds_dwordx4 v130, s[78:79]
	s_mov_b32 m0, s26
	s_nop 0
	global_load_lds_dwordx4 v150, s[78:79]
	s_add_i32 m0, s26, 0x2000
	s_nop 0
	global_load_lds_dwordx4 v151, s[78:79]
	s_mov_b32 m0, s50
	s_nop 0
	global_load_lds_dwordx4 v136, s[48:49]
	s_mov_b32 m0, s51
	s_nop 0
	global_load_lds_dwordx4 v132, s[48:49]
	s_waitcnt vmcnt(8)
	s_waitcnt lgkmcnt(0)
	s_barrier
	s_setprio 1
	s_waitcnt lgkmcnt(0)
	v_mfma_f32_16x16x32_bf16 v[92:95], v[156:159], v[198:201], v[92:95]
	v_mfma_f32_16x16x32_bf16 v[88:91], v[164:167], v[198:201], v[88:91]
	v_mfma_f32_16x16x32_bf16 v[84:87], v[156:159], v[206:209], v[84:87]
	v_mfma_f32_16x16x32_bf16 v[80:83], v[164:167], v[206:209], v[80:83]
	v_mfma_f32_16x16x32_bf16 v[76:79], v[156:159], v[214:217], v[76:79]
	v_mfma_f32_16x16x32_bf16 v[72:75], v[164:167], v[214:217], v[72:75]
	v_mfma_f32_16x16x32_bf16 v[68:71], v[156:159], v[222:225], v[68:71]
	v_mfma_f32_16x16x32_bf16 v[64:67], v[164:167], v[222:225], v[64:67]
	v_mfma_f32_16x16x32_bf16 v[92:95], v[160:163], v[202:205], v[92:95]
	v_mfma_f32_16x16x32_bf16 v[88:91], v[168:171], v[202:205], v[88:91]
	v_mfma_f32_16x16x32_bf16 v[84:87], v[160:163], v[210:213], v[84:87]
	v_mfma_f32_16x16x32_bf16 v[80:83], v[168:171], v[210:213], v[80:83]
	v_mfma_f32_16x16x32_bf16 v[76:79], v[160:163], v[218:221], v[76:79]
	v_mfma_f32_16x16x32_bf16 v[72:75], v[168:171], v[218:221], v[72:75]
	v_mfma_f32_16x16x32_bf16 v[68:71], v[160:163], v[226:229], v[68:71]
	v_mfma_f32_16x16x32_bf16 v[64:67], v[168:171], v[226:229], v[64:67]
	v_mfma_f32_16x16x32_bf16 v[28:31], v[172:175], v[198:201], v[28:31]
	v_mfma_f32_16x16x32_bf16 v[24:27], v[180:183], v[198:201], v[24:27]
	v_mfma_f32_16x16x32_bf16 v[20:23], v[172:175], v[206:209], v[20:23]
	v_mfma_f32_16x16x32_bf16 v[16:19], v[180:183], v[206:209], v[16:19]
	v_mfma_f32_16x16x32_bf16 v[12:15], v[172:175], v[214:217], v[12:15]
	v_mfma_f32_16x16x32_bf16 v[8:11], v[180:183], v[214:217], v[8:11]
	v_mfma_f32_16x16x32_bf16 v[4:7], v[172:175], v[222:225], v[4:7]
	v_mfma_f32_16x16x32_bf16 v[0:3], v[180:183], v[222:225], v[0:3]
	v_mfma_f32_16x16x32_bf16 v[28:31], v[176:179], v[202:205], v[28:31]
	v_mfma_f32_16x16x32_bf16 v[24:27], v[194:197], v[202:205], v[24:27]
	v_mfma_f32_16x16x32_bf16 v[20:23], v[176:179], v[210:213], v[20:23]
	v_mfma_f32_16x16x32_bf16 v[16:19], v[194:197], v[210:213], v[16:19]
	v_mfma_f32_16x16x32_bf16 v[12:15], v[176:179], v[218:221], v[12:15]
	v_mfma_f32_16x16x32_bf16 v[8:11], v[194:197], v[218:221], v[8:11]
	v_mfma_f32_16x16x32_bf16 v[4:7], v[176:179], v[226:229], v[4:7]
	v_mfma_f32_16x16x32_bf16 v[0:3], v[194:197], v[226:229], v[0:3]
	s_setprio 0
	s_barrier
; #define PG8_STAGE(bufoff, gbase, voff) do { _Pragma("unroll") for (int _i = 0; _i < 2; ++_i) \
;         __builtin_amdgcn_global_load_lds((const unsigned*)((const char*)(gbase) + (voff)[_i]), (PG8_LAS unsigned*)(lds + (bufoff) + ldsw + _i * 8192), 16, 0, 0); } while (0)
; #define PG8_LDA(dst, b, h) do { _Pragma("unroll") for (int m = 0; m < 4; ++m) _Pragma("unroll") for (int k = 0; k < 2; ++k) dst[m][k] = *(const PG8_LAS bf16x8*)(lds + PG8_SA(b, h) + aoff + m * 2048 + k * 1024); } while (0)
; #define PG8_LDB(dst, b, h) do { _Pragma("unroll") for (int n = 0; n < 2; ++n) _Pragma("unroll") for (int k = 0; k < 2; ++k) dst[n][k] = *(const PG8_LAS bf16x8*)(lds + PG8_SB(b, h) + boff + n * 2048 + k * 1024); } while (0)
; #define PG8_MMA(ai, bj, At, Bt) do { __builtin_amdgcn_s_setprio(1); _Pragma("unroll") for (int m = 0; m < 4; ++m) _Pragma("unroll") for (int n = 0; n < 2; ++n) _Pragma("unroll") for (int k = 0; k < 2; ++k) \
;         acc[ai][bj][m][n] = __builtin_amdgcn_mfma_f32_16x16x32_bf16(Bt[n][k], At[m][k], acc[ai][bj][m][n], 0, 0, 0); __builtin_amdgcn_s_setprio(0); } while (0)
; #define PG8_WAIT_V(n) asm volatile("s_waitcnt vmcnt(" #n ")" ::: "memory")
; #define PG8_WAIT_L(n) asm volatile("s_waitcnt lgkmcnt(" #n ")" ::: "memory")
; #define PG8_BAR __builtin_amdgcn_s_barrier()
; #define PG8_SCHED __builtin_amdgcn_sched_barrier(0)
; template <class Epi, class Sched, bool ALIGN_EPI = false, bool SP2 = false>
; __device__ __forceinline__ void gemm_phase(PG8_LAS unsigned char* lds, const Gemm g, const Sched& S, const Epi& E, int wid_s_) {
;     ...
;             PG8_LDB(B0, 1, 0); PG8_LDB(B1, 1, 1); PG8_SCHED; PG8_LDA(At, 1, 0); PG8_STAGE(PG8_SA(0, 1), a2 + hstep, voffA);
;             PG8_WAIT_V(8); PG8_WAIT_L(0); PG8_BAR; PG8_MMA(0, 0, At, B0); PG8_MMA(0, 1, At, B1); PG8_BAR; PG8_SCHED;
;             PG8_LDA(At, 1, 1); PG8_STAGE(PG8_SB(1, 0), b3, voffB); PG8_STAGE(PG8_SB(1, 1), b3 + hstep, voffB); PG8_STAGE(PG8_SA(1, 0), a3, voffA);
;             PG8_WAIT_V(8); PG8_WAIT_L(0); PG8_BAR; PG8_MMA(1, 0, At, B0); PG8_MMA(1, 1, At, B1); PG8_BAR; PG8_SCHED;
	s_add_i32 s26, 16, 0x18000
	v_add_u32_e32 v96, s26, v146
	s_add_i32 s37, 16, 0x1c000
	ds_read_b128 v[156:159], v96
	ds_read_b128 v[160:163], v96 offset:1024
	ds_read_b128 v[164:167], v96 offset:2048
	ds_read_b128 v[168:171], v96 offset:3072
	v_add_u32_e32 v96, s37, v146
	ds_read_b128 v[172:175], v96
	ds_read_b128 v[176:179], v96 offset:1024
	ds_read_b128 v[180:183], v96 offset:2048
	ds_read_b128 v[194:197], v96 offset:3072
	s_mov_b32 m0, s80
	ds_read_b128 v[198:201], v148 offset:32768
	ds_read_b128 v[202:205], v148 offset:33792
	ds_read_b128 v[206:209], v148 offset:34816
	ds_read_b128 v[210:213], v148 offset:35840
	ds_read_b128 v[214:217], v148 offset:36864
	ds_read_b128 v[218:221], v148 offset:37888
	ds_read_b128 v[222:225], v148 offset:38912
	ds_read_b128 v[226:229], v148 offset:39936
	global_load_lds_dwordx4 v188, s[48:49]
	s_mov_b32 m0, s81
	s_nop 0
	global_load_lds_dwordx4 v189, s[48:49]
	s_waitcnt vmcnt(8)
	s_waitcnt lgkmcnt(0)
	s_barrier
	s_setprio 1
	s_waitcnt lgkmcnt(0)
	v_mfma_f32_16x16x32_bf16 v[122:125], v[156:159], v[198:201], v[122:125]
	v_mfma_f32_16x16x32_bf16 v[126:129], v[164:167], v[198:201], v[126:129]
	v_mfma_f32_16x16x32_bf16 v[118:121], v[156:159], v[206:209], v[118:121]
	v_mfma_f32_16x16x32_bf16 v[114:117], v[164:167], v[206:209], v[114:117]
	v_mfma_f32_16x16x32_bf16 v[110:113], v[156:159], v[214:217], v[110:113]
	v_mfma_f32_16x16x32_bf16 v[106:109], v[164:167], v[214:217], v[106:109]
	v_mfma_f32_16x16x32_bf16 v[102:105], v[156:159], v[222:225], v[102:105]
	v_mfma_f32_16x16x32_bf16 v[98:101], v[164:167], v[222:225], v[98:101]
	v_mfma_f32_16x16x32_bf16 v[122:125], v[160:163], v[202:205], v[122:125]
	v_mfma_f32_16x16x32_bf16 v[126:129], v[168:171], v[202:205], v[126:129]
	v_mfma_f32_16x16x32_bf16 v[118:121], v[160:163], v[210:213], v[118:121]
	v_mfma_f32_16x16x32_bf16 v[114:117], v[168:171], v[210:213], v[114:117]
	v_mfma_f32_16x16x32_bf16 v[110:113], v[160:163], v[218:221], v[110:113]
	v_mfma_f32_16x16x32_bf16 v[106:109], v[168:171], v[218:221], v[106:109]
	v_mfma_f32_16x16x32_bf16 v[102:105], v[160:163], v[226:229], v[102:105]
	v_mfma_f32_16x16x32_bf16 v[98:101], v[168:171], v[226:229], v[98:101]
	v_mfma_f32_16x16x32_bf16 v[60:63], v[172:175], v[198:201], v[60:63]
	v_mfma_f32_16x16x32_bf16 v[56:59], v[180:183], v[198:201], v[56:59]
	v_mfma_f32_16x16x32_bf16 v[52:55], v[172:175], v[206:209], v[52:55]
	v_mfma_f32_16x16x32_bf16 v[48:51], v[180:183], v[206:209], v[48:51]
	v_mfma_f32_16x16x32_bf16 v[44:47], v[172:175], v[214:217], v[44:47]
	v_mfma_f32_16x16x32_bf16 v[40:43], v[180:183], v[214:217], v[40:43]
	v_mfma_f32_16x16x32_bf16 v[36:39], v[172:175], v[222:225], v[36:39]
	v_mfma_f32_16x16x32_bf16 v[32:35], v[180:183], v[222:225], v[32:35]
	v_mfma_f32_16x16x32_bf16 v[60:63], v[176:179], v[202:205], v[60:63]
	v_mfma_f32_16x16x32_bf16 v[56:59], v[194:197], v[202:205], v[56:59]
	v_mfma_f32_16x16x32_bf16 v[52:55], v[176:179], v[210:213], v[52:55]
	v_mfma_f32_16x16x32_bf16 v[48:51], v[194:197], v[210:213], v[48:51]
	v_mfma_f32_16x16x32_bf16 v[44:47], v[176:179], v[218:221], v[44:47]
	v_mfma_f32_16x16x32_bf16 v[40:43], v[194:197], v[218:221], v[40:43]
	v_mfma_f32_16x16x32_bf16 v[36:39], v[176:179], v[226:229], v[36:39]
	v_mfma_f32_16x16x32_bf16 v[32:35], v[194:197], v[226:229], v[32:35]
	s_setprio 0
	s_barrier
	s_add_i32 s26, s26, s40
	s_mov_b32 m0, s26
	ds_read_b128 v[198:201], v148 offset:49152
	ds_read_b128 v[202:205], v148 offset:50176
	ds_read_b128 v[206:209], v148 offset:51200
	ds_read_b128 v[210:213], v148 offset:52224
	ds_read_b128 v[214:217], v148 offset:53248
	ds_read_b128 v[218:221], v148 offset:54272
	ds_read_b128 v[222:225], v148 offset:55296
	ds_read_b128 v[226:229], v148 offset:56320
	global_load_lds_dwordx4 v192, s[78:79]
	s_add_i32 m0, s26, 0x2000
	s_add_i32 s26, s37, s40
	global_load_lds_dwordx4 v193, s[78:79]
	s_mov_b32 m0, s26
	s_nop 0
	global_load_lds_dwordx4 v230, s[78:79]
	s_add_i32 m0, s26, 0x2000
	s_nop 0
	global_load_lds_dwordx4 v231, s[78:79]
	s_mov_b32 m0, s82
	s_nop 0
	global_load_lds_dwordx4 v232, s[48:49]
	s_mov_b32 m0, s83
	s_nop 0
	global_load_lds_dwordx4 v233, s[48:49]
	s_waitcnt vmcnt(8)
	s_waitcnt lgkmcnt(0)
	s_barrier
	s_setprio 1
	s_waitcnt lgkmcnt(0)
	v_mfma_f32_16x16x32_bf16 v[92:95], v[156:159], v[198:201], v[92:95]
	v_mfma_f32_16x16x32_bf16 v[88:91], v[164:167], v[198:201], v[88:91]
	v_mfma_f32_16x16x32_bf16 v[84:87], v[156:159], v[206:209], v[84:87]
	v_mfma_f32_16x16x32_bf16 v[80:83], v[164:167], v[206:209], v[80:83]
	v_mfma_f32_16x16x32_bf16 v[76:79], v[156:159], v[214:217], v[76:79]
	v_mfma_f32_16x16x32_bf16 v[72:75], v[164:167], v[214:217], v[72:75]
	v_mfma_f32_16x16x32_bf16 v[68:71], v[156:159], v[222:225], v[68:71]
	v_mfma_f32_16x16x32_bf16 v[64:67], v[164:167], v[222:225], v[64:67]
	v_mfma_f32_16x16x32_bf16 v[92:95], v[160:163], v[202:205], v[92:95]
	v_mfma_f32_16x16x32_bf16 v[88:91], v[168:171], v[202:205], v[88:91]
	v_mfma_f32_16x16x32_bf16 v[84:87], v[160:163], v[210:213], v[84:87]
	v_mfma_f32_16x16x32_bf16 v[80:83], v[168:171], v[210:213], v[80:83]
	v_mfma_f32_16x16x32_bf16 v[76:79], v[160:163], v[218:221], v[76:79]
	v_mfma_f32_16x16x32_bf16 v[72:75], v[168:171], v[218:221], v[72:75]
	v_mfma_f32_16x16x32_bf16 v[68:71], v[160:163], v[226:229], v[68:71]
	v_mfma_f32_16x16x32_bf16 v[64:67], v[168:171], v[226:229], v[64:67]
	v_mfma_f32_16x16x32_bf16 v[28:31], v[172:175], v[198:201], v[28:31]
	v_mfma_f32_16x16x32_bf16 v[24:27], v[180:183], v[198:201], v[24:27]
	v_mfma_f32_16x16x32_bf16 v[20:23], v[172:175], v[206:209], v[20:23]
	v_mfma_f32_16x16x32_bf16 v[16:19], v[180:183], v[206:209], v[16:19]
	v_mfma_f32_16x16x32_bf16 v[12:15], v[172:175], v[214:217], v[12:15]
	v_mfma_f32_16x16x32_bf16 v[8:11], v[180:183], v[214:217], v[8:11]
	v_mfma_f32_16x16x32_bf16 v[4:7], v[172:175], v[222:225], v[4:7]
	v_mfma_f32_16x16x32_bf16 v[0:3], v[180:183], v[222:225], v[0:3]
	v_mfma_f32_16x16x32_bf16 v[28:31], v[176:179], v[202:205], v[28:31]
	v_mfma_f32_16x16x32_bf16 v[24:27], v[194:197], v[202:205], v[24:27]
	v_mfma_f32_16x16x32_bf16 v[20:23], v[176:179], v[210:213], v[20:23]
	v_mfma_f32_16x16x32_bf16 v[16:19], v[194:197], v[210:213], v[16:19]
	v_mfma_f32_16x16x32_bf16 v[12:15], v[176:179], v[218:221], v[12:15]
	v_mfma_f32_16x16x32_bf16 v[8:11], v[194:197], v[218:221], v[8:11]
	v_mfma_f32_16x16x32_bf16 v[4:7], v[176:179], v[226:229], v[4:7]
	v_mfma_f32_16x16x32_bf16 v[0:3], v[194:197], v[226:229], v[0:3]
	s_setprio 0
	s_barrier
	s_add_u32 s91, s91, 0x100
	s_addc_u32 vcc_lo, vcc_lo, 0
	s_add_u32 s24, s24, 0x100
	s_addc_u32 s25, s25, 0
	s_cmp_ge_i32 vcc_hi, s84
	s_mov_b32 s48, vcc_hi
	s_cbranch_scc0 .LBB0_466
	v_add_u32_e32 v192, 64, v191

; #define PG8_STAGE(bufoff, gbase, voff) do { _Pragma("unroll") for (int _i = 0; _i < 2; ++_i) \
;         __builtin_amdgcn_global_load_lds((const unsigned*)((const char*)(gbase) + (voff)[_i]), (PG8_LAS unsigned*)(lds + (bufoff) + ldsw + _i * 8192), 16, 0, 0); } while (0)
; #define PG8_LDA(dst, b, h) do { _Pragma("unroll") for (int m = 0; m < 4; ++m) _Pragma("unroll") for (int k = 0; k < 2; ++k) dst[m][k] = *(const PG8_LAS bf16x8*)(lds + PG8_SA(b, h) + aoff + m * 2048 + k * 1024); } while (0)
; #define PG8_LDB(dst, b, h) do { _Pragma("unroll") for (int n = 0; n < 2; ++n) _Pragma("unroll") for (int k = 0; k < 2; ++k) dst[n][k] = *(const PG8_LAS bf16x8*)(lds + PG8_SB(b, h) + boff + n * 2048 + k * 1024); } while (0)
; #define PG8_MMA(ai, bj, At, Bt) do { __builtin_amdgcn_s_setprio(1); _Pragma("unroll") for (int m = 0; m < 4; ++m) _Pragma("unroll") for (int n = 0; n < 2; ++n) _Pragma("unroll") for (int k = 0; k < 2; ++k) \
;         acc[ai][bj][m][n] = __builtin_amdgcn_mfma_f32_16x16x32_bf16(Bt[n][k], At[m][k], acc[ai][bj][m][n], 0, 0, 0); __builtin_amdgcn_s_setprio(0); } while (0)
; #define PG8_WAIT_V(n) asm volatile("s_waitcnt vmcnt(" #n ")" ::: "memory")
; #define PG8_WAIT_L(n) asm volatile("s_waitcnt lgkmcnt(" #n ")" ::: "memory")
; template <class Epi, class Sched, bool ALIGN_EPI = false, bool SP2 = false>
; __device__ __forceinline__ void gemm_phase(PG8_LAS unsigned char* lds, const Gemm g, const Sched& S, const Epi& E, int wid_s_) {
;     ...
;             const bool last = (t == nt - 2);
;             const char* a1 = cA + (size_t)(t + 1) * kstep;
;             const char* a2 = last ? nA : cA + (size_t)(t + 2) * kstep; const char* b2 = last ? nB : cB + (size_t)(t + 2) * kstep;
;             const char* a3 = a2 + kstep; const char* b3 = b2 + kstep;
;             if (last && has_next) S.a_ready(nxt);
;             if constexpr (SP2) {
;             PG8_LDB(B0, 0, 0); PG8_LDB(B1, 0, 1); PG8_SCHED; PG8_LDA(At, 0, 0); PG8_STAGE(PG8_SA(1, 1), a1 + hstep, voffA);
;             PG8_WAIT_V(8); PG8_WAIT_L(0); PG8_BAR; PG8_MMA(0, 0, At, B0); PG8_MMA(0, 1, At, B1); PG8_BAR; PG8_SCHED;
;             PG8_LDA(At, 0, 1); PG8_STAGE(PG8_SB(0, 0), b2, voffB); PG8_STAGE(PG8_SB(0, 1), b2 + hstep, voffB); PG8_STAGE(PG8_SA(0, 0), a2, voffA);
;             PG8_WAIT_V(8); PG8_WAIT_L(0); PG8_BAR; PG8_MMA(1, 0, At, B0); PG8_MMA(1, 1, At, B1); PG8_BAR; PG8_SCHED;
.LBB0_540:
	s_add_i32 vcc_hi, s48, 2
	s_add_u32 s78, s2, 0x80
	s_addc_u32 s49, s3, 0
	s_add_i32 s12, 16, 0x10000
	s_cmp_eq_u32 s87, s48
	s_cselect_b32 s49, s25, s49
	s_cselect_b32 s48, s24, s78
	v_add_u32_e32 v151, s12, v144
	s_cselect_b32 s79, s81, vcc_lo
	s_cselect_b32 s78, s80, s91
	s_add_i32 s13, 16, 0x14000
	ds_read_b128 v[140:143], v151
	ds_read_b128 v[152:155], v151 offset:1024
	ds_read_b128 v[156:159], v151 offset:2048
	ds_read_b128 v[160:163], v151 offset:3072
	v_add_u32_e32 v151, s13, v144
	ds_read_b128 v[164:167], v151
	ds_read_b128 v[168:171], v151 offset:1024
	ds_read_b128 v[172:175], v151 offset:2048
	ds_read_b128 v[176:179], v151 offset:3072
	s_add_i32 m0, s41, 0xc000
	ds_read_b128 v[180:183], v150
	ds_read_b128 v[194:197], v150 offset:1024
	ds_read_b128 v[198:201], v150 offset:2048
	ds_read_b128 v[202:205], v150 offset:3072
	ds_read_b128 v[206:209], v150 offset:4096
	ds_read_b128 v[210:213], v150 offset:5120
	ds_read_b128 v[214:217], v150 offset:6144
	ds_read_b128 v[218:221], v150 offset:7168
	global_load_lds_dwordx4 v138, s[2:3]
	s_add_i32 m0, s41, 0xe000
	s_nop 0
	global_load_lds_dwordx4 v136, s[2:3]
	s_waitcnt vmcnt(8)
	s_waitcnt lgkmcnt(0)
	s_barrier
	s_setprio 1
	s_waitcnt lgkmcnt(0)
	v_mfma_f32_16x16x32_bf16 v[126:129], v[140:143], v[180:183], v[126:129]
	v_mfma_f32_16x16x32_bf16 v[122:125], v[156:159], v[180:183], v[122:125]
	v_mfma_f32_16x16x32_bf16 v[110:113], v[140:143], v[198:201], v[110:113]
	v_mfma_f32_16x16x32_bf16 v[106:109], v[156:159], v[198:201], v[106:109]
	v_mfma_f32_16x16x32_bf16 v[92:95], v[140:143], v[206:209], v[92:95]
	v_mfma_f32_16x16x32_bf16 v[88:91], v[156:159], v[206:209], v[88:91]
	v_mfma_f32_16x16x32_bf16 v[76:79], v[140:143], v[214:217], v[76:79]
	v_mfma_f32_16x16x32_bf16 v[72:75], v[156:159], v[214:217], v[72:75]
	v_mfma_f32_16x16x32_bf16 v[126:129], v[152:155], v[194:197], v[126:129]
	v_mfma_f32_16x16x32_bf16 v[122:125], v[160:163], v[194:197], v[122:125]
	v_mfma_f32_16x16x32_bf16 v[110:113], v[152:155], v[202:205], v[110:113]
	v_mfma_f32_16x16x32_bf16 v[106:109], v[160:163], v[202:205], v[106:109]
	v_mfma_f32_16x16x32_bf16 v[92:95], v[152:155], v[210:213], v[92:95]
	v_mfma_f32_16x16x32_bf16 v[88:91], v[160:163], v[210:213], v[88:91]
	v_mfma_f32_16x16x32_bf16 v[76:79], v[152:155], v[218:221], v[76:79]
	v_mfma_f32_16x16x32_bf16 v[72:75], v[160:163], v[218:221], v[72:75]
	v_mfma_f32_16x16x32_bf16 v[118:121], v[164:167], v[180:183], v[118:121]
	v_mfma_f32_16x16x32_bf16 v[114:117], v[172:175], v[180:183], v[114:117]
	v_mfma_f32_16x16x32_bf16 v[102:105], v[164:167], v[198:201], v[102:105]
	v_mfma_f32_16x16x32_bf16 v[98:101], v[172:175], v[198:201], v[98:101]
	v_mfma_f32_16x16x32_bf16 v[84:87], v[164:167], v[206:209], v[84:87]
	v_mfma_f32_16x16x32_bf16 v[80:83], v[172:175], v[206:209], v[80:83]
	v_mfma_f32_16x16x32_bf16 v[68:71], v[164:167], v[214:217], v[68:71]
	v_mfma_f32_16x16x32_bf16 v[64:67], v[172:175], v[214:217], v[64:67]
	v_mfma_f32_16x16x32_bf16 v[118:121], v[168:171], v[194:197], v[118:121]
	v_mfma_f32_16x16x32_bf16 v[114:117], v[176:179], v[194:197], v[114:117]
	v_mfma_f32_16x16x32_bf16 v[102:105], v[168:171], v[202:205], v[102:105]
	v_mfma_f32_16x16x32_bf16 v[98:101], v[176:179], v[202:205], v[98:101]
	v_mfma_f32_16x16x32_bf16 v[84:87], v[168:171], v[210:213], v[84:87]
	v_mfma_f32_16x16x32_bf16 v[80:83], v[176:179], v[210:213], v[80:83]
	v_mfma_f32_16x16x32_bf16 v[68:71], v[168:171], v[218:221], v[68:71]
	v_mfma_f32_16x16x32_bf16 v[64:67], v[176:179], v[218:221], v[64:67]
	s_setprio 0
	s_barrier
	s_add_i32 s12, s12, s40
	s_mov_b32 m0, s12
	ds_read_b128 v[180:183], v150 offset:16384
	ds_read_b128 v[194:197], v150 offset:17408
	ds_read_b128 v[198:201], v150 offset:18432
	ds_read_b128 v[202:205], v150 offset:19456
	ds_read_b128 v[206:209], v150 offset:20480
	ds_read_b128 v[210:213], v150 offset:21504
	ds_read_b128 v[214:217], v150 offset:22528
	ds_read_b128 v[218:221], v150 offset:23552
	global_load_lds_dwordx4 v96, s[78:79]
	s_add_i32 m0, s12, 0x2000
	s_add_i32 s12, s13, s40
	global_load_lds_dwordx4 v130, s[78:79]
	s_mov_b32 m0, s12
	s_nop 0
	global_load_lds_dwordx4 v188, s[78:79]
	s_add_i32 m0, s12, 0x2000
	s_nop 0
	global_load_lds_dwordx4 v189, s[78:79]
	s_mov_b32 m0, s41
	s_nop 0
	global_load_lds_dwordx4 v134, s[48:49]
	s_mov_b32 m0, s50
	s_nop 0
	global_load_lds_dwordx4 v132, s[48:49]
	s_waitcnt vmcnt(8)
	s_waitcnt lgkmcnt(0)
	s_barrier
	s_setprio 1
	s_waitcnt lgkmcnt(0)
	v_mfma_f32_16x16x32_bf16 v[60:63], v[140:143], v[180:183], v[60:63]
	v_mfma_f32_16x16x32_bf16 v[56:59], v[156:159], v[180:183], v[56:59]
	v_mfma_f32_16x16x32_bf16 v[44:47], v[140:143], v[198:201], v[44:47]
	v_mfma_f32_16x16x32_bf16 v[40:43], v[156:159], v[198:201], v[40:43]
	v_mfma_f32_16x16x32_bf16 v[28:31], v[140:143], v[206:209], v[28:31]
	v_mfma_f32_16x16x32_bf16 v[24:27], v[156:159], v[206:209], v[24:27]
	v_mfma_f32_16x16x32_bf16 v[12:15], v[140:143], v[214:217], v[12:15]
	v_mfma_f32_16x16x32_bf16 v[8:11], v[156:159], v[214:217], v[8:11]
	v_mfma_f32_16x16x32_bf16 v[60:63], v[152:155], v[194:197], v[60:63]
	v_mfma_f32_16x16x32_bf16 v[56:59], v[160:163], v[194:197], v[56:59]
	v_mfma_f32_16x16x32_bf16 v[44:47], v[152:155], v[202:205], v[44:47]
	v_mfma_f32_16x16x32_bf16 v[40:43], v[160:163], v[202:205], v[40:43]
	v_mfma_f32_16x16x32_bf16 v[28:31], v[152:155], v[210:213], v[28:31]
	v_mfma_f32_16x16x32_bf16 v[24:27], v[160:163], v[210:213], v[24:27]
	v_mfma_f32_16x16x32_bf16 v[12:15], v[152:155], v[218:221], v[12:15]
	v_mfma_f32_16x16x32_bf16 v[8:11], v[160:163], v[218:221], v[8:11]
	v_mfma_f32_16x16x32_bf16 v[52:55], v[164:167], v[180:183], v[52:55]
	v_mfma_f32_16x16x32_bf16 v[48:51], v[172:175], v[180:183], v[48:51]
	v_mfma_f32_16x16x32_bf16 v[36:39], v[164:167], v[198:201], v[36:39]
	v_mfma_f32_16x16x32_bf16 v[32:35], v[172:175], v[198:201], v[32:35]
	v_mfma_f32_16x16x32_bf16 v[20:23], v[164:167], v[206:209], v[20:23]
	v_mfma_f32_16x16x32_bf16 v[16:19], v[172:175], v[206:209], v[16:19]
	v_mfma_f32_16x16x32_bf16 v[4:7], v[164:167], v[214:217], v[4:7]
	v_mfma_f32_16x16x32_bf16 v[0:3], v[172:175], v[214:217], v[0:3]
	v_mfma_f32_16x16x32_bf16 v[52:55], v[168:171], v[194:197], v[52:55]
	v_mfma_f32_16x16x32_bf16 v[48:51], v[176:179], v[194:197], v[48:51]
	v_mfma_f32_16x16x32_bf16 v[36:39], v[168:171], v[202:205], v[36:39]
	v_mfma_f32_16x16x32_bf16 v[32:35], v[176:179], v[202:205], v[32:35]
	v_mfma_f32_16x16x32_bf16 v[20:23], v[168:171], v[210:213], v[20:23]
	v_mfma_f32_16x16x32_bf16 v[16:19], v[176:179], v[210:213], v[16:19]
	v_mfma_f32_16x16x32_bf16 v[4:7], v[168:171], v[218:221], v[4:7]
	v_mfma_f32_16x16x32_bf16 v[0:3], v[176:179], v[218:221], v[0:3]
	s_setprio 0
	s_barrier
; #define PG8_STAGE(bufoff, gbase, voff) do { _Pragma("unroll") for (int _i = 0; _i < 2; ++_i) \
;         __builtin_amdgcn_global_load_lds((const unsigned*)((const char*)(gbase) + (voff)[_i]), (PG8_LAS unsigned*)(lds + (bufoff) + ldsw + _i * 8192), 16, 0, 0); } while (0)
; #define PG8_LDA(dst, b, h) do { _Pragma("unroll") for (int m = 0; m < 4; ++m) _Pragma("unroll") for (int k = 0; k < 2; ++k) dst[m][k] = *(const PG8_LAS bf16x8*)(lds + PG8_SA(b, h) + aoff + m * 2048 + k * 1024); } while (0)
; #define PG8_LDB(dst, b, h) do { _Pragma("unroll") for (int n = 0; n < 2; ++n) _Pragma("unroll") for (int k = 0; k < 2; ++k) dst[n][k] = *(const PG8_LAS bf16x8*)(lds + PG8_SB(b, h) + boff + n * 2048 + k * 1024); } while (0)
; #define PG8_MMA(ai, bj, At, Bt) do { __builtin_amdgcn_s_setprio(1); _Pragma("unroll") for (int m = 0; m < 4; ++m) _Pragma("unroll") for (int n = 0; n < 2; ++n) _Pragma("unroll") for (int k = 0; k < 2; ++k) \
;         acc[ai][bj][m][n] = __builtin_amdgcn_mfma_f32_16x16x32_bf16(Bt[n][k], At[m][k], acc[ai][bj][m][n], 0, 0, 0); __builtin_amdgcn_s_setprio(0); } while (0)
; #define PG8_WAIT_V(n) asm volatile("s_waitcnt vmcnt(" #n ")" ::: "memory")
; #define PG8_WAIT_L(n) asm volatile("s_waitcnt lgkmcnt(" #n ")" ::: "memory")
; #define PG8_BAR __builtin_amdgcn_s_barrier()
; #define PG8_SCHED __builtin_amdgcn_sched_barrier(0)
; template <class Epi, class Sched, bool ALIGN_EPI = false, bool SP2 = false>
; __device__ __forceinline__ void gemm_phase(PG8_LAS unsigned char* lds, const Gemm g, const Sched& S, const Epi& E, int wid_s_) {
;     ...
;             PG8_LDB(B0, 1, 0); PG8_LDB(B1, 1, 1); PG8_SCHED; PG8_LDA(At, 1, 0); PG8_STAGE(PG8_SA(0, 1), a2 + hstep, voffA);
;             PG8_WAIT_V(8); PG8_WAIT_L(0); PG8_BAR; PG8_MMA(0, 0, At, B0); PG8_MMA(0, 1, At, B1); PG8_BAR; PG8_SCHED;
;             PG8_LDA(At, 1, 1); PG8_STAGE(PG8_SB(1, 0), b3, voffB); PG8_STAGE(PG8_SB(1, 1), b3 + hstep, voffB); PG8_STAGE(PG8_SA(1, 0), a3, voffA);
;             PG8_WAIT_V(8); PG8_WAIT_L(0); PG8_BAR; PG8_MMA(1, 0, At, B0); PG8_MMA(1, 1, At, B1); PG8_BAR; PG8_SCHED;
	s_add_i32 s12, 16, 0x18000
	v_add_u32_e32 v151, s12, v144
	s_add_i32 s13, 16, 0x1c000
	ds_read_b128 v[140:143], v151
	ds_read_b128 v[152:155], v151 offset:1024
	ds_read_b128 v[156:159], v151 offset:2048
	ds_read_b128 v[160:163], v151 offset:3072
	v_add_u32_e32 v151, s13, v144
	ds_read_b128 v[164:167], v151
	ds_read_b128 v[168:171], v151 offset:1024
	ds_read_b128 v[172:175], v151 offset:2048
	ds_read_b128 v[176:179], v151 offset:3072
	s_mov_b32 m0, s51
	ds_read_b128 v[180:183], v150 offset:32768
	ds_read_b128 v[194:197], v150 offset:33792
	ds_read_b128 v[198:201], v150 offset:34816
	ds_read_b128 v[202:205], v150 offset:35840
	ds_read_b128 v[206:209], v150 offset:36864
	ds_read_b128 v[210:213], v150 offset:37888
	ds_read_b128 v[214:217], v150 offset:38912
	ds_read_b128 v[218:221], v150 offset:39936
	global_load_lds_dwordx4 v192, s[48:49]
	s_mov_b32 m0, s82
	s_nop 0
	global_load_lds_dwordx4 v193, s[48:49]
	s_waitcnt vmcnt(8)
	s_waitcnt lgkmcnt(0)
	s_barrier
	s_setprio 1
	s_waitcnt lgkmcnt(0)
	v_mfma_f32_16x16x32_bf16 v[126:129], v[140:143], v[180:183], v[126:129]
	v_mfma_f32_16x16x32_bf16 v[122:125], v[156:159], v[180:183], v[122:125]
	v_mfma_f32_16x16x32_bf16 v[110:113], v[140:143], v[198:201], v[110:113]
	v_mfma_f32_16x16x32_bf16 v[106:109], v[156:159], v[198:201], v[106:109]
	v_mfma_f32_16x16x32_bf16 v[92:95], v[140:143], v[206:209], v[92:95]
	v_mfma_f32_16x16x32_bf16 v[88:91], v[156:159], v[206:209], v[88:91]
	v_mfma_f32_16x16x32_bf16 v[76:79], v[140:143], v[214:217], v[76:79]
	v_mfma_f32_16x16x32_bf16 v[72:75], v[156:159], v[214:217], v[72:75]
	v_mfma_f32_16x16x32_bf16 v[126:129], v[152:155], v[194:197], v[126:129]
	v_mfma_f32_16x16x32_bf16 v[122:125], v[160:163], v[194:197], v[122:125]
	v_mfma_f32_16x16x32_bf16 v[110:113], v[152:155], v[202:205], v[110:113]
	v_mfma_f32_16x16x32_bf16 v[106:109], v[160:163], v[202:205], v[106:109]
	v_mfma_f32_16x16x32_bf16 v[92:95], v[152:155], v[210:213], v[92:95]
	v_mfma_f32_16x16x32_bf16 v[88:91], v[160:163], v[210:213], v[88:91]
	v_mfma_f32_16x16x32_bf16 v[76:79], v[152:155], v[218:221], v[76:79]
	v_mfma_f32_16x16x32_bf16 v[72:75], v[160:163], v[218:221], v[72:75]
	v_mfma_f32_16x16x32_bf16 v[118:121], v[164:167], v[180:183], v[118:121]
	v_mfma_f32_16x16x32_bf16 v[114:117], v[172:175], v[180:183], v[114:117]
	v_mfma_f32_16x16x32_bf16 v[102:105], v[164:167], v[198:201], v[102:105]
	v_mfma_f32_16x16x32_bf16 v[98:101], v[172:175], v[198:201], v[98:101]
	v_mfma_f32_16x16x32_bf16 v[84:87], v[164:167], v[206:209], v[84:87]
	v_mfma_f32_16x16x32_bf16 v[80:83], v[172:175], v[206:209], v[80:83]
	v_mfma_f32_16x16x32_bf16 v[68:71], v[164:167], v[214:217], v[68:71]
	v_mfma_f32_16x16x32_bf16 v[64:67], v[172:175], v[214:217], v[64:67]
	v_mfma_f32_16x16x32_bf16 v[118:121], v[168:171], v[194:197], v[118:121]
	v_mfma_f32_16x16x32_bf16 v[114:117], v[176:179], v[194:197], v[114:117]
	v_mfma_f32_16x16x32_bf16 v[102:105], v[168:171], v[202:205], v[102:105]
	v_mfma_f32_16x16x32_bf16 v[98:101], v[176:179], v[202:205], v[98:101]
	v_mfma_f32_16x16x32_bf16 v[84:87], v[168:171], v[210:213], v[84:87]
	v_mfma_f32_16x16x32_bf16 v[80:83], v[176:179], v[210:213], v[80:83]
	v_mfma_f32_16x16x32_bf16 v[68:71], v[168:171], v[218:221], v[68:71]
	v_mfma_f32_16x16x32_bf16 v[64:67], v[176:179], v[218:221], v[64:67]
	s_setprio 0
	s_barrier
	s_add_i32 s12, s12, s40
	s_mov_b32 m0, s12
	ds_read_b128 v[180:183], v150 offset:49152
	ds_read_b128 v[194:197], v150 offset:50176
	ds_read_b128 v[198:201], v150 offset:51200
	ds_read_b128 v[202:205], v150 offset:52224
	ds_read_b128 v[206:209], v150 offset:53248
	ds_read_b128 v[210:213], v150 offset:54272
	ds_read_b128 v[214:217], v150 offset:55296
	ds_read_b128 v[218:221], v150 offset:56320
	global_load_lds_dwordx4 v222, s[78:79]
	s_add_i32 m0, s12, 0x2000
	s_add_i32 s12, s13, s40
	global_load_lds_dwordx4 v223, s[78:79]
	s_mov_b32 m0, s12
	s_nop 0
	global_load_lds_dwordx4 v224, s[78:79]
	s_add_i32 m0, s12, 0x2000
	s_nop 0
	global_load_lds_dwordx4 v225, s[78:79]
	s_mov_b32 m0, s83
	s_nop 0
	global_load_lds_dwordx4 v226, s[48:49]
	s_mov_b32 m0, s84
	s_nop 0
	global_load_lds_dwordx4 v227, s[48:49]
	s_waitcnt vmcnt(8)
	s_waitcnt lgkmcnt(0)
	s_barrier
	s_setprio 1
	s_waitcnt lgkmcnt(0)
	v_mfma_f32_16x16x32_bf16 v[60:63], v[140:143], v[180:183], v[60:63]
	v_mfma_f32_16x16x32_bf16 v[56:59], v[156:159], v[180:183], v[56:59]
	v_mfma_f32_16x16x32_bf16 v[44:47], v[140:143], v[198:201], v[44:47]
	v_mfma_f32_16x16x32_bf16 v[40:43], v[156:159], v[198:201], v[40:43]
	v_mfma_f32_16x16x32_bf16 v[28:31], v[140:143], v[206:209], v[28:31]
	v_mfma_f32_16x16x32_bf16 v[24:27], v[156:159], v[206:209], v[24:27]
	v_mfma_f32_16x16x32_bf16 v[12:15], v[140:143], v[214:217], v[12:15]
	v_mfma_f32_16x16x32_bf16 v[8:11], v[156:159], v[214:217], v[8:11]
	v_mfma_f32_16x16x32_bf16 v[60:63], v[152:155], v[194:197], v[60:63]
	v_mfma_f32_16x16x32_bf16 v[56:59], v[160:163], v[194:197], v[56:59]
	v_mfma_f32_16x16x32_bf16 v[44:47], v[152:155], v[202:205], v[44:47]
	v_mfma_f32_16x16x32_bf16 v[40:43], v[160:163], v[202:205], v[40:43]
	v_mfma_f32_16x16x32_bf16 v[28:31], v[152:155], v[210:213], v[28:31]
	v_mfma_f32_16x16x32_bf16 v[24:27], v[160:163], v[210:213], v[24:27]
	v_mfma_f32_16x16x32_bf16 v[12:15], v[152:155], v[218:221], v[12:15]
	v_mfma_f32_16x16x32_bf16 v[8:11], v[160:163], v[218:221], v[8:11]
	v_mfma_f32_16x16x32_bf16 v[52:55], v[164:167], v[180:183], v[52:55]
	v_mfma_f32_16x16x32_bf16 v[48:51], v[172:175], v[180:183], v[48:51]
	v_mfma_f32_16x16x32_bf16 v[36:39], v[164:167], v[198:201], v[36:39]
	v_mfma_f32_16x16x32_bf16 v[32:35], v[172:175], v[198:201], v[32:35]
	v_mfma_f32_16x16x32_bf16 v[20:23], v[164:167], v[206:209], v[20:23]
	v_mfma_f32_16x16x32_bf16 v[16:19], v[172:175], v[206:209], v[16:19]
	v_mfma_f32_16x16x32_bf16 v[4:7], v[164:167], v[214:217], v[4:7]
	v_mfma_f32_16x16x32_bf16 v[0:3], v[172:175], v[214:217], v[0:3]
	v_mfma_f32_16x16x32_bf16 v[52:55], v[168:171], v[194:197], v[52:55]
	v_mfma_f32_16x16x32_bf16 v[48:51], v[176:179], v[194:197], v[48:51]
	v_mfma_f32_16x16x32_bf16 v[36:39], v[168:171], v[202:205], v[36:39]
	v_mfma_f32_16x16x32_bf16 v[32:35], v[176:179], v[202:205], v[32:35]
	v_mfma_f32_16x16x32_bf16 v[20:23], v[168:171], v[210:213], v[20:23]
	v_mfma_f32_16x16x32_bf16 v[16:19], v[176:179], v[210:213], v[16:19]
	v_mfma_f32_16x16x32_bf16 v[4:7], v[168:171], v[218:221], v[4:7]
	v_mfma_f32_16x16x32_bf16 v[0:3], v[176:179], v[218:221], v[0:3]
	s_setprio 0
	s_barrier
	s_add_u32 s91, s91, 0x100
	s_addc_u32 vcc_lo, vcc_lo, 0
	s_add_u32 s2, s2, 0x100
	s_addc_u32 s3, s3, 0
	s_cmp_ge_i32 vcc_hi, s85
	s_mov_b32 s48, vcc_hi
	s_cbranch_scc0 .LBB0_540
	v_add_u32_e32 v192, 64, v191

; #define PG8_STAGE(bufoff, gbase, voff) do { _Pragma("unroll") for (int _i = 0; _i < 2; ++_i) \
;         __builtin_amdgcn_global_load_lds((const unsigned*)((const char*)(gbase) + (voff)[_i]), (PG8_LAS unsigned*)(lds + (bufoff) + ldsw + _i * 8192), 16, 0, 0); } while (0)
; #define PG8_LDA(dst, b, h) do { _Pragma("unroll") for (int m = 0; m < 4; ++m) _Pragma("unroll") for (int k = 0; k < 2; ++k) dst[m][k] = *(const PG8_LAS bf16x8*)(lds + PG8_SA(b, h) + aoff + m * 2048 + k * 1024); } while (0)
; #define PG8_LDB(dst, b, h) do { _Pragma("unroll") for (int n = 0; n < 2; ++n) _Pragma("unroll") for (int k = 0; k < 2; ++k) dst[n][k] = *(const PG8_LAS bf16x8*)(lds + PG8_SB(b, h) + boff + n * 2048 + k * 1024); } while (0)
; #define PG8_MMA(ai, bj, At, Bt) do { __builtin_amdgcn_s_setprio(1); _Pragma("unroll") for (int m = 0; m < 4; ++m) _Pragma("unroll") for (int n = 0; n < 2; ++n) _Pragma("unroll") for (int k = 0; k < 2; ++k) \
;         acc[ai][bj][m][n] = __builtin_amdgcn_mfma_f32_16x16x32_bf16(Bt[n][k], At[m][k], acc[ai][bj][m][n], 0, 0, 0); __builtin_amdgcn_s_setprio(0); } while (0)
; #define PG8_WAIT_V(n) asm volatile("s_waitcnt vmcnt(" #n ")" ::: "memory")
; #define PG8_WAIT_L(n) asm volatile("s_waitcnt lgkmcnt(" #n ")" ::: "memory")
; template <class Epi, class Sched, bool ALIGN_EPI = false, bool SP2 = false>
; __device__ __forceinline__ void gemm_phase(PG8_LAS unsigned char* lds, const Gemm g, const Sched& S, const Epi& E, int wid_s_) {
;     ...
;             const bool last = (t == nt - 2);
;             const char* a1 = cA + (size_t)(t + 1) * kstep;
;             const char* a2 = last ? nA : cA + (size_t)(t + 2) * kstep; const char* b2 = last ? nB : cB + (size_t)(t + 2) * kstep;
;             const char* a3 = a2 + kstep; const char* b3 = b2 + kstep;
;             if (last && has_next) S.a_ready(nxt);
;             if constexpr (SP2) {
;             PG8_LDB(B0, 0, 0); PG8_LDB(B1, 0, 1); PG8_SCHED; PG8_LDA(At, 0, 0); PG8_STAGE(PG8_SA(1, 1), a1 + hstep, voffA);
;             PG8_WAIT_V(8); PG8_WAIT_L(0); PG8_BAR; PG8_MMA(0, 0, At, B0); PG8_MMA(0, 1, At, B1); PG8_BAR; PG8_SCHED;
;             PG8_LDA(At, 0, 1); PG8_STAGE(PG8_SB(0, 0), b2, voffB); PG8_STAGE(PG8_SB(0, 1), b2 + hstep, voffB); PG8_STAGE(PG8_SA(0, 0), a2, voffA);
;             PG8_WAIT_V(8); PG8_WAIT_L(0); PG8_BAR; PG8_MMA(1, 0, At, B0); PG8_MMA(1, 1, At, B1); PG8_BAR; PG8_SCHED;
.LBB0_628:
	s_add_i32 s84, s48, 2
	s_add_u32 s78, s2, 0x80
	s_addc_u32 s49, s3, 0
	s_add_i32 s85, 16, 0x10000
	s_cmp_eq_u32 s5, s48
	s_cselect_b32 s49, s81, s49
	s_cselect_b32 s48, s80, s78
	v_add_u32_e32 v150, s85, v147
	s_cselect_b32 s79, s83, vcc_hi
	s_cselect_b32 s78, s82, vcc_lo
	s_add_i32 s20, 16, 0x14000
	ds_read_b128 v[122:125], v150
	ds_read_b128 v[126:129], v150 offset:1024
	ds_read_b128 v[154:157], v150 offset:2048
	ds_read_b128 v[158:161], v150 offset:3072
	v_add_u32_e32 v150, s20, v147
	ds_read_b128 v[162:165], v150
	ds_read_b128 v[166:169], v150 offset:1024
	ds_read_b128 v[170:173], v150 offset:2048
	ds_read_b128 v[174:177], v150 offset:3072
	s_add_i32 m0, s51, 0xc000
	ds_read_b128 v[180:183], v149
	ds_read_b128 v[196:199], v149 offset:1024
	ds_read_b128 v[200:203], v149 offset:2048
	ds_read_b128 v[204:207], v149 offset:3072
	ds_read_b128 v[208:211], v149 offset:4096
	ds_read_b128 v[212:215], v149 offset:5120
	ds_read_b128 v[216:219], v149 offset:6144
	ds_read_b128 v[220:223], v149 offset:7168
	global_load_lds_dwordx4 v152, s[2:3]
	s_add_i32 m0, s51, 0xe000
	s_nop 0
	global_load_lds_dwordx4 v144, s[2:3]
	s_waitcnt vmcnt(8)
	s_waitcnt lgkmcnt(0)
	s_barrier
	s_setprio 1
	s_waitcnt lgkmcnt(0)
	v_mfma_f32_16x16x32_bf16 v[134:137], v[122:125], v[180:183], v[134:137]
	v_mfma_f32_16x16x32_bf16 v[130:133], v[154:157], v[180:183], v[130:133]
	v_mfma_f32_16x16x32_bf16 v[118:121], v[122:125], v[200:203], v[118:121]
	v_mfma_f32_16x16x32_bf16 v[114:117], v[154:157], v[200:203], v[114:117]
	v_mfma_f32_16x16x32_bf16 v[110:113], v[122:125], v[208:211], v[110:113]
	v_mfma_f32_16x16x32_bf16 v[106:109], v[154:157], v[208:211], v[106:109]
	v_mfma_f32_16x16x32_bf16 v[102:105], v[122:125], v[216:219], v[102:105]
	v_mfma_f32_16x16x32_bf16 v[98:101], v[154:157], v[216:219], v[98:101]
	v_mfma_f32_16x16x32_bf16 v[134:137], v[126:129], v[196:199], v[134:137]
	v_mfma_f32_16x16x32_bf16 v[130:133], v[158:161], v[196:199], v[130:133]
	v_mfma_f32_16x16x32_bf16 v[118:121], v[126:129], v[204:207], v[118:121]
	v_mfma_f32_16x16x32_bf16 v[114:117], v[158:161], v[204:207], v[114:117]
	v_mfma_f32_16x16x32_bf16 v[110:113], v[126:129], v[212:215], v[110:113]
	v_mfma_f32_16x16x32_bf16 v[106:109], v[158:161], v[212:215], v[106:109]
	v_mfma_f32_16x16x32_bf16 v[102:105], v[126:129], v[220:223], v[102:105]
	v_mfma_f32_16x16x32_bf16 v[98:101], v[158:161], v[220:223], v[98:101]
	v_mfma_f32_16x16x32_bf16 v[60:63], v[162:165], v[180:183], v[60:63]
	v_mfma_f32_16x16x32_bf16 v[56:59], v[170:173], v[180:183], v[56:59]
	v_mfma_f32_16x16x32_bf16 v[52:55], v[162:165], v[200:203], v[52:55]
	v_mfma_f32_16x16x32_bf16 v[48:51], v[170:173], v[200:203], v[48:51]
	v_mfma_f32_16x16x32_bf16 v[44:47], v[162:165], v[208:211], v[44:47]
	v_mfma_f32_16x16x32_bf16 v[40:43], v[170:173], v[208:211], v[40:43]
	v_mfma_f32_16x16x32_bf16 v[36:39], v[162:165], v[216:219], v[36:39]
	v_mfma_f32_16x16x32_bf16 v[32:35], v[170:173], v[216:219], v[32:35]
	v_mfma_f32_16x16x32_bf16 v[60:63], v[166:169], v[196:199], v[60:63]
	v_mfma_f32_16x16x32_bf16 v[56:59], v[174:177], v[196:199], v[56:59]
	v_mfma_f32_16x16x32_bf16 v[52:55], v[166:169], v[204:207], v[52:55]
	v_mfma_f32_16x16x32_bf16 v[48:51], v[174:177], v[204:207], v[48:51]
	v_mfma_f32_16x16x32_bf16 v[44:47], v[166:169], v[212:215], v[44:47]
	v_mfma_f32_16x16x32_bf16 v[40:43], v[174:177], v[212:215], v[40:43]
	v_mfma_f32_16x16x32_bf16 v[36:39], v[166:169], v[220:223], v[36:39]
	v_mfma_f32_16x16x32_bf16 v[32:35], v[174:177], v[220:223], v[32:35]
	s_setprio 0
	s_barrier
	s_add_i32 s21, s85, s50
	s_mov_b32 m0, s21
	ds_read_b128 v[180:183], v149 offset:16384
	ds_read_b128 v[196:199], v149 offset:17408
	ds_read_b128 v[200:203], v149 offset:18432
	ds_read_b128 v[204:207], v149 offset:19456
	ds_read_b128 v[208:211], v149 offset:20480
	ds_read_b128 v[212:215], v149 offset:21504
	ds_read_b128 v[216:219], v149 offset:22528
	ds_read_b128 v[220:223], v149 offset:23552
	global_load_lds_dwordx4 v96, s[78:79]
	s_add_i32 m0, s21, 0x2000
	s_add_i32 s20, s20, s50
	global_load_lds_dwordx4 v142, s[78:79]
	s_mov_b32 m0, s20
	s_nop 0
	global_load_lds_dwordx4 v151, s[78:79]
	s_add_i32 m0, s20, 0x2000
	s_nop 0
	global_load_lds_dwordx4 v178, s[78:79]
	s_mov_b32 m0, s51
	s_nop 0
	global_load_lds_dwordx4 v138, s[48:49]
	s_mov_b32 m0, s86
	s_nop 0
	global_load_lds_dwordx4 v140, s[48:49]
	s_waitcnt vmcnt(8)
	s_waitcnt lgkmcnt(0)
	s_barrier
	s_setprio 1
	s_waitcnt lgkmcnt(0)
	v_mfma_f32_16x16x32_bf16 v[92:95], v[122:125], v[180:183], v[92:95]
	v_mfma_f32_16x16x32_bf16 v[88:91], v[154:157], v[180:183], v[88:91]
	v_mfma_f32_16x16x32_bf16 v[84:87], v[122:125], v[200:203], v[84:87]
	v_mfma_f32_16x16x32_bf16 v[80:83], v[154:157], v[200:203], v[80:83]
	v_mfma_f32_16x16x32_bf16 v[76:79], v[122:125], v[208:211], v[76:79]
	v_mfma_f32_16x16x32_bf16 v[72:75], v[154:157], v[208:211], v[72:75]
	v_mfma_f32_16x16x32_bf16 v[68:71], v[122:125], v[216:219], v[68:71]
	v_mfma_f32_16x16x32_bf16 v[64:67], v[154:157], v[216:219], v[64:67]
	v_mfma_f32_16x16x32_bf16 v[92:95], v[126:129], v[196:199], v[92:95]
	v_mfma_f32_16x16x32_bf16 v[88:91], v[158:161], v[196:199], v[88:91]
	v_mfma_f32_16x16x32_bf16 v[84:87], v[126:129], v[204:207], v[84:87]
	v_mfma_f32_16x16x32_bf16 v[80:83], v[158:161], v[204:207], v[80:83]
	v_mfma_f32_16x16x32_bf16 v[76:79], v[126:129], v[212:215], v[76:79]
	v_mfma_f32_16x16x32_bf16 v[72:75], v[158:161], v[212:215], v[72:75]
	v_mfma_f32_16x16x32_bf16 v[68:71], v[126:129], v[220:223], v[68:71]
	v_mfma_f32_16x16x32_bf16 v[64:67], v[158:161], v[220:223], v[64:67]
	v_mfma_f32_16x16x32_bf16 v[28:31], v[162:165], v[180:183], v[28:31]
	v_mfma_f32_16x16x32_bf16 v[24:27], v[170:173], v[180:183], v[24:27]
	v_mfma_f32_16x16x32_bf16 v[20:23], v[162:165], v[200:203], v[20:23]
	v_mfma_f32_16x16x32_bf16 v[16:19], v[170:173], v[200:203], v[16:19]
	v_mfma_f32_16x16x32_bf16 v[12:15], v[162:165], v[208:211], v[12:15]
	v_mfma_f32_16x16x32_bf16 v[8:11], v[170:173], v[208:211], v[8:11]
	v_mfma_f32_16x16x32_bf16 v[4:7], v[162:165], v[216:219], v[4:7]
	v_mfma_f32_16x16x32_bf16 v[0:3], v[170:173], v[216:219], v[0:3]
	v_mfma_f32_16x16x32_bf16 v[28:31], v[166:169], v[196:199], v[28:31]
	v_mfma_f32_16x16x32_bf16 v[24:27], v[174:177], v[196:199], v[24:27]
	v_mfma_f32_16x16x32_bf16 v[20:23], v[166:169], v[204:207], v[20:23]
	v_mfma_f32_16x16x32_bf16 v[16:19], v[174:177], v[204:207], v[16:19]
	v_mfma_f32_16x16x32_bf16 v[12:15], v[166:169], v[212:215], v[12:15]
	v_mfma_f32_16x16x32_bf16 v[8:11], v[174:177], v[212:215], v[8:11]
	v_mfma_f32_16x16x32_bf16 v[4:7], v[166:169], v[220:223], v[4:7]
	v_mfma_f32_16x16x32_bf16 v[0:3], v[174:177], v[220:223], v[0:3]
	s_setprio 0
	s_barrier
; #define PG8_STAGE(bufoff, gbase, voff) do { _Pragma("unroll") for (int _i = 0; _i < 2; ++_i) \
;         __builtin_amdgcn_global_load_lds((const unsigned*)((const char*)(gbase) + (voff)[_i]), (PG8_LAS unsigned*)(lds + (bufoff) + ldsw + _i * 8192), 16, 0, 0); } while (0)
; #define PG8_LDA(dst, b, h) do { _Pragma("unroll") for (int m = 0; m < 4; ++m) _Pragma("unroll") for (int k = 0; k < 2; ++k) dst[m][k] = *(const PG8_LAS bf16x8*)(lds + PG8_SA(b, h) + aoff + m * 2048 + k * 1024); } while (0)
; #define PG8_LDB(dst, b, h) do { _Pragma("unroll") for (int n = 0; n < 2; ++n) _Pragma("unroll") for (int k = 0; k < 2; ++k) dst[n][k] = *(const PG8_LAS bf16x8*)(lds + PG8_SB(b, h) + boff + n * 2048 + k * 1024); } while (0)
; #define PG8_MMA(ai, bj, At, Bt) do { __builtin_amdgcn_s_setprio(1); _Pragma("unroll") for (int m = 0; m < 4; ++m) _Pragma("unroll") for (int n = 0; n < 2; ++n) _Pragma("unroll") for (int k = 0; k < 2; ++k) \
;         acc[ai][bj][m][n] = __builtin_amdgcn_mfma_f32_16x16x32_bf16(Bt[n][k], At[m][k], acc[ai][bj][m][n], 0, 0, 0); __builtin_amdgcn_s_setprio(0); } while (0)
; #define PG8_WAIT_V(n) asm volatile("s_waitcnt vmcnt(" #n ")" ::: "memory")
; #define PG8_WAIT_L(n) asm volatile("s_waitcnt lgkmcnt(" #n ")" ::: "memory")
; #define PG8_BAR __builtin_amdgcn_s_barrier()
; #define PG8_SCHED __builtin_amdgcn_sched_barrier(0)
; template <class Epi, class Sched, bool ALIGN_EPI = false, bool SP2 = false>
; __device__ __forceinline__ void gemm_phase(PG8_LAS unsigned char* lds, const Gemm g, const Sched& S, const Epi& E, int wid_s_) {
;     ...
;             PG8_LDB(B0, 1, 0); PG8_LDB(B1, 1, 1); PG8_SCHED; PG8_LDA(At, 1, 0); PG8_STAGE(PG8_SA(0, 1), a2 + hstep, voffA);
;             PG8_WAIT_V(8); PG8_WAIT_L(0); PG8_BAR; PG8_MMA(0, 0, At, B0); PG8_MMA(0, 1, At, B1); PG8_BAR; PG8_SCHED;
;             PG8_LDA(At, 1, 1); PG8_STAGE(PG8_SB(1, 0), b3, voffB); PG8_STAGE(PG8_SB(1, 1), b3 + hstep, voffB); PG8_STAGE(PG8_SA(1, 0), a3, voffA);
;             PG8_WAIT_V(8); PG8_WAIT_L(0); PG8_BAR; PG8_MMA(1, 0, At, B0); PG8_MMA(1, 1, At, B1); PG8_BAR; PG8_SCHED;
	s_add_i32 s20, 16, 0x18000
	s_add_i32 s21, 16, 0x1c000
	v_add_u32_e32 v158, s20, v147
	v_add_u32_e32 v174, s21, v147
	ds_read_b128 v[122:125], v158
	ds_read_b128 v[126:129], v158 offset:1024
	ds_read_b128 v[154:157], v158 offset:2048
	ds_read_b128 v[158:161], v158 offset:3072
	ds_read_b128 v[162:165], v174
	ds_read_b128 v[166:169], v174 offset:1024
	ds_read_b128 v[170:173], v174 offset:2048
	ds_read_b128 v[174:177], v174 offset:3072
	s_mov_b32 m0, s87
	ds_read_b128 v[180:183], v149 offset:32768
	ds_read_b128 v[196:199], v149 offset:33792
	ds_read_b128 v[200:203], v149 offset:34816
	ds_read_b128 v[204:207], v149 offset:35840
	ds_read_b128 v[208:211], v149 offset:36864
	ds_read_b128 v[212:215], v149 offset:37888
	ds_read_b128 v[216:219], v149 offset:38912
	ds_read_b128 v[220:223], v149 offset:39936
	global_load_lds_dwordx4 v179, s[48:49]
	s_mov_b32 m0, s88
	s_nop 0
	global_load_lds_dwordx4 v188, s[48:49]
	s_waitcnt vmcnt(8)
	s_waitcnt lgkmcnt(0)
	s_barrier
	s_setprio 1
	s_waitcnt lgkmcnt(0)
	v_mfma_f32_16x16x32_bf16 v[134:137], v[122:125], v[180:183], v[134:137]
	v_mfma_f32_16x16x32_bf16 v[130:133], v[154:157], v[180:183], v[130:133]
	v_mfma_f32_16x16x32_bf16 v[118:121], v[122:125], v[200:203], v[118:121]
	v_mfma_f32_16x16x32_bf16 v[114:117], v[154:157], v[200:203], v[114:117]
	v_mfma_f32_16x16x32_bf16 v[110:113], v[122:125], v[208:211], v[110:113]
	v_mfma_f32_16x16x32_bf16 v[106:109], v[154:157], v[208:211], v[106:109]
	v_mfma_f32_16x16x32_bf16 v[102:105], v[122:125], v[216:219], v[102:105]
	v_mfma_f32_16x16x32_bf16 v[98:101], v[154:157], v[216:219], v[98:101]
	v_mfma_f32_16x16x32_bf16 v[134:137], v[126:129], v[196:199], v[134:137]
	v_mfma_f32_16x16x32_bf16 v[130:133], v[158:161], v[196:199], v[130:133]
	v_mfma_f32_16x16x32_bf16 v[118:121], v[126:129], v[204:207], v[118:121]
	v_mfma_f32_16x16x32_bf16 v[114:117], v[158:161], v[204:207], v[114:117]
	v_mfma_f32_16x16x32_bf16 v[110:113], v[126:129], v[212:215], v[110:113]
	v_mfma_f32_16x16x32_bf16 v[106:109], v[158:161], v[212:215], v[106:109]
	v_mfma_f32_16x16x32_bf16 v[102:105], v[126:129], v[220:223], v[102:105]
	v_mfma_f32_16x16x32_bf16 v[98:101], v[158:161], v[220:223], v[98:101]
	v_mfma_f32_16x16x32_bf16 v[60:63], v[162:165], v[180:183], v[60:63]
	v_mfma_f32_16x16x32_bf16 v[56:59], v[170:173], v[180:183], v[56:59]
	v_mfma_f32_16x16x32_bf16 v[52:55], v[162:165], v[200:203], v[52:55]
	v_mfma_f32_16x16x32_bf16 v[48:51], v[170:173], v[200:203], v[48:51]
	v_mfma_f32_16x16x32_bf16 v[44:47], v[162:165], v[208:211], v[44:47]
	v_mfma_f32_16x16x32_bf16 v[40:43], v[170:173], v[208:211], v[40:43]
	v_mfma_f32_16x16x32_bf16 v[36:39], v[162:165], v[216:219], v[36:39]
	v_mfma_f32_16x16x32_bf16 v[32:35], v[170:173], v[216:219], v[32:35]
	v_mfma_f32_16x16x32_bf16 v[60:63], v[166:169], v[196:199], v[60:63]
	v_mfma_f32_16x16x32_bf16 v[56:59], v[174:177], v[196:199], v[56:59]
	v_mfma_f32_16x16x32_bf16 v[52:55], v[166:169], v[204:207], v[52:55]
	v_mfma_f32_16x16x32_bf16 v[48:51], v[174:177], v[204:207], v[48:51]
	v_mfma_f32_16x16x32_bf16 v[44:47], v[166:169], v[212:215], v[44:47]
	v_mfma_f32_16x16x32_bf16 v[40:43], v[174:177], v[212:215], v[40:43]
	v_mfma_f32_16x16x32_bf16 v[36:39], v[166:169], v[220:223], v[36:39]
	v_mfma_f32_16x16x32_bf16 v[32:35], v[174:177], v[220:223], v[32:35]
	s_setprio 0
	s_barrier
	s_add_i32 s20, s20, s50
	s_mov_b32 m0, s20
	ds_read_b128 v[180:183], v149 offset:49152
	ds_read_b128 v[196:199], v149 offset:50176
	ds_read_b128 v[200:203], v149 offset:51200
	ds_read_b128 v[204:207], v149 offset:52224
	ds_read_b128 v[208:211], v149 offset:53248
	ds_read_b128 v[212:215], v149 offset:54272
	ds_read_b128 v[216:219], v149 offset:55296
	ds_read_b128 v[220:223], v149 offset:56320
	global_load_lds_dwordx4 v189, s[78:79]
	s_add_i32 m0, s20, 0x2000
	s_add_i32 s20, s21, s50
	global_load_lds_dwordx4 v192, s[78:79]
	s_mov_b32 m0, s20
	s_nop 0
	global_load_lds_dwordx4 v193, s[78:79]
	s_add_i32 m0, s20, 0x2000
	s_nop 0
	global_load_lds_dwordx4 v194, s[78:79]
	s_mov_b32 m0, s89
	s_nop 0
	global_load_lds_dwordx4 v195, s[48:49]
	s_mov_b32 m0, s90
	s_nop 0
	global_load_lds_dwordx4 v224, s[48:49]
	s_waitcnt vmcnt(8)
	s_waitcnt lgkmcnt(0)
	s_barrier
	s_setprio 1
	s_waitcnt lgkmcnt(0)
	v_mfma_f32_16x16x32_bf16 v[92:95], v[122:125], v[180:183], v[92:95]
	v_mfma_f32_16x16x32_bf16 v[88:91], v[154:157], v[180:183], v[88:91]
	v_mfma_f32_16x16x32_bf16 v[84:87], v[122:125], v[200:203], v[84:87]
	v_mfma_f32_16x16x32_bf16 v[80:83], v[154:157], v[200:203], v[80:83]
	v_mfma_f32_16x16x32_bf16 v[76:79], v[122:125], v[208:211], v[76:79]
	v_mfma_f32_16x16x32_bf16 v[72:75], v[154:157], v[208:211], v[72:75]
	v_mfma_f32_16x16x32_bf16 v[68:71], v[122:125], v[216:219], v[68:71]
	v_mfma_f32_16x16x32_bf16 v[64:67], v[154:157], v[216:219], v[64:67]
	v_mfma_f32_16x16x32_bf16 v[92:95], v[126:129], v[196:199], v[92:95]
	v_mfma_f32_16x16x32_bf16 v[88:91], v[158:161], v[196:199], v[88:91]
	v_mfma_f32_16x16x32_bf16 v[84:87], v[126:129], v[204:207], v[84:87]
	v_mfma_f32_16x16x32_bf16 v[80:83], v[158:161], v[204:207], v[80:83]
	v_mfma_f32_16x16x32_bf16 v[76:79], v[126:129], v[212:215], v[76:79]
	v_mfma_f32_16x16x32_bf16 v[72:75], v[158:161], v[212:215], v[72:75]
	v_mfma_f32_16x16x32_bf16 v[68:71], v[126:129], v[220:223], v[68:71]
	v_mfma_f32_16x16x32_bf16 v[64:67], v[158:161], v[220:223], v[64:67]
	v_mfma_f32_16x16x32_bf16 v[28:31], v[162:165], v[180:183], v[28:31]
	v_mfma_f32_16x16x32_bf16 v[24:27], v[170:173], v[180:183], v[24:27]
	v_mfma_f32_16x16x32_bf16 v[20:23], v[162:165], v[200:203], v[20:23]
	v_mfma_f32_16x16x32_bf16 v[16:19], v[170:173], v[200:203], v[16:19]
	v_mfma_f32_16x16x32_bf16 v[12:15], v[162:165], v[208:211], v[12:15]
	v_mfma_f32_16x16x32_bf16 v[8:11], v[170:173], v[208:211], v[8:11]
	v_mfma_f32_16x16x32_bf16 v[4:7], v[162:165], v[216:219], v[4:7]
	v_mfma_f32_16x16x32_bf16 v[0:3], v[170:173], v[216:219], v[0:3]
	v_mfma_f32_16x16x32_bf16 v[28:31], v[166:169], v[196:199], v[28:31]
	v_mfma_f32_16x16x32_bf16 v[24:27], v[174:177], v[196:199], v[24:27]
	v_mfma_f32_16x16x32_bf16 v[20:23], v[166:169], v[204:207], v[20:23]
	v_mfma_f32_16x16x32_bf16 v[16:19], v[174:177], v[204:207], v[16:19]
	v_mfma_f32_16x16x32_bf16 v[12:15], v[166:169], v[212:215], v[12:15]
	v_mfma_f32_16x16x32_bf16 v[8:11], v[174:177], v[212:215], v[8:11]
	v_mfma_f32_16x16x32_bf16 v[4:7], v[166:169], v[220:223], v[4:7]
	v_mfma_f32_16x16x32_bf16 v[0:3], v[174:177], v[220:223], v[0:3]
	s_setprio 0
	s_barrier
	s_add_u32 vcc_lo, vcc_lo, 0x100
	s_addc_u32 vcc_hi, vcc_hi, 0
	s_add_u32 s2, s2, 0x100
	s_addc_u32 s3, s3, 0
	s_cmp_ge_i32 s84, s4
	s_mov_b32 s48, s84
	s_cbranch_scc0 .LBB0_628
	s_movk_i32 s21, 0x3fff
	v_add_u32_e32 v192, 64, v191

; #define PG8_STAGE(bufoff, gbase, voff) do { _Pragma("unroll") for (int _i = 0; _i < 2; ++_i) \
;         __builtin_amdgcn_global_load_lds((const unsigned*)((const char*)(gbase) + (voff)[_i]), (PG8_LAS unsigned*)(lds + (bufoff) + ldsw + _i * 8192), 16, 0, 0); } while (0)
; #define PG8_LDA(dst, b, h) do { _Pragma("unroll") for (int m = 0; m < 4; ++m) _Pragma("unroll") for (int k = 0; k < 2; ++k) dst[m][k] = *(const PG8_LAS bf16x8*)(lds + PG8_SA(b, h) + aoff + m * 2048 + k * 1024); } while (0)
; #define PG8_LDB(dst, b, h) do { _Pragma("unroll") for (int n = 0; n < 2; ++n) _Pragma("unroll") for (int k = 0; k < 2; ++k) dst[n][k] = *(const PG8_LAS bf16x8*)(lds + PG8_SB(b, h) + boff + n * 2048 + k * 1024); } while (0)
; #define PG8_MMA(ai, bj, At, Bt) do { __builtin_amdgcn_s_setprio(1); _Pragma("unroll") for (int m = 0; m < 4; ++m) _Pragma("unroll") for (int n = 0; n < 2; ++n) _Pragma("unroll") for (int k = 0; k < 2; ++k) \
;         acc[ai][bj][m][n] = __builtin_amdgcn_mfma_f32_16x16x32_bf16(Bt[n][k], At[m][k], acc[ai][bj][m][n], 0, 0, 0); __builtin_amdgcn_s_setprio(0); } while (0)
; #define PG8_WAIT_V(n) asm volatile("s_waitcnt vmcnt(" #n ")" ::: "memory")
; #define PG8_WAIT_L(n) asm volatile("s_waitcnt lgkmcnt(" #n ")" ::: "memory")
; template <class Epi, class Sched, bool ALIGN_EPI = false, bool SP2 = false>
; __device__ __forceinline__ void gemm_phase(PG8_LAS unsigned char* lds, const Gemm g, const Sched& S, const Epi& E, int wid_s_) {
;     ...
;             const bool last = (t == nt - 2);
;             const char* a1 = cA + (size_t)(t + 1) * kstep;
;             const char* a2 = last ? nA : cA + (size_t)(t + 2) * kstep; const char* b2 = last ? nB : cB + (size_t)(t + 2) * kstep;
;             const char* a3 = a2 + kstep; const char* b3 = b2 + kstep;
;             if (last && has_next) S.a_ready(nxt);
;             if constexpr (SP2) {
;             PG8_LDB(B0, 0, 0); PG8_LDB(B1, 0, 1); PG8_SCHED; PG8_LDA(At, 0, 0); PG8_STAGE(PG8_SA(1, 1), a1 + hstep, voffA);
;             PG8_WAIT_V(8); PG8_WAIT_L(0); PG8_BAR; PG8_MMA(0, 0, At, B0); PG8_MMA(0, 1, At, B1); PG8_BAR; PG8_SCHED;
;             PG8_LDA(At, 0, 1); PG8_STAGE(PG8_SB(0, 0), b2, voffB); PG8_STAGE(PG8_SB(0, 1), b2 + hstep, voffB); PG8_STAGE(PG8_SA(0, 0), a2, voffA);
;             PG8_WAIT_V(8); PG8_WAIT_L(0); PG8_BAR; PG8_MMA(1, 0, At, B0); PG8_MMA(1, 1, At, B1); PG8_BAR; PG8_SCHED;
.LBB0_788:
	s_add_i32 vcc_hi, s20, 2
	s_add_u32 s8, s18, 0x80
	s_addc_u32 s9, s19, 0
	s_add_i32 s78, 16, 0x10000
	s_cmp_eq_u32 s85, s20
	s_cselect_b32 s21, s3, s9
	s_cselect_b32 s20, s2, s8
	v_add_u32_e32 v96, s78, v147
	s_cselect_b32 s9, s17, vcc_lo
	s_cselect_b32 s8, s16, s91
	s_add_i32 s79, 16, 0x14000
	ds_read_b128 v[142:145], v96
	ds_read_b128 v[150:153], v96 offset:1024
	ds_read_b128 v[154:157], v96 offset:2048
	ds_read_b128 v[158:161], v96 offset:3072
	v_add_u32_e32 v96, s79, v147
	ds_read_b128 v[162:165], v96
	ds_read_b128 v[166:169], v96 offset:1024
	ds_read_b128 v[170:173], v96 offset:2048
	ds_read_b128 v[174:177], v96 offset:3072
	v_lshl_add_u64 v[178:179], s[18:19], 0, v[140:141]
	s_add_i32 m0, s48, 0xc000
	ds_read_b128 v[180:183], v149
	ds_read_b128 v[196:199], v149 offset:1024
	ds_read_b128 v[200:203], v149 offset:2048
	ds_read_b128 v[204:207], v149 offset:3072
	ds_read_b128 v[208:211], v149 offset:4096
	ds_read_b128 v[212:215], v149 offset:5120
	ds_read_b128 v[216:219], v149 offset:6144
	ds_read_b128 v[220:223], v149 offset:7168
	global_load_lds_dwordx4 v[178:179], off
	v_lshl_add_u64 v[178:179], s[18:19], 0, v[138:139]
	s_add_i32 m0, s48, 0xe000
	s_nop 0
	global_load_lds_dwordx4 v[178:179], off
	s_waitcnt vmcnt(8)
	s_waitcnt lgkmcnt(0)
	s_barrier
	s_setprio 1
	s_waitcnt lgkmcnt(0)
	v_mfma_f32_16x16x32_bf16 v[126:129], v[142:145], v[180:183], v[126:129]
	v_mfma_f32_16x16x32_bf16 v[122:125], v[154:157], v[180:183], v[122:125]
	v_mfma_f32_16x16x32_bf16 v[118:121], v[142:145], v[200:203], v[118:121]
	v_mfma_f32_16x16x32_bf16 v[114:117], v[154:157], v[200:203], v[114:117]
	v_mfma_f32_16x16x32_bf16 v[106:109], v[142:145], v[208:211], v[106:109]
	v_mfma_f32_16x16x32_bf16 v[98:101], v[154:157], v[208:211], v[98:101]
	v_mfma_f32_16x16x32_bf16 v[88:91], v[142:145], v[216:219], v[88:91]
	v_mfma_f32_16x16x32_bf16 v[80:83], v[154:157], v[216:219], v[80:83]
	v_mfma_f32_16x16x32_bf16 v[126:129], v[150:153], v[196:199], v[126:129]
	v_mfma_f32_16x16x32_bf16 v[122:125], v[158:161], v[196:199], v[122:125]
	v_mfma_f32_16x16x32_bf16 v[118:121], v[150:153], v[204:207], v[118:121]
	v_mfma_f32_16x16x32_bf16 v[114:117], v[158:161], v[204:207], v[114:117]
	v_mfma_f32_16x16x32_bf16 v[106:109], v[150:153], v[212:215], v[106:109]
	v_mfma_f32_16x16x32_bf16 v[98:101], v[158:161], v[212:215], v[98:101]
	v_mfma_f32_16x16x32_bf16 v[88:91], v[150:153], v[220:223], v[88:91]
	v_mfma_f32_16x16x32_bf16 v[80:83], v[158:161], v[220:223], v[80:83]
	v_mfma_f32_16x16x32_bf16 v[110:113], v[162:165], v[180:183], v[110:113]
	v_mfma_f32_16x16x32_bf16 v[102:105], v[170:173], v[180:183], v[102:105]
	v_mfma_f32_16x16x32_bf16 v[92:95], v[162:165], v[200:203], v[92:95]
	v_mfma_f32_16x16x32_bf16 v[84:87], v[170:173], v[200:203], v[84:87]
	v_mfma_f32_16x16x32_bf16 v[76:79], v[162:165], v[208:211], v[76:79]
	v_mfma_f32_16x16x32_bf16 v[72:75], v[170:173], v[208:211], v[72:75]
	v_mfma_f32_16x16x32_bf16 v[68:71], v[162:165], v[216:219], v[68:71]
	v_mfma_f32_16x16x32_bf16 v[64:67], v[170:173], v[216:219], v[64:67]
	v_mfma_f32_16x16x32_bf16 v[110:113], v[166:169], v[196:199], v[110:113]
	v_mfma_f32_16x16x32_bf16 v[102:105], v[174:177], v[196:199], v[102:105]
	v_mfma_f32_16x16x32_bf16 v[92:95], v[166:169], v[204:207], v[92:95]
	v_mfma_f32_16x16x32_bf16 v[84:87], v[174:177], v[204:207], v[84:87]
	v_mfma_f32_16x16x32_bf16 v[76:79], v[166:169], v[212:215], v[76:79]
	v_mfma_f32_16x16x32_bf16 v[72:75], v[174:177], v[212:215], v[72:75]
	v_mfma_f32_16x16x32_bf16 v[68:71], v[166:169], v[220:223], v[68:71]
	v_mfma_f32_16x16x32_bf16 v[64:67], v[174:177], v[220:223], v[64:67]
	s_setprio 0
	s_barrier
	s_add_i32 s78, s78, s41
	v_lshl_add_u64 v[178:179], s[8:9], 0, v[132:133]
	s_mov_b32 m0, s78
	ds_read_b128 v[180:183], v149 offset:16384
	ds_read_b128 v[196:199], v149 offset:17408
	ds_read_b128 v[200:203], v149 offset:18432
	ds_read_b128 v[204:207], v149 offset:19456
	ds_read_b128 v[208:211], v149 offset:20480
	ds_read_b128 v[212:215], v149 offset:21504
	ds_read_b128 v[216:219], v149 offset:22528
	ds_read_b128 v[220:223], v149 offset:23552
	global_load_lds_dwordx4 v[178:179], off
	s_add_i32 m0, s78, 0x2000
	v_lshl_add_u64 v[188:189], s[8:9], 0, v[136:137]
	s_add_u32 s8, s8, s4
	s_addc_u32 s9, s9, s5
	s_add_i32 s78, s79, s41
	global_load_lds_dwordx4 v[188:189], off
	v_lshl_add_u64 v[194:195], s[8:9], 0, v[132:133]
	s_mov_b32 m0, s78
	v_lshl_add_u64 v[224:225], s[8:9], 0, v[136:137]
	global_load_lds_dwordx4 v[194:195], off
	s_add_i32 m0, s78, 0x2000
	v_lshl_add_u64 v[226:227], s[20:21], 0, v[130:131]
	global_load_lds_dwordx4 v[224:225], off
	s_mov_b32 m0, s48
	v_lshl_add_u64 v[228:229], s[20:21], 0, v[134:135]
	global_load_lds_dwordx4 v[226:227], off
	s_mov_b32 m0, s49
	s_nop 0
	global_load_lds_dwordx4 v[228:229], off
	s_waitcnt vmcnt(8)
	s_waitcnt lgkmcnt(0)
	s_barrier
; #define PG8_STAGE(bufoff, gbase, voff) do { _Pragma("unroll") for (int _i = 0; _i < 2; ++_i) \
;         __builtin_amdgcn_global_load_lds((const unsigned*)((const char*)(gbase) + (voff)[_i]), (PG8_LAS unsigned*)(lds + (bufoff) + ldsw + _i * 8192), 16, 0, 0); } while (0)
; #define PG8_LDA(dst, b, h) do { _Pragma("unroll") for (int m = 0; m < 4; ++m) _Pragma("unroll") for (int k = 0; k < 2; ++k) dst[m][k] = *(const PG8_LAS bf16x8*)(lds + PG8_SA(b, h) + aoff + m * 2048 + k * 1024); } while (0)
; #define PG8_LDB(dst, b, h) do { _Pragma("unroll") for (int n = 0; n < 2; ++n) _Pragma("unroll") for (int k = 0; k < 2; ++k) dst[n][k] = *(const PG8_LAS bf16x8*)(lds + PG8_SB(b, h) + boff + n * 2048 + k * 1024); } while (0)
; #define PG8_MMA(ai, bj, At, Bt) do { __builtin_amdgcn_s_setprio(1); _Pragma("unroll") for (int m = 0; m < 4; ++m) _Pragma("unroll") for (int n = 0; n < 2; ++n) _Pragma("unroll") for (int k = 0; k < 2; ++k) \
;         acc[ai][bj][m][n] = __builtin_amdgcn_mfma_f32_16x16x32_bf16(Bt[n][k], At[m][k], acc[ai][bj][m][n], 0, 0, 0); __builtin_amdgcn_s_setprio(0); } while (0)
; #define PG8_WAIT_V(n) asm volatile("s_waitcnt vmcnt(" #n ")" ::: "memory")
; #define PG8_WAIT_L(n) asm volatile("s_waitcnt lgkmcnt(" #n ")" ::: "memory")
; #define PG8_BAR __builtin_amdgcn_s_barrier()
; #define PG8_SCHED __builtin_amdgcn_sched_barrier(0)
; template <class Epi, class Sched, bool ALIGN_EPI = false, bool SP2 = false>
; __device__ __forceinline__ void gemm_phase(PG8_LAS unsigned char* lds, const Gemm g, const Sched& S, const Epi& E, int wid_s_) {
;     ...
;             PG8_WAIT_V(8); PG8_WAIT_L(0); PG8_BAR; PG8_MMA(1, 0, At, B0); PG8_MMA(1, 1, At, B1); PG8_BAR; PG8_SCHED;
;             PG8_LDB(B0, 1, 0); PG8_LDB(B1, 1, 1); PG8_SCHED; PG8_LDA(At, 1, 0); PG8_STAGE(PG8_SA(0, 1), a2 + hstep, voffA);
;             PG8_WAIT_V(8); PG8_WAIT_L(0); PG8_BAR; PG8_MMA(0, 0, At, B0); PG8_MMA(0, 1, At, B1); PG8_BAR; PG8_SCHED;
	s_setprio 1
	s_waitcnt lgkmcnt(0)
	v_mfma_f32_16x16x32_bf16 v[60:63], v[142:145], v[180:183], v[60:63]
	v_mfma_f32_16x16x32_bf16 v[56:59], v[154:157], v[180:183], v[56:59]
	v_mfma_f32_16x16x32_bf16 v[52:55], v[142:145], v[200:203], v[52:55]
	v_mfma_f32_16x16x32_bf16 v[48:51], v[154:157], v[200:203], v[48:51]
	v_mfma_f32_16x16x32_bf16 v[40:43], v[142:145], v[208:211], v[40:43]
	v_mfma_f32_16x16x32_bf16 v[32:35], v[154:157], v[208:211], v[32:35]
	v_mfma_f32_16x16x32_bf16 v[24:27], v[142:145], v[216:219], v[24:27]
	v_mfma_f32_16x16x32_bf16 v[16:19], v[154:157], v[216:219], v[16:19]
	v_mfma_f32_16x16x32_bf16 v[60:63], v[150:153], v[196:199], v[60:63]
	v_mfma_f32_16x16x32_bf16 v[56:59], v[158:161], v[196:199], v[56:59]
	v_mfma_f32_16x16x32_bf16 v[52:55], v[150:153], v[204:207], v[52:55]
	v_mfma_f32_16x16x32_bf16 v[48:51], v[158:161], v[204:207], v[48:51]
	v_mfma_f32_16x16x32_bf16 v[40:43], v[150:153], v[212:215], v[40:43]
	v_mfma_f32_16x16x32_bf16 v[32:35], v[158:161], v[212:215], v[32:35]
	v_mfma_f32_16x16x32_bf16 v[24:27], v[150:153], v[220:223], v[24:27]
	v_mfma_f32_16x16x32_bf16 v[16:19], v[158:161], v[220:223], v[16:19]
	v_mfma_f32_16x16x32_bf16 v[44:47], v[162:165], v[180:183], v[44:47]
	v_mfma_f32_16x16x32_bf16 v[36:39], v[170:173], v[180:183], v[36:39]
	v_mfma_f32_16x16x32_bf16 v[28:31], v[162:165], v[200:203], v[28:31]
	v_mfma_f32_16x16x32_bf16 v[20:23], v[170:173], v[200:203], v[20:23]
	v_mfma_f32_16x16x32_bf16 v[12:15], v[162:165], v[208:211], v[12:15]
	v_mfma_f32_16x16x32_bf16 v[8:11], v[170:173], v[208:211], v[8:11]
	v_mfma_f32_16x16x32_bf16 v[4:7], v[162:165], v[216:219], v[4:7]
	v_mfma_f32_16x16x32_bf16 v[0:3], v[170:173], v[216:219], v[0:3]
	v_mfma_f32_16x16x32_bf16 v[44:47], v[166:169], v[196:199], v[44:47]
	v_mfma_f32_16x16x32_bf16 v[36:39], v[174:177], v[196:199], v[36:39]
	v_mfma_f32_16x16x32_bf16 v[28:31], v[166:169], v[204:207], v[28:31]
	v_mfma_f32_16x16x32_bf16 v[20:23], v[174:177], v[204:207], v[20:23]
	v_mfma_f32_16x16x32_bf16 v[12:15], v[166:169], v[212:215], v[12:15]
	v_mfma_f32_16x16x32_bf16 v[8:11], v[174:177], v[212:215], v[8:11]
	v_mfma_f32_16x16x32_bf16 v[4:7], v[166:169], v[220:223], v[4:7]
	v_mfma_f32_16x16x32_bf16 v[0:3], v[174:177], v[220:223], v[0:3]
	s_setprio 0
	s_barrier
	s_add_i32 s78, 16, 0x18000
	v_add_u32_e32 v96, s78, v147
	s_add_i32 s79, 16, 0x1c000
	ds_read_b128 v[142:145], v96
	ds_read_b128 v[150:153], v96 offset:1024
	ds_read_b128 v[154:157], v96 offset:2048
	ds_read_b128 v[158:161], v96 offset:3072
	v_add_u32_e32 v96, s79, v147
	ds_read_b128 v[162:165], v96
	ds_read_b128 v[166:169], v96 offset:1024
	ds_read_b128 v[170:173], v96 offset:2048
	ds_read_b128 v[174:177], v96 offset:3072
	s_add_u32 s8, s20, s4
	s_addc_u32 s9, s21, s5
	s_mov_b32 m0, s50
	v_lshl_add_u64 v[230:231], s[8:9], 0, v[130:131]
	ds_read_b128 v[180:183], v149 offset:32768
	ds_read_b128 v[196:199], v149 offset:33792
	ds_read_b128 v[200:203], v149 offset:34816
	ds_read_b128 v[204:207], v149 offset:35840
	ds_read_b128 v[208:211], v149 offset:36864
	ds_read_b128 v[212:215], v149 offset:37888
	ds_read_b128 v[216:219], v149 offset:38912
	ds_read_b128 v[220:223], v149 offset:39936
	global_load_lds_dwordx4 v[230:231], off
	v_lshl_add_u64 v[230:231], s[8:9], 0, v[134:135]
	s_mov_b32 m0, s51
	s_nop 0
	global_load_lds_dwordx4 v[230:231], off
	s_waitcnt vmcnt(8)
	s_waitcnt lgkmcnt(0)
	s_barrier
	s_setprio 1
	s_waitcnt lgkmcnt(0)
	v_mfma_f32_16x16x32_bf16 v[126:129], v[142:145], v[180:183], v[126:129]
	v_mfma_f32_16x16x32_bf16 v[122:125], v[154:157], v[180:183], v[122:125]
	v_mfma_f32_16x16x32_bf16 v[118:121], v[142:145], v[200:203], v[118:121]
	v_mfma_f32_16x16x32_bf16 v[114:117], v[154:157], v[200:203], v[114:117]
	v_mfma_f32_16x16x32_bf16 v[106:109], v[142:145], v[208:211], v[106:109]
	v_mfma_f32_16x16x32_bf16 v[98:101], v[154:157], v[208:211], v[98:101]
	v_mfma_f32_16x16x32_bf16 v[88:91], v[142:145], v[216:219], v[88:91]
	v_mfma_f32_16x16x32_bf16 v[80:83], v[154:157], v[216:219], v[80:83]
	v_mfma_f32_16x16x32_bf16 v[126:129], v[150:153], v[196:199], v[126:129]
	v_mfma_f32_16x16x32_bf16 v[122:125], v[158:161], v[196:199], v[122:125]
	v_mfma_f32_16x16x32_bf16 v[118:121], v[150:153], v[204:207], v[118:121]
	v_mfma_f32_16x16x32_bf16 v[114:117], v[158:161], v[204:207], v[114:117]
	v_mfma_f32_16x16x32_bf16 v[106:109], v[150:153], v[212:215], v[106:109]
	v_mfma_f32_16x16x32_bf16 v[98:101], v[158:161], v[212:215], v[98:101]
	v_mfma_f32_16x16x32_bf16 v[88:91], v[150:153], v[220:223], v[88:91]
	v_mfma_f32_16x16x32_bf16 v[80:83], v[158:161], v[220:223], v[80:83]
	v_mfma_f32_16x16x32_bf16 v[110:113], v[162:165], v[180:183], v[110:113]
	v_mfma_f32_16x16x32_bf16 v[102:105], v[170:173], v[180:183], v[102:105]
	v_mfma_f32_16x16x32_bf16 v[92:95], v[162:165], v[200:203], v[92:95]
	v_mfma_f32_16x16x32_bf16 v[84:87], v[170:173], v[200:203], v[84:87]
	v_mfma_f32_16x16x32_bf16 v[76:79], v[162:165], v[208:211], v[76:79]
	v_mfma_f32_16x16x32_bf16 v[72:75], v[170:173], v[208:211], v[72:75]
	v_mfma_f32_16x16x32_bf16 v[68:71], v[162:165], v[216:219], v[68:71]
	v_mfma_f32_16x16x32_bf16 v[64:67], v[170:173], v[216:219], v[64:67]
	v_mfma_f32_16x16x32_bf16 v[110:113], v[166:169], v[196:199], v[110:113]
	v_mfma_f32_16x16x32_bf16 v[102:105], v[174:177], v[196:199], v[102:105]
	v_mfma_f32_16x16x32_bf16 v[92:95], v[166:169], v[204:207], v[92:95]
	v_mfma_f32_16x16x32_bf16 v[84:87], v[174:177], v[204:207], v[84:87]
	v_mfma_f32_16x16x32_bf16 v[76:79], v[166:169], v[212:215], v[76:79]
	v_mfma_f32_16x16x32_bf16 v[72:75], v[174:177], v[212:215], v[72:75]
	v_mfma_f32_16x16x32_bf16 v[68:71], v[166:169], v[220:223], v[68:71]
	v_mfma_f32_16x16x32_bf16 v[64:67], v[174:177], v[220:223], v[64:67]
	s_setprio 0
	s_barrier
; #define PG8_STAGE(bufoff, gbase, voff) do { _Pragma("unroll") for (int _i = 0; _i < 2; ++_i) \
;         __builtin_amdgcn_global_load_lds((const unsigned*)((const char*)(gbase) + (voff)[_i]), (PG8_LAS unsigned*)(lds + (bufoff) + ldsw + _i * 8192), 16, 0, 0); } while (0)
; #define PG8_LDA(dst, b, h) do { _Pragma("unroll") for (int m = 0; m < 4; ++m) _Pragma("unroll") for (int k = 0; k < 2; ++k) dst[m][k] = *(const PG8_LAS bf16x8*)(lds + PG8_SA(b, h) + aoff + m * 2048 + k * 1024); } while (0)
; #define PG8_MMA(ai, bj, At, Bt) do { __builtin_amdgcn_s_setprio(1); _Pragma("unroll") for (int m = 0; m < 4; ++m) _Pragma("unroll") for (int n = 0; n < 2; ++n) _Pragma("unroll") for (int k = 0; k < 2; ++k) \
;         acc[ai][bj][m][n] = __builtin_amdgcn_mfma_f32_16x16x32_bf16(Bt[n][k], At[m][k], acc[ai][bj][m][n], 0, 0, 0); __builtin_amdgcn_s_setprio(0); } while (0)
; #define PG8_WAIT_V(n) asm volatile("s_waitcnt vmcnt(" #n ")" ::: "memory")
; #define PG8_WAIT_L(n) asm volatile("s_waitcnt lgkmcnt(" #n ")" ::: "memory")
; #define PG8_BAR __builtin_amdgcn_s_barrier()
; #define PG8_SCHED __builtin_amdgcn_sched_barrier(0)
; template <class Epi, class Sched, bool ALIGN_EPI = false, bool SP2 = false>
; __device__ __forceinline__ void gemm_phase(PG8_LAS unsigned char* lds, const Gemm g, const Sched& S, const Epi& E, int wid_s_) {
;     ...
;             PG8_LDA(At, 1, 1); PG8_STAGE(PG8_SB(1, 0), b3, voffB); PG8_STAGE(PG8_SB(1, 1), b3 + hstep, voffB); PG8_STAGE(PG8_SA(1, 0), a3, voffA);
;             PG8_WAIT_V(8); PG8_WAIT_L(0); PG8_BAR; PG8_MMA(1, 0, At, B0); PG8_MMA(1, 1, At, B1); PG8_BAR; PG8_SCHED;
	s_add_i32 s8, s78, s41
	v_lshl_add_u64 v[178:179], v[178:179], 0, s[42:43]
	s_mov_b32 m0, s8
	ds_read_b128 v[180:183], v149 offset:49152
	ds_read_b128 v[196:199], v149 offset:50176
	ds_read_b128 v[200:203], v149 offset:51200
	ds_read_b128 v[204:207], v149 offset:52224
	ds_read_b128 v[208:211], v149 offset:53248
	ds_read_b128 v[212:215], v149 offset:54272
	ds_read_b128 v[216:219], v149 offset:55296
	ds_read_b128 v[220:223], v149 offset:56320
	global_load_lds_dwordx4 v[178:179], off
	v_lshl_add_u64 v[178:179], v[188:189], 0, s[42:43]
	s_add_i32 m0, s8, 0x2000
	s_add_i32 s8, s79, s41
	global_load_lds_dwordx4 v[178:179], off
	v_lshl_add_u64 v[178:179], v[194:195], 0, s[42:43]
	s_mov_b32 m0, s8
	s_nop 0
	global_load_lds_dwordx4 v[178:179], off
	v_lshl_add_u64 v[178:179], v[224:225], 0, s[42:43]
	s_add_i32 m0, s8, 0x2000
	s_nop 0
	global_load_lds_dwordx4 v[178:179], off
	v_lshl_add_u64 v[178:179], v[226:227], 0, s[42:43]
	s_mov_b32 m0, s80
	s_nop 0
	global_load_lds_dwordx4 v[178:179], off
	v_lshl_add_u64 v[178:179], v[228:229], 0, s[42:43]
	s_mov_b32 m0, s81
	s_nop 0
	global_load_lds_dwordx4 v[178:179], off
	s_waitcnt vmcnt(8)
	s_waitcnt lgkmcnt(0)
	s_barrier
	s_setprio 1
	s_waitcnt lgkmcnt(0)
	v_mfma_f32_16x16x32_bf16 v[60:63], v[142:145], v[180:183], v[60:63]
	v_mfma_f32_16x16x32_bf16 v[56:59], v[154:157], v[180:183], v[56:59]
	v_mfma_f32_16x16x32_bf16 v[52:55], v[142:145], v[200:203], v[52:55]
	v_mfma_f32_16x16x32_bf16 v[48:51], v[154:157], v[200:203], v[48:51]
	v_mfma_f32_16x16x32_bf16 v[40:43], v[142:145], v[208:211], v[40:43]
	v_mfma_f32_16x16x32_bf16 v[32:35], v[154:157], v[208:211], v[32:35]
	v_mfma_f32_16x16x32_bf16 v[24:27], v[142:145], v[216:219], v[24:27]
	v_mfma_f32_16x16x32_bf16 v[16:19], v[154:157], v[216:219], v[16:19]
	v_mfma_f32_16x16x32_bf16 v[60:63], v[150:153], v[196:199], v[60:63]
	v_mfma_f32_16x16x32_bf16 v[56:59], v[158:161], v[196:199], v[56:59]
	v_mfma_f32_16x16x32_bf16 v[52:55], v[150:153], v[204:207], v[52:55]
	v_mfma_f32_16x16x32_bf16 v[48:51], v[158:161], v[204:207], v[48:51]
	v_mfma_f32_16x16x32_bf16 v[40:43], v[150:153], v[212:215], v[40:43]
	v_mfma_f32_16x16x32_bf16 v[32:35], v[158:161], v[212:215], v[32:35]
	v_mfma_f32_16x16x32_bf16 v[24:27], v[150:153], v[220:223], v[24:27]
	v_mfma_f32_16x16x32_bf16 v[16:19], v[158:161], v[220:223], v[16:19]
	v_mfma_f32_16x16x32_bf16 v[44:47], v[162:165], v[180:183], v[44:47]
	v_mfma_f32_16x16x32_bf16 v[36:39], v[170:173], v[180:183], v[36:39]
	v_mfma_f32_16x16x32_bf16 v[28:31], v[162:165], v[200:203], v[28:31]
	v_mfma_f32_16x16x32_bf16 v[20:23], v[170:173], v[200:203], v[20:23]
	v_mfma_f32_16x16x32_bf16 v[12:15], v[162:165], v[208:211], v[12:15]
	v_mfma_f32_16x16x32_bf16 v[8:11], v[170:173], v[208:211], v[8:11]
	v_mfma_f32_16x16x32_bf16 v[4:7], v[162:165], v[216:219], v[4:7]
	v_mfma_f32_16x16x32_bf16 v[0:3], v[170:173], v[216:219], v[0:3]
	v_mfma_f32_16x16x32_bf16 v[44:47], v[166:169], v[196:199], v[44:47]
	v_mfma_f32_16x16x32_bf16 v[36:39], v[174:177], v[196:199], v[36:39]
	v_mfma_f32_16x16x32_bf16 v[28:31], v[166:169], v[204:207], v[28:31]
	v_mfma_f32_16x16x32_bf16 v[20:23], v[174:177], v[204:207], v[20:23]
	v_mfma_f32_16x16x32_bf16 v[12:15], v[166:169], v[212:215], v[12:15]
	v_mfma_f32_16x16x32_bf16 v[8:11], v[174:177], v[212:215], v[8:11]
	v_mfma_f32_16x16x32_bf16 v[4:7], v[166:169], v[220:223], v[4:7]
	v_mfma_f32_16x16x32_bf16 v[0:3], v[174:177], v[220:223], v[0:3]
	s_setprio 0
	s_barrier
	s_add_u32 s91, s91, 0x100
	s_addc_u32 vcc_lo, vcc_lo, 0
	s_add_u32 s18, s18, 0x100
	s_addc_u32 s19, s19, 0
	s_cmp_ge_i32 vcc_hi, s82
	s_mov_b32 s20, vcc_hi
	s_cbranch_scc0 .LBB0_788
; __device__ __forceinline__ unsigned cvtpk(float lo, float hi) { f32x2_t v = {lo, hi}; bf16x2_t b = __builtin_convertvector(v, bf16x2_t); return __builtin_bit_cast(unsigned, b); }
;     __device__ __forceinline__ void operator()(const f32x4 (&acc)[2][2][4][2], const Unit& u, int wr, int wc, int fr, int fq) const {
;     ...
;             for (int m = 0; m < 4; ++m) { const int row = row0 + ai * HALF + m * 16, jg = row >> 9, d = row & 511;
; #pragma unroll
;                 for (int bj = 0; bj < 2; ++bj) { const int n = col0 + bj * HALF, half = n >> 10;
;                     const f32x4 v0 = acc[ai][bj][m][0] * scale, v1 = acc[ai][bj][m][1] * scale;
;                     u32x4 w; w.x = cvtpk(v0[0], v0[1]); w.y = cvtpk(v0[2], v0[3]); w.z = cvtpk(v1[0], v1[1]); w.w = cvtpk(v1[2], v1[3]);
;                     *(u32x4*)(O + ((size_t)(jg * 2 + half) * 512 + d) * 1024 + (n & 1023)) = w; } }
	s_mov_b32 s8, 0x39b504f3
	v_pk_mul_f32 v[128:129], v[128:129], s[8:9] op_sel_hi:[1,0]
	v_pk_mul_f32 v[126:127], v[126:127], s[8:9] op_sel_hi:[1,0]
	v_pk_mul_f32 v[124:125], v[124:125], s[8:9] op_sel_hi:[1,0]
	v_pk_mul_f32 v[122:123], v[122:123], s[8:9] op_sel_hi:[1,0]
	v_pk_mul_f32 v[142:143], v[112:113], s[8:9] op_sel_hi:[1,0]
	v_pk_mul_f32 v[144:145], v[110:111], s[8:9] op_sel_hi:[1,0]
	v_pk_mul_f32 v[152:153], v[104:105], s[8:9] op_sel_hi:[1,0]
	v_pk_mul_f32 v[154:155], v[102:103], s[8:9] op_sel_hi:[1,0]
	v_pk_mul_f32 v[102:103], v[120:121], s[8:9] op_sel_hi:[1,0]
	v_pk_mul_f32 v[104:105], v[118:119], s[8:9] op_sel_hi:[1,0]
	v_pk_mul_f32 v[110:111], v[116:117], s[8:9] op_sel_hi:[1,0]
	v_pk_mul_f32 v[112:113], v[114:115], s[8:9] op_sel_hi:[1,0]
	v_pk_mul_f32 v[114:115], v[94:95], s[8:9] op_sel_hi:[1,0]
	v_pk_mul_f32 v[116:117], v[92:93], s[8:9] op_sel_hi:[1,0]
	v_pk_mul_f32 v[118:119], v[86:87], s[8:9] op_sel_hi:[1,0]
	v_pk_mul_f32 v[120:121], v[84:85], s[8:9] op_sel_hi:[1,0]
	v_pk_mul_f32 v[84:85], v[108:109], s[8:9] op_sel_hi:[1,0]
	v_pk_mul_f32 v[86:87], v[106:107], s[8:9] op_sel_hi:[1,0]
	v_pk_mul_f32 v[92:93], v[100:101], s[8:9] op_sel_hi:[1,0]
	v_pk_mul_f32 v[94:95], v[98:99], s[8:9] op_sel_hi:[1,0]
	v_pk_mul_f32 v[98:99], v[78:79], s[8:9] op_sel_hi:[1,0]
	v_pk_mul_f32 v[100:101], v[76:77], s[8:9] op_sel_hi:[1,0]
	v_pk_mul_f32 v[106:107], v[74:75], s[8:9] op_sel_hi:[1,0]
	v_pk_mul_f32 v[108:109], v[72:73], s[8:9] op_sel_hi:[1,0]
	v_pk_mul_f32 v[72:73], v[90:91], s[8:9] op_sel_hi:[1,0]
	v_pk_mul_f32 v[74:75], v[88:89], s[8:9] op_sel_hi:[1,0]
	v_pk_mul_f32 v[76:77], v[82:83], s[8:9] op_sel_hi:[1,0]
	v_pk_mul_f32 v[78:79], v[80:81], s[8:9] op_sel_hi:[1,0]
	v_pk_mul_f32 v[70:71], v[70:71], s[8:9] op_sel_hi:[1,0]
	v_pk_mul_f32 v[68:69], v[68:69], s[8:9] op_sel_hi:[1,0]
	v_pk_mul_f32 v[66:67], v[66:67], s[8:9] op_sel_hi:[1,0]
	v_pk_mul_f32 v[64:65], v[64:65], s[8:9] op_sel_hi:[1,0]
	v_pk_mul_f32 v[62:63], v[62:63], s[8:9] op_sel_hi:[1,0]
	v_pk_mul_f32 v[60:61], v[60:61], s[8:9] op_sel_hi:[1,0]
	v_pk_mul_f32 v[58:59], v[58:59], s[8:9] op_sel_hi:[1,0]
	v_pk_mul_f32 v[56:57], v[56:57], s[8:9] op_sel_hi:[1,0]
	v_pk_mul_f32 v[80:81], v[46:47], s[8:9] op_sel_hi:[1,0]
	v_pk_mul_f32 v[82:83], v[44:45], s[8:9] op_sel_hi:[1,0]
	v_pk_mul_f32 v[88:89], v[38:39], s[8:9] op_sel_hi:[1,0]
	v_pk_mul_f32 v[90:91], v[36:37], s[8:9] op_sel_hi:[1,0]
	v_pk_mul_f32 v[36:37], v[54:55], s[8:9] op_sel_hi:[1,0]
	v_pk_mul_f32 v[38:39], v[52:53], s[8:9] op_sel_hi:[1,0]
	v_pk_mul_f32 v[44:45], v[50:51], s[8:9] op_sel_hi:[1,0]
	v_pk_mul_f32 v[46:47], v[48:49], s[8:9] op_sel_hi:[1,0]
	v_pk_mul_f32 v[48:49], v[30:31], s[8:9] op_sel_hi:[1,0]
	v_pk_mul_f32 v[50:51], v[28:29], s[8:9] op_sel_hi:[1,0]
	v_pk_mul_f32 v[52:53], v[22:23], s[8:9] op_sel_hi:[1,0]
	v_pk_mul_f32 v[54:55], v[20:21], s[8:9] op_sel_hi:[1,0]
	v_pk_mul_f32 v[20:21], v[42:43], s[8:9] op_sel_hi:[1,0]
	v_pk_mul_f32 v[22:23], v[40:41], s[8:9] op_sel_hi:[1,0]
	v_pk_mul_f32 v[28:29], v[34:35], s[8:9] op_sel_hi:[1,0]
	v_pk_mul_f32 v[30:31], v[32:33], s[8:9] op_sel_hi:[1,0]
	v_pk_mul_f32 v[32:33], v[14:15], s[8:9] op_sel_hi:[1,0]
	v_pk_mul_f32 v[34:35], v[12:13], s[8:9] op_sel_hi:[1,0]
	v_pk_mul_f32 v[40:41], v[10:11], s[8:9] op_sel_hi:[1,0]
	v_pk_mul_f32 v[42:43], v[8:9], s[8:9] op_sel_hi:[1,0]
	v_pk_mul_f32 v[8:9], v[26:27], s[8:9] op_sel_hi:[1,0]
	v_pk_mul_f32 v[10:11], v[24:25], s[8:9] op_sel_hi:[1,0]
	v_pk_mul_f32 v[12:13], v[18:19], s[8:9] op_sel_hi:[1,0]
	v_pk_mul_f32 v[14:15], v[16:17], s[8:9] op_sel_hi:[1,0]
	v_pk_mul_f32 v[6:7], v[6:7], s[8:9] op_sel_hi:[1,0]
	v_pk_mul_f32 v[4:5], v[4:5], s[8:9] op_sel_hi:[1,0]
	v_pk_mul_f32 v[2:3], v[2:3], s[8:9] op_sel_hi:[1,0]
	v_pk_mul_f32 v[0:1], v[0:1], s[8:9] op_sel_hi:[1,0]

; #define PG8_STAGE(bufoff, gbase, voff) do { _Pragma("unroll") for (int _i = 0; _i < 2; ++_i) \
;         __builtin_amdgcn_global_load_lds((const unsigned*)((const char*)(gbase) + (voff)[_i]), (PG8_LAS unsigned*)(lds + (bufoff) + ldsw + _i * 8192), 16, 0, 0); } while (0)
; #define PG8_LDA(dst, b, h) do { _Pragma("unroll") for (int m = 0; m < 4; ++m) _Pragma("unroll") for (int k = 0; k < 2; ++k) dst[m][k] = *(const PG8_LAS bf16x8*)(lds + PG8_SA(b, h) + aoff + m * 2048 + k * 1024); } while (0)
; #define PG8_LDB(dst, b, h) do { _Pragma("unroll") for (int n = 0; n < 2; ++n) _Pragma("unroll") for (int k = 0; k < 2; ++k) dst[n][k] = *(const PG8_LAS bf16x8*)(lds + PG8_SB(b, h) + boff + n * 2048 + k * 1024); } while (0)
; #define PG8_MMA(ai, bj, At, Bt) do { __builtin_amdgcn_s_setprio(1); _Pragma("unroll") for (int m = 0; m < 4; ++m) _Pragma("unroll") for (int n = 0; n < 2; ++n) _Pragma("unroll") for (int k = 0; k < 2; ++k) \
;         acc[ai][bj][m][n] = __builtin_amdgcn_mfma_f32_16x16x32_bf16(Bt[n][k], At[m][k], acc[ai][bj][m][n], 0, 0, 0); __builtin_amdgcn_s_setprio(0); } while (0)
; #define PG8_WAIT_V(n) asm volatile("s_waitcnt vmcnt(" #n ")" ::: "memory")
; #define PG8_WAIT_L(n) asm volatile("s_waitcnt lgkmcnt(" #n ")" ::: "memory")
; template <class Epi, class Sched, bool ALIGN_EPI = false, bool SP2 = false>
; __device__ __forceinline__ void gemm_phase(PG8_LAS unsigned char* lds, const Gemm g, const Sched& S, const Epi& E, int wid_s_) {
;     ...
;             const bool last = (t == nt - 2);
;             const char* a1 = cA + (size_t)(t + 1) * kstep;
;             const char* a2 = last ? nA : cA + (size_t)(t + 2) * kstep; const char* b2 = last ? nB : cB + (size_t)(t + 2) * kstep;
;             const char* a3 = a2 + kstep; const char* b3 = b2 + kstep;
;             if (last && has_next) S.a_ready(nxt);
;             if constexpr (SP2) {
;             PG8_LDB(B0, 0, 0); PG8_LDB(B1, 0, 1); PG8_SCHED; PG8_LDA(At, 0, 0); PG8_STAGE(PG8_SA(1, 1), a1 + hstep, voffA);
;             PG8_WAIT_V(8); PG8_WAIT_L(0); PG8_BAR; PG8_MMA(0, 0, At, B0); PG8_MMA(0, 1, At, B1); PG8_BAR; PG8_SCHED;
;             PG8_LDA(At, 0, 1); PG8_STAGE(PG8_SB(0, 0), b2, voffB); PG8_STAGE(PG8_SB(0, 1), b2 + hstep, voffB); PG8_STAGE(PG8_SA(0, 0), a2, voffA);
;             PG8_WAIT_V(8); PG8_WAIT_L(0); PG8_BAR; PG8_MMA(1, 0, At, B0); PG8_MMA(1, 1, At, B1); PG8_BAR; PG8_SCHED;
.LBB0_886:
	s_add_i32 s91, s18, 2
	s_add_u32 s8, s2, 0x80
	s_addc_u32 s19, s3, 0
	s_add_i32 s25, 16, 0x10000
	s_cmp_eq_u32 s88, s18
	s_cselect_b32 s19, s15, s19
	s_cselect_b32 s18, s14, s8
	v_add_u32_e32 v96, s25, v147
	s_cselect_b32 s79, s17, vcc_hi
	s_cselect_b32 s78, s16, vcc_lo
	s_add_i32 s8, 16, 0x14000
	ds_read_b128 v[132:135], v96
	ds_read_b128 v[136:139], v96 offset:1024
	ds_read_b128 v[160:163], v96 offset:2048
	ds_read_b128 v[164:167], v96 offset:3072
	v_add_u32_e32 v96, s8, v147
	ds_read_b128 v[168:171], v96
	ds_read_b128 v[172:175], v96 offset:1024
	ds_read_b128 v[176:179], v96 offset:2048
	ds_read_b128 v[180:183], v96 offset:3072
	s_add_i32 m0, s41, 0xc000
	ds_read_b128 v[194:197], v150
	ds_read_b128 v[198:201], v150 offset:1024
	ds_read_b128 v[202:205], v150 offset:2048
	ds_read_b128 v[206:209], v150 offset:3072
	ds_read_b128 v[210:213], v150 offset:4096
	ds_read_b128 v[214:217], v150 offset:5120
	ds_read_b128 v[218:221], v150 offset:6144
	ds_read_b128 v[222:225], v150 offset:7168
	global_load_lds_dwordx4 v156, s[2:3]
	s_add_i32 m0, s41, 0xe000
	s_nop 0
	global_load_lds_dwordx4 v154, s[2:3]
	s_waitcnt vmcnt(8)
	s_waitcnt lgkmcnt(0)
	s_barrier
	s_setprio 1
	s_waitcnt lgkmcnt(0)
	v_mfma_f32_16x16x32_bf16 v[128:131], v[132:135], v[194:197], v[128:131]
	v_mfma_f32_16x16x32_bf16 v[124:127], v[160:163], v[194:197], v[124:127]
	v_mfma_f32_16x16x32_bf16 v[120:123], v[132:135], v[202:205], v[120:123]
	v_mfma_f32_16x16x32_bf16 v[112:115], v[160:163], v[202:205], v[112:115]
	v_mfma_f32_16x16x32_bf16 v[104:107], v[132:135], v[210:213], v[104:107]
	v_mfma_f32_16x16x32_bf16 v[92:95], v[160:163], v[210:213], v[92:95]
	v_mfma_f32_16x16x32_bf16 v[84:87], v[132:135], v[218:221], v[84:87]
	v_mfma_f32_16x16x32_bf16 v[76:79], v[160:163], v[218:221], v[76:79]
	v_mfma_f32_16x16x32_bf16 v[128:131], v[136:139], v[198:201], v[128:131]
	v_mfma_f32_16x16x32_bf16 v[124:127], v[164:167], v[198:201], v[124:127]
	v_mfma_f32_16x16x32_bf16 v[120:123], v[136:139], v[206:209], v[120:123]
	v_mfma_f32_16x16x32_bf16 v[112:115], v[164:167], v[206:209], v[112:115]
	v_mfma_f32_16x16x32_bf16 v[104:107], v[136:139], v[214:217], v[104:107]
	v_mfma_f32_16x16x32_bf16 v[92:95], v[164:167], v[214:217], v[92:95]
	v_mfma_f32_16x16x32_bf16 v[84:87], v[136:139], v[222:225], v[84:87]
	v_mfma_f32_16x16x32_bf16 v[76:79], v[164:167], v[222:225], v[76:79]
	v_mfma_f32_16x16x32_bf16 v[116:119], v[168:171], v[194:197], v[116:119]
	v_mfma_f32_16x16x32_bf16 v[108:111], v[176:179], v[194:197], v[108:111]
	v_mfma_f32_16x16x32_bf16 v[98:101], v[168:171], v[202:205], v[100:103]
	v_mfma_f32_16x16x32_bf16 v[88:91], v[176:179], v[202:205], v[88:91]
	v_mfma_f32_16x16x32_bf16 v[80:83], v[168:171], v[210:213], v[80:83]
	v_mfma_f32_16x16x32_bf16 v[72:75], v[176:179], v[210:213], v[72:75]
	v_mfma_f32_16x16x32_bf16 v[68:71], v[168:171], v[218:221], v[68:71]
	v_mfma_f32_16x16x32_bf16 v[64:67], v[176:179], v[218:221], v[64:67]
	v_mfma_f32_16x16x32_bf16 v[116:119], v[172:175], v[198:201], v[116:119]
	v_mfma_f32_16x16x32_bf16 v[108:111], v[180:183], v[198:201], v[108:111]
	v_mfma_f32_16x16x32_bf16 v[98:101], v[172:175], v[206:209], v[98:101]
	v_mfma_f32_16x16x32_bf16 v[88:91], v[180:183], v[206:209], v[88:91]
	v_mfma_f32_16x16x32_bf16 v[80:83], v[172:175], v[214:217], v[80:83]
	v_mfma_f32_16x16x32_bf16 v[72:75], v[180:183], v[214:217], v[72:75]
	v_mfma_f32_16x16x32_bf16 v[68:71], v[172:175], v[222:225], v[68:71]
	v_mfma_f32_16x16x32_bf16 v[64:67], v[180:183], v[222:225], v[64:67]
	s_setprio 0
	s_barrier
	s_add_i32 s25, s25, s40
	s_mov_b32 m0, s25
	ds_read_b128 v[194:197], v150 offset:16384
	ds_read_b128 v[198:201], v150 offset:17408
	ds_read_b128 v[202:205], v150 offset:18432
	ds_read_b128 v[206:209], v150 offset:19456
	ds_read_b128 v[210:213], v150 offset:20480
	ds_read_b128 v[214:217], v150 offset:21504
	ds_read_b128 v[218:221], v150 offset:22528
	ds_read_b128 v[222:225], v150 offset:23552
	global_load_lds_dwordx4 v142, s[78:79]
	s_add_i32 m0, s25, 0x2000
	s_add_i32 s8, s8, s40
	global_load_lds_dwordx4 v152, s[78:79]
	s_mov_b32 m0, s8
	s_nop 0
	global_load_lds_dwordx4 v226, s[78:79]
	s_add_i32 m0, s8, 0x2000
	s_nop 0
	global_load_lds_dwordx4 v227, s[78:79]
	s_mov_b32 m0, s41
	s_nop 0
	global_load_lds_dwordx4 v140, s[18:19]
	s_mov_b32 m0, s48
	s_nop 0
	global_load_lds_dwordx4 v144, s[18:19]
	s_waitcnt vmcnt(8)
	s_waitcnt lgkmcnt(0)
	s_barrier
	s_setprio 1
	s_waitcnt lgkmcnt(0)
	v_mfma_f32_16x16x32_bf16 v[60:63], v[132:135], v[194:197], v[60:63]
	v_mfma_f32_16x16x32_bf16 v[56:59], v[160:163], v[194:197], v[56:59]
	v_mfma_f32_16x16x32_bf16 v[52:55], v[132:135], v[202:205], v[52:55]
	v_mfma_f32_16x16x32_bf16 v[48:51], v[160:163], v[202:205], v[48:51]
	v_mfma_f32_16x16x32_bf16 v[36:39], v[132:135], v[210:213], v[36:39]
	v_mfma_f32_16x16x32_bf16 v[32:35], v[160:163], v[210:213], v[32:35]
	v_mfma_f32_16x16x32_bf16 v[20:23], v[132:135], v[218:221], v[20:23]
	v_mfma_f32_16x16x32_bf16 v[16:19], v[160:163], v[218:221], v[16:19]
	v_mfma_f32_16x16x32_bf16 v[60:63], v[136:139], v[198:201], v[60:63]
	v_mfma_f32_16x16x32_bf16 v[56:59], v[164:167], v[198:201], v[56:59]
	v_mfma_f32_16x16x32_bf16 v[52:55], v[136:139], v[206:209], v[52:55]
	v_mfma_f32_16x16x32_bf16 v[48:51], v[164:167], v[206:209], v[48:51]
	v_mfma_f32_16x16x32_bf16 v[36:39], v[136:139], v[214:217], v[36:39]
	v_mfma_f32_16x16x32_bf16 v[32:35], v[164:167], v[214:217], v[32:35]
	v_mfma_f32_16x16x32_bf16 v[20:23], v[136:139], v[222:225], v[20:23]
	v_mfma_f32_16x16x32_bf16 v[16:19], v[164:167], v[222:225], v[16:19]
	v_mfma_f32_16x16x32_bf16 v[44:47], v[168:171], v[194:197], v[44:47]
	v_mfma_f32_16x16x32_bf16 v[40:43], v[176:179], v[194:197], v[40:43]
	v_mfma_f32_16x16x32_bf16 v[28:31], v[168:171], v[202:205], v[28:31]
	v_mfma_f32_16x16x32_bf16 v[24:27], v[176:179], v[202:205], v[24:27]
	v_mfma_f32_16x16x32_bf16 v[12:15], v[168:171], v[210:213], v[12:15]
	v_mfma_f32_16x16x32_bf16 v[8:11], v[176:179], v[210:213], v[8:11]
	v_mfma_f32_16x16x32_bf16 v[4:7], v[168:171], v[218:221], v[4:7]
	v_mfma_f32_16x16x32_bf16 v[0:3], v[176:179], v[218:221], v[0:3]
	v_mfma_f32_16x16x32_bf16 v[44:47], v[172:175], v[198:201], v[44:47]
	v_mfma_f32_16x16x32_bf16 v[40:43], v[180:183], v[198:201], v[40:43]
	v_mfma_f32_16x16x32_bf16 v[28:31], v[172:175], v[206:209], v[28:31]
	v_mfma_f32_16x16x32_bf16 v[24:27], v[180:183], v[206:209], v[24:27]
	v_mfma_f32_16x16x32_bf16 v[12:15], v[172:175], v[214:217], v[12:15]
	v_mfma_f32_16x16x32_bf16 v[8:11], v[180:183], v[214:217], v[8:11]
	v_mfma_f32_16x16x32_bf16 v[4:7], v[172:175], v[222:225], v[4:7]
	v_mfma_f32_16x16x32_bf16 v[0:3], v[180:183], v[222:225], v[0:3]
	s_setprio 0
	s_barrier
; #define PG8_STAGE(bufoff, gbase, voff) do { _Pragma("unroll") for (int _i = 0; _i < 2; ++_i) \
;         __builtin_amdgcn_global_load_lds((const unsigned*)((const char*)(gbase) + (voff)[_i]), (PG8_LAS unsigned*)(lds + (bufoff) + ldsw + _i * 8192), 16, 0, 0); } while (0)
; #define PG8_LDA(dst, b, h) do { _Pragma("unroll") for (int m = 0; m < 4; ++m) _Pragma("unroll") for (int k = 0; k < 2; ++k) dst[m][k] = *(const PG8_LAS bf16x8*)(lds + PG8_SA(b, h) + aoff + m * 2048 + k * 1024); } while (0)
; #define PG8_LDB(dst, b, h) do { _Pragma("unroll") for (int n = 0; n < 2; ++n) _Pragma("unroll") for (int k = 0; k < 2; ++k) dst[n][k] = *(const PG8_LAS bf16x8*)(lds + PG8_SB(b, h) + boff + n * 2048 + k * 1024); } while (0)
; #define PG8_MMA(ai, bj, At, Bt) do { __builtin_amdgcn_s_setprio(1); _Pragma("unroll") for (int m = 0; m < 4; ++m) _Pragma("unroll") for (int n = 0; n < 2; ++n) _Pragma("unroll") for (int k = 0; k < 2; ++k) \
;         acc[ai][bj][m][n] = __builtin_amdgcn_mfma_f32_16x16x32_bf16(Bt[n][k], At[m][k], acc[ai][bj][m][n], 0, 0, 0); __builtin_amdgcn_s_setprio(0); } while (0)
; #define PG8_WAIT_V(n) asm volatile("s_waitcnt vmcnt(" #n ")" ::: "memory")
; #define PG8_WAIT_L(n) asm volatile("s_waitcnt lgkmcnt(" #n ")" ::: "memory")
; #define PG8_BAR __builtin_amdgcn_s_barrier()
; #define PG8_SCHED __builtin_amdgcn_sched_barrier(0)
; template <class Epi, class Sched, bool ALIGN_EPI = false, bool SP2 = false>
; __device__ __forceinline__ void gemm_phase(PG8_LAS unsigned char* lds, const Gemm g, const Sched& S, const Epi& E, int wid_s_) {
;     ...
;             PG8_LDB(B0, 1, 0); PG8_LDB(B1, 1, 1); PG8_SCHED; PG8_LDA(At, 1, 0); PG8_STAGE(PG8_SA(0, 1), a2 + hstep, voffA);
;             PG8_WAIT_V(8); PG8_WAIT_L(0); PG8_BAR; PG8_MMA(0, 0, At, B0); PG8_MMA(0, 1, At, B1); PG8_BAR; PG8_SCHED;
;             PG8_LDA(At, 1, 1); PG8_STAGE(PG8_SB(1, 0), b3, voffB); PG8_STAGE(PG8_SB(1, 1), b3 + hstep, voffB); PG8_STAGE(PG8_SA(1, 0), a3, voffA);
;             PG8_WAIT_V(8); PG8_WAIT_L(0); PG8_BAR; PG8_MMA(1, 0, At, B0); PG8_MMA(1, 1, At, B1); PG8_BAR; PG8_SCHED;
	s_add_i32 s8, 16, 0x18000
	v_add_u32_e32 v96, s8, v147
	s_add_i32 s25, 16, 0x1c000
	ds_read_b128 v[132:135], v96
	ds_read_b128 v[136:139], v96 offset:1024
	ds_read_b128 v[160:163], v96 offset:2048
	ds_read_b128 v[164:167], v96 offset:3072
	v_add_u32_e32 v96, s25, v147
	ds_read_b128 v[168:171], v96
	ds_read_b128 v[172:175], v96 offset:1024
	ds_read_b128 v[176:179], v96 offset:2048
	ds_read_b128 v[180:183], v96 offset:3072
	s_mov_b32 m0, s49
	ds_read_b128 v[194:197], v150 offset:32768
	ds_read_b128 v[198:201], v150 offset:33792
	ds_read_b128 v[202:205], v150 offset:34816
	ds_read_b128 v[206:209], v150 offset:35840
	ds_read_b128 v[210:213], v150 offset:36864
	ds_read_b128 v[214:217], v150 offset:37888
	ds_read_b128 v[218:221], v150 offset:38912
	ds_read_b128 v[222:225], v150 offset:39936
	global_load_lds_dwordx4 v228, s[18:19]
	s_mov_b32 m0, s50
	s_nop 0
	global_load_lds_dwordx4 v229, s[18:19]
	s_waitcnt vmcnt(8)
	s_waitcnt lgkmcnt(0)
	s_barrier
	s_setprio 1
	s_waitcnt lgkmcnt(0)
	v_mfma_f32_16x16x32_bf16 v[128:131], v[132:135], v[194:197], v[128:131]
	v_mfma_f32_16x16x32_bf16 v[124:127], v[160:163], v[194:197], v[124:127]
	v_mfma_f32_16x16x32_bf16 v[120:123], v[132:135], v[202:205], v[120:123]
	v_mfma_f32_16x16x32_bf16 v[112:115], v[160:163], v[202:205], v[112:115]
	v_mfma_f32_16x16x32_bf16 v[102:105], v[132:135], v[210:213], v[104:107]
	v_mfma_f32_16x16x32_bf16 v[92:95], v[160:163], v[210:213], v[92:95]
	v_mfma_f32_16x16x32_bf16 v[84:87], v[132:135], v[218:221], v[84:87]
	v_mfma_f32_16x16x32_bf16 v[76:79], v[160:163], v[218:221], v[76:79]
	v_mfma_f32_16x16x32_bf16 v[128:131], v[136:139], v[198:201], v[128:131]
	v_mfma_f32_16x16x32_bf16 v[124:127], v[164:167], v[198:201], v[124:127]
	v_mfma_f32_16x16x32_bf16 v[120:123], v[136:139], v[206:209], v[120:123]
	v_mfma_f32_16x16x32_bf16 v[112:115], v[164:167], v[206:209], v[112:115]
	v_mfma_f32_16x16x32_bf16 v[104:107], v[136:139], v[214:217], v[102:105]
	v_mfma_f32_16x16x32_bf16 v[92:95], v[164:167], v[214:217], v[92:95]
	v_mfma_f32_16x16x32_bf16 v[84:87], v[136:139], v[222:225], v[84:87]
	v_mfma_f32_16x16x32_bf16 v[76:79], v[164:167], v[222:225], v[76:79]
	v_mfma_f32_16x16x32_bf16 v[116:119], v[168:171], v[194:197], v[116:119]
	v_mfma_f32_16x16x32_bf16 v[108:111], v[176:179], v[194:197], v[108:111]
	v_mfma_f32_16x16x32_bf16 v[98:101], v[168:171], v[202:205], v[98:101]
	v_mfma_f32_16x16x32_bf16 v[88:91], v[176:179], v[202:205], v[88:91]
	v_mfma_f32_16x16x32_bf16 v[80:83], v[168:171], v[210:213], v[80:83]
	v_mfma_f32_16x16x32_bf16 v[72:75], v[176:179], v[210:213], v[72:75]
	v_mfma_f32_16x16x32_bf16 v[68:71], v[168:171], v[218:221], v[68:71]
	v_mfma_f32_16x16x32_bf16 v[64:67], v[176:179], v[218:221], v[64:67]
	v_mfma_f32_16x16x32_bf16 v[116:119], v[172:175], v[198:201], v[116:119]
	v_mfma_f32_16x16x32_bf16 v[108:111], v[180:183], v[198:201], v[108:111]
	v_mfma_f32_16x16x32_bf16 v[100:103], v[172:175], v[206:209], v[98:101]
	v_mfma_f32_16x16x32_bf16 v[88:91], v[180:183], v[206:209], v[88:91]
	v_mfma_f32_16x16x32_bf16 v[80:83], v[172:175], v[214:217], v[80:83]
	v_mfma_f32_16x16x32_bf16 v[72:75], v[180:183], v[214:217], v[72:75]
	v_mfma_f32_16x16x32_bf16 v[68:71], v[172:175], v[222:225], v[68:71]
	v_mfma_f32_16x16x32_bf16 v[64:67], v[180:183], v[222:225], v[64:67]
	s_setprio 0
	s_barrier
	s_add_i32 s8, s8, s40
	s_mov_b32 m0, s8
	ds_read_b128 v[194:197], v150 offset:49152
	ds_read_b128 v[198:201], v150 offset:50176
	ds_read_b128 v[202:205], v150 offset:51200
	ds_read_b128 v[206:209], v150 offset:52224
	ds_read_b128 v[210:213], v150 offset:53248
	ds_read_b128 v[214:217], v150 offset:54272
	ds_read_b128 v[218:221], v150 offset:55296
	ds_read_b128 v[222:225], v150 offset:56320
	global_load_lds_dwordx4 v230, s[78:79]
	s_add_i32 m0, s8, 0x2000
	s_add_i32 s8, s25, s40
	global_load_lds_dwordx4 v231, s[78:79]
	s_mov_b32 m0, s8
	s_nop 0
	global_load_lds_dwordx4 v232, s[78:79]
	s_add_i32 m0, s8, 0x2000
	s_nop 0
	global_load_lds_dwordx4 v233, s[78:79]
	s_mov_b32 m0, s85
	s_nop 0
	global_load_lds_dwordx4 v188, s[18:19]
	s_mov_b32 m0, s86
	s_nop 0
	global_load_lds_dwordx4 v189, s[18:19]
	s_waitcnt vmcnt(8)
	s_waitcnt lgkmcnt(0)
	s_barrier
	s_setprio 1
	s_waitcnt lgkmcnt(0)
	v_mfma_f32_16x16x32_bf16 v[60:63], v[132:135], v[194:197], v[60:63]
	v_mfma_f32_16x16x32_bf16 v[56:59], v[160:163], v[194:197], v[56:59]
	v_mfma_f32_16x16x32_bf16 v[52:55], v[132:135], v[202:205], v[52:55]
	v_mfma_f32_16x16x32_bf16 v[48:51], v[160:163], v[202:205], v[48:51]
	v_mfma_f32_16x16x32_bf16 v[36:39], v[132:135], v[210:213], v[36:39]
	v_mfma_f32_16x16x32_bf16 v[32:35], v[160:163], v[210:213], v[32:35]
	v_mfma_f32_16x16x32_bf16 v[20:23], v[132:135], v[218:221], v[20:23]
	v_mfma_f32_16x16x32_bf16 v[16:19], v[160:163], v[218:221], v[16:19]
	v_mfma_f32_16x16x32_bf16 v[60:63], v[136:139], v[198:201], v[60:63]
	v_mfma_f32_16x16x32_bf16 v[56:59], v[164:167], v[198:201], v[56:59]
	v_mfma_f32_16x16x32_bf16 v[52:55], v[136:139], v[206:209], v[52:55]
	v_mfma_f32_16x16x32_bf16 v[48:51], v[164:167], v[206:209], v[48:51]
	v_mfma_f32_16x16x32_bf16 v[36:39], v[136:139], v[214:217], v[36:39]
	v_mfma_f32_16x16x32_bf16 v[32:35], v[164:167], v[214:217], v[32:35]
	v_mfma_f32_16x16x32_bf16 v[20:23], v[136:139], v[222:225], v[20:23]
	v_mfma_f32_16x16x32_bf16 v[16:19], v[164:167], v[222:225], v[16:19]
	v_mfma_f32_16x16x32_bf16 v[44:47], v[168:171], v[194:197], v[44:47]
	v_mfma_f32_16x16x32_bf16 v[40:43], v[176:179], v[194:197], v[40:43]
	v_mfma_f32_16x16x32_bf16 v[28:31], v[168:171], v[202:205], v[28:31]
	v_mfma_f32_16x16x32_bf16 v[24:27], v[176:179], v[202:205], v[24:27]
	v_mfma_f32_16x16x32_bf16 v[12:15], v[168:171], v[210:213], v[12:15]
	v_mfma_f32_16x16x32_bf16 v[8:11], v[176:179], v[210:213], v[8:11]
	v_mfma_f32_16x16x32_bf16 v[4:7], v[168:171], v[218:221], v[4:7]
	v_mfma_f32_16x16x32_bf16 v[0:3], v[176:179], v[218:221], v[0:3]
	v_mfma_f32_16x16x32_bf16 v[44:47], v[172:175], v[198:201], v[44:47]
	v_mfma_f32_16x16x32_bf16 v[40:43], v[180:183], v[198:201], v[40:43]
	v_mfma_f32_16x16x32_bf16 v[28:31], v[172:175], v[206:209], v[28:31]
	v_mfma_f32_16x16x32_bf16 v[24:27], v[180:183], v[206:209], v[24:27]
	v_mfma_f32_16x16x32_bf16 v[12:15], v[172:175], v[214:217], v[12:15]
	v_mfma_f32_16x16x32_bf16 v[8:11], v[180:183], v[214:217], v[8:11]
	v_mfma_f32_16x16x32_bf16 v[4:7], v[172:175], v[222:225], v[4:7]
	v_mfma_f32_16x16x32_bf16 v[0:3], v[180:183], v[222:225], v[0:3]
	s_setprio 0
	s_barrier
	s_add_u32 vcc_lo, vcc_lo, 0x100
	s_addc_u32 vcc_hi, vcc_hi, 0
	s_add_u32 s2, s2, 0x100
	s_addc_u32 s3, s3, 0
	s_cmp_ge_i32 s91, s87
	s_mov_b32 s18, s91
	s_cbranch_scc0 .LBB0_886
	v_readlane_b32 s78, v255, 54
	v_readlane_b32 s79, v255, 55
	s_and_b64 vcc, exec, s[12:13]
	s_cbranch_vccnz .LBB0_891
	s_branch .LBB0_892

; #define PG8_STAGE(bufoff, gbase, voff) do { _Pragma("unroll") for (int _i = 0; _i < 2; ++_i) \
;         __builtin_amdgcn_global_load_lds((const unsigned*)((const char*)(gbase) + (voff)[_i]), (PG8_LAS unsigned*)(lds + (bufoff) + ldsw + _i * 8192), 16, 0, 0); } while (0)
; #define PG8_LDA(dst, b, h) do { _Pragma("unroll") for (int m = 0; m < 4; ++m) _Pragma("unroll") for (int k = 0; k < 2; ++k) dst[m][k] = *(const PG8_LAS bf16x8*)(lds + PG8_SA(b, h) + aoff + m * 2048 + k * 1024); } while (0)
; #define PG8_LDB(dst, b, h) do { _Pragma("unroll") for (int n = 0; n < 2; ++n) _Pragma("unroll") for (int k = 0; k < 2; ++k) dst[n][k] = *(const PG8_LAS bf16x8*)(lds + PG8_SB(b, h) + boff + n * 2048 + k * 1024); } while (0)
; #define PG8_MMA(ai, bj, At, Bt) do { __builtin_amdgcn_s_setprio(1); _Pragma("unroll") for (int m = 0; m < 4; ++m) _Pragma("unroll") for (int n = 0; n < 2; ++n) _Pragma("unroll") for (int k = 0; k < 2; ++k) \
;         acc[ai][bj][m][n] = __builtin_amdgcn_mfma_f32_16x16x32_bf16(Bt[n][k], At[m][k], acc[ai][bj][m][n], 0, 0, 0); __builtin_amdgcn_s_setprio(0); } while (0)
; #define PG8_WAIT_V(n) asm volatile("s_waitcnt vmcnt(" #n ")" ::: "memory")
; #define PG8_WAIT_L(n) asm volatile("s_waitcnt lgkmcnt(" #n ")" ::: "memory")
; template <class Epi, class Sched, bool ALIGN_EPI = false, bool SP2 = false>
; __device__ __forceinline__ void gemm_phase(PG8_LAS unsigned char* lds, const Gemm g, const Sched& S, const Epi& E, int wid_s_) {
;     ...
;             const bool last = (t == nt - 2);
;             const char* a1 = cA + (size_t)(t + 1) * kstep;
;             const char* a2 = last ? nA : cA + (size_t)(t + 2) * kstep; const char* b2 = last ? nB : cB + (size_t)(t + 2) * kstep;
;             const char* a3 = a2 + kstep; const char* b3 = b2 + kstep;
;             if (last && has_next) S.a_ready(nxt);
;             if constexpr (SP2) {
;             PG8_LDB(B0, 0, 0); PG8_LDB(B1, 0, 1); PG8_SCHED; PG8_LDA(At, 0, 0); PG8_STAGE(PG8_SA(1, 1), a1 + hstep, voffA);
;             PG8_WAIT_V(8); PG8_WAIT_L(0); PG8_BAR; PG8_MMA(0, 0, At, B0); PG8_MMA(0, 1, At, B1); PG8_BAR; PG8_SCHED;
;             PG8_LDA(At, 0, 1); PG8_STAGE(PG8_SB(0, 0), b2, voffB); PG8_STAGE(PG8_SB(0, 1), b2 + hstep, voffB); PG8_STAGE(PG8_SA(0, 0), a2, voffA);
;             PG8_WAIT_V(8); PG8_WAIT_L(0); PG8_BAR; PG8_MMA(1, 0, At, B0); PG8_MMA(1, 1, At, B1); PG8_BAR; PG8_SCHED;
.LBB0_1276:
	s_add_i32 s84, s22, 2
	s_add_u32 s78, s20, 0x80
	s_addc_u32 s23, s21, 0
	s_add_i32 s85, 16, 0x10000
	s_cmp_eq_u32 s86, s22
	s_cselect_b32 s23, s17, s23
	s_cselect_b32 s22, s16, s78
	v_add_u32_e32 v150, s85, v147
	s_cselect_b32 s79, s19, vcc_hi
	s_cselect_b32 s78, s18, vcc_lo
	s_add_i32 s8, 16, 0x14000
	ds_read_b128 v[130:133], v150
	ds_read_b128 v[134:137], v150 offset:1024
	ds_read_b128 v[154:157], v150 offset:2048
	ds_read_b128 v[158:161], v150 offset:3072
	v_add_u32_e32 v150, s8, v147
	ds_read_b128 v[162:165], v150
	ds_read_b128 v[166:169], v150 offset:1024
	ds_read_b128 v[170:173], v150 offset:2048
	ds_read_b128 v[174:177], v150 offset:3072
	s_add_i32 m0, s40, 0xc000
	ds_read_b128 v[180:183], v149
	ds_read_b128 v[196:199], v149 offset:1024
	ds_read_b128 v[200:203], v149 offset:2048
	ds_read_b128 v[204:207], v149 offset:3072
	ds_read_b128 v[208:211], v149 offset:4096
	ds_read_b128 v[212:215], v149 offset:5120
	ds_read_b128 v[216:219], v149 offset:6144
	ds_read_b128 v[220:223], v149 offset:7168
	global_load_lds_dwordx4 v152, s[20:21]
	s_add_i32 m0, s40, 0xe000
	s_nop 0
	global_load_lds_dwordx4 v144, s[20:21]
	s_waitcnt vmcnt(8)
	s_waitcnt lgkmcnt(0)
	s_barrier
	s_setprio 1
	s_waitcnt lgkmcnt(0)
	v_mfma_f32_16x16x32_bf16 v[122:125], v[130:133], v[180:183], v[122:125]
	v_mfma_f32_16x16x32_bf16 v[126:129], v[154:157], v[180:183], v[126:129]
	v_mfma_f32_16x16x32_bf16 v[118:121], v[130:133], v[200:203], v[118:121]
	v_mfma_f32_16x16x32_bf16 v[114:117], v[154:157], v[200:203], v[114:117]
	v_mfma_f32_16x16x32_bf16 v[110:113], v[130:133], v[208:211], v[110:113]
	v_mfma_f32_16x16x32_bf16 v[106:109], v[154:157], v[208:211], v[106:109]
	v_mfma_f32_16x16x32_bf16 v[102:105], v[130:133], v[216:219], v[102:105]
	v_mfma_f32_16x16x32_bf16 v[98:101], v[154:157], v[216:219], v[98:101]
	v_mfma_f32_16x16x32_bf16 v[122:125], v[134:137], v[196:199], v[122:125]
	v_mfma_f32_16x16x32_bf16 v[126:129], v[158:161], v[196:199], v[126:129]
	v_mfma_f32_16x16x32_bf16 v[118:121], v[134:137], v[204:207], v[118:121]
	v_mfma_f32_16x16x32_bf16 v[114:117], v[158:161], v[204:207], v[114:117]
	v_mfma_f32_16x16x32_bf16 v[110:113], v[134:137], v[212:215], v[110:113]
	v_mfma_f32_16x16x32_bf16 v[106:109], v[158:161], v[212:215], v[106:109]
	v_mfma_f32_16x16x32_bf16 v[102:105], v[134:137], v[220:223], v[102:105]
	v_mfma_f32_16x16x32_bf16 v[98:101], v[158:161], v[220:223], v[98:101]
	v_mfma_f32_16x16x32_bf16 v[60:63], v[162:165], v[180:183], v[60:63]
	v_mfma_f32_16x16x32_bf16 v[56:59], v[170:173], v[180:183], v[56:59]
	v_mfma_f32_16x16x32_bf16 v[52:55], v[162:165], v[200:203], v[52:55]
	v_mfma_f32_16x16x32_bf16 v[48:51], v[170:173], v[200:203], v[48:51]
	v_mfma_f32_16x16x32_bf16 v[44:47], v[162:165], v[208:211], v[44:47]
	v_mfma_f32_16x16x32_bf16 v[40:43], v[170:173], v[208:211], v[40:43]
	v_mfma_f32_16x16x32_bf16 v[36:39], v[162:165], v[216:219], v[36:39]
	v_mfma_f32_16x16x32_bf16 v[32:35], v[170:173], v[216:219], v[32:35]
	v_mfma_f32_16x16x32_bf16 v[60:63], v[166:169], v[196:199], v[60:63]
	v_mfma_f32_16x16x32_bf16 v[56:59], v[174:177], v[196:199], v[56:59]
	v_mfma_f32_16x16x32_bf16 v[52:55], v[166:169], v[204:207], v[52:55]
	v_mfma_f32_16x16x32_bf16 v[48:51], v[174:177], v[204:207], v[48:51]
	v_mfma_f32_16x16x32_bf16 v[44:47], v[166:169], v[212:215], v[44:47]
	v_mfma_f32_16x16x32_bf16 v[40:43], v[174:177], v[212:215], v[40:43]
	v_mfma_f32_16x16x32_bf16 v[36:39], v[166:169], v[220:223], v[36:39]
	v_mfma_f32_16x16x32_bf16 v[32:35], v[174:177], v[220:223], v[32:35]
	s_setprio 0
	s_barrier
	s_add_i32 s9, s85, s37
	s_mov_b32 m0, s9
	ds_read_b128 v[180:183], v149 offset:16384
	ds_read_b128 v[196:199], v149 offset:17408
	ds_read_b128 v[200:203], v149 offset:18432
	ds_read_b128 v[204:207], v149 offset:19456
	ds_read_b128 v[208:211], v149 offset:20480
	ds_read_b128 v[212:215], v149 offset:21504
	ds_read_b128 v[216:219], v149 offset:22528
	ds_read_b128 v[220:223], v149 offset:23552
	global_load_lds_dwordx4 v96, s[78:79]
	s_add_i32 m0, s9, 0x2000
	s_add_i32 s8, s8, s37
	global_load_lds_dwordx4 v138, s[78:79]
	s_mov_b32 m0, s8
	s_nop 0
	global_load_lds_dwordx4 v151, s[78:79]
	s_add_i32 m0, s8, 0x2000
	s_nop 0
	global_load_lds_dwordx4 v178, s[78:79]
	s_mov_b32 m0, s40
	s_nop 0
	global_load_lds_dwordx4 v142, s[22:23]
	s_mov_b32 m0, s41
	s_nop 0
	global_load_lds_dwordx4 v140, s[22:23]
	s_waitcnt vmcnt(8)
	s_waitcnt lgkmcnt(0)
	s_barrier
	s_setprio 1
	s_waitcnt lgkmcnt(0)
	v_mfma_f32_16x16x32_bf16 v[92:95], v[130:133], v[180:183], v[92:95]
	v_mfma_f32_16x16x32_bf16 v[88:91], v[154:157], v[180:183], v[88:91]
	v_mfma_f32_16x16x32_bf16 v[84:87], v[130:133], v[200:203], v[84:87]
	v_mfma_f32_16x16x32_bf16 v[80:83], v[154:157], v[200:203], v[80:83]
	v_mfma_f32_16x16x32_bf16 v[76:79], v[130:133], v[208:211], v[76:79]
	v_mfma_f32_16x16x32_bf16 v[72:75], v[154:157], v[208:211], v[72:75]
	v_mfma_f32_16x16x32_bf16 v[68:71], v[130:133], v[216:219], v[68:71]
	v_mfma_f32_16x16x32_bf16 v[64:67], v[154:157], v[216:219], v[64:67]
	v_mfma_f32_16x16x32_bf16 v[92:95], v[134:137], v[196:199], v[92:95]
	v_mfma_f32_16x16x32_bf16 v[88:91], v[158:161], v[196:199], v[88:91]
	v_mfma_f32_16x16x32_bf16 v[84:87], v[134:137], v[204:207], v[84:87]
	v_mfma_f32_16x16x32_bf16 v[80:83], v[158:161], v[204:207], v[80:83]
	v_mfma_f32_16x16x32_bf16 v[76:79], v[134:137], v[212:215], v[76:79]
	v_mfma_f32_16x16x32_bf16 v[72:75], v[158:161], v[212:215], v[72:75]
	v_mfma_f32_16x16x32_bf16 v[68:71], v[134:137], v[220:223], v[68:71]
	v_mfma_f32_16x16x32_bf16 v[64:67], v[158:161], v[220:223], v[64:67]
	v_mfma_f32_16x16x32_bf16 v[28:31], v[162:165], v[180:183], v[28:31]
	v_mfma_f32_16x16x32_bf16 v[24:27], v[170:173], v[180:183], v[24:27]
	v_mfma_f32_16x16x32_bf16 v[20:23], v[162:165], v[200:203], v[20:23]
	v_mfma_f32_16x16x32_bf16 v[16:19], v[170:173], v[200:203], v[16:19]
	v_mfma_f32_16x16x32_bf16 v[12:15], v[162:165], v[208:211], v[12:15]
	v_mfma_f32_16x16x32_bf16 v[8:11], v[170:173], v[208:211], v[8:11]
	v_mfma_f32_16x16x32_bf16 v[4:7], v[162:165], v[216:219], v[4:7]
	v_mfma_f32_16x16x32_bf16 v[0:3], v[170:173], v[216:219], v[0:3]
	v_mfma_f32_16x16x32_bf16 v[28:31], v[166:169], v[196:199], v[28:31]
	v_mfma_f32_16x16x32_bf16 v[24:27], v[174:177], v[196:199], v[24:27]
	v_mfma_f32_16x16x32_bf16 v[20:23], v[166:169], v[204:207], v[20:23]
	v_mfma_f32_16x16x32_bf16 v[16:19], v[174:177], v[204:207], v[16:19]
	v_mfma_f32_16x16x32_bf16 v[12:15], v[166:169], v[212:215], v[12:15]
	v_mfma_f32_16x16x32_bf16 v[8:11], v[174:177], v[212:215], v[8:11]
	v_mfma_f32_16x16x32_bf16 v[4:7], v[166:169], v[220:223], v[4:7]
	v_mfma_f32_16x16x32_bf16 v[0:3], v[174:177], v[220:223], v[0:3]
	s_setprio 0
	s_barrier
; #define PG8_STAGE(bufoff, gbase, voff) do { _Pragma("unroll") for (int _i = 0; _i < 2; ++_i) \
;         __builtin_amdgcn_global_load_lds((const unsigned*)((const char*)(gbase) + (voff)[_i]), (PG8_LAS unsigned*)(lds + (bufoff) + ldsw + _i * 8192), 16, 0, 0); } while (0)
; #define PG8_LDA(dst, b, h) do { _Pragma("unroll") for (int m = 0; m < 4; ++m) _Pragma("unroll") for (int k = 0; k < 2; ++k) dst[m][k] = *(const PG8_LAS bf16x8*)(lds + PG8_SA(b, h) + aoff + m * 2048 + k * 1024); } while (0)
; #define PG8_LDB(dst, b, h) do { _Pragma("unroll") for (int n = 0; n < 2; ++n) _Pragma("unroll") for (int k = 0; k < 2; ++k) dst[n][k] = *(const PG8_LAS bf16x8*)(lds + PG8_SB(b, h) + boff + n * 2048 + k * 1024); } while (0)
; #define PG8_MMA(ai, bj, At, Bt) do { __builtin_amdgcn_s_setprio(1); _Pragma("unroll") for (int m = 0; m < 4; ++m) _Pragma("unroll") for (int n = 0; n < 2; ++n) _Pragma("unroll") for (int k = 0; k < 2; ++k) \
;         acc[ai][bj][m][n] = __builtin_amdgcn_mfma_f32_16x16x32_bf16(Bt[n][k], At[m][k], acc[ai][bj][m][n], 0, 0, 0); __builtin_amdgcn_s_setprio(0); } while (0)
; #define PG8_WAIT_V(n) asm volatile("s_waitcnt vmcnt(" #n ")" ::: "memory")
; #define PG8_WAIT_L(n) asm volatile("s_waitcnt lgkmcnt(" #n ")" ::: "memory")
; #define PG8_BAR __builtin_amdgcn_s_barrier()
; #define PG8_SCHED __builtin_amdgcn_sched_barrier(0)
; template <class Epi, class Sched, bool ALIGN_EPI = false, bool SP2 = false>
; __device__ __forceinline__ void gemm_phase(PG8_LAS unsigned char* lds, const Gemm g, const Sched& S, const Epi& E, int wid_s_) {
;     ...
;             PG8_LDB(B0, 1, 0); PG8_LDB(B1, 1, 1); PG8_SCHED; PG8_LDA(At, 1, 0); PG8_STAGE(PG8_SA(0, 1), a2 + hstep, voffA);
;             PG8_WAIT_V(8); PG8_WAIT_L(0); PG8_BAR; PG8_MMA(0, 0, At, B0); PG8_MMA(0, 1, At, B1); PG8_BAR; PG8_SCHED;
;             PG8_LDA(At, 1, 1); PG8_STAGE(PG8_SB(1, 0), b3, voffB); PG8_STAGE(PG8_SB(1, 1), b3 + hstep, voffB); PG8_STAGE(PG8_SA(1, 0), a3, voffA);
;             PG8_WAIT_V(8); PG8_WAIT_L(0); PG8_BAR; PG8_MMA(1, 0, At, B0); PG8_MMA(1, 1, At, B1); PG8_BAR; PG8_SCHED;
	s_add_i32 s8, 16, 0x18000
	s_add_i32 s9, 16, 0x1c000
	v_add_u32_e32 v158, s8, v147
	v_add_u32_e32 v174, s9, v147
	ds_read_b128 v[130:133], v158
	ds_read_b128 v[134:137], v158 offset:1024
	ds_read_b128 v[154:157], v158 offset:2048
	ds_read_b128 v[158:161], v158 offset:3072
	ds_read_b128 v[162:165], v174
	ds_read_b128 v[166:169], v174 offset:1024
	ds_read_b128 v[170:173], v174 offset:2048
	ds_read_b128 v[174:177], v174 offset:3072
	s_mov_b32 m0, s48
	ds_read_b128 v[180:183], v149 offset:32768
	ds_read_b128 v[196:199], v149 offset:33792
	ds_read_b128 v[200:203], v149 offset:34816
	ds_read_b128 v[204:207], v149 offset:35840
	ds_read_b128 v[208:211], v149 offset:36864
	ds_read_b128 v[212:215], v149 offset:37888
	ds_read_b128 v[216:219], v149 offset:38912
	ds_read_b128 v[220:223], v149 offset:39936
	global_load_lds_dwordx4 v179, s[22:23]
	s_mov_b32 m0, s49
	s_nop 0
	global_load_lds_dwordx4 v188, s[22:23]
	s_waitcnt vmcnt(8)
	s_waitcnt lgkmcnt(0)
	s_barrier
	s_setprio 1
	s_waitcnt lgkmcnt(0)
	v_mfma_f32_16x16x32_bf16 v[122:125], v[130:133], v[180:183], v[122:125]
	v_mfma_f32_16x16x32_bf16 v[126:129], v[154:157], v[180:183], v[126:129]
	v_mfma_f32_16x16x32_bf16 v[118:121], v[130:133], v[200:203], v[118:121]
	v_mfma_f32_16x16x32_bf16 v[114:117], v[154:157], v[200:203], v[114:117]
	v_mfma_f32_16x16x32_bf16 v[110:113], v[130:133], v[208:211], v[110:113]
	v_mfma_f32_16x16x32_bf16 v[106:109], v[154:157], v[208:211], v[106:109]
	v_mfma_f32_16x16x32_bf16 v[102:105], v[130:133], v[216:219], v[102:105]
	v_mfma_f32_16x16x32_bf16 v[98:101], v[154:157], v[216:219], v[98:101]
	v_mfma_f32_16x16x32_bf16 v[122:125], v[134:137], v[196:199], v[122:125]
	v_mfma_f32_16x16x32_bf16 v[126:129], v[158:161], v[196:199], v[126:129]
	v_mfma_f32_16x16x32_bf16 v[118:121], v[134:137], v[204:207], v[118:121]
	v_mfma_f32_16x16x32_bf16 v[114:117], v[158:161], v[204:207], v[114:117]
	v_mfma_f32_16x16x32_bf16 v[110:113], v[134:137], v[212:215], v[110:113]
	v_mfma_f32_16x16x32_bf16 v[106:109], v[158:161], v[212:215], v[106:109]
	v_mfma_f32_16x16x32_bf16 v[102:105], v[134:137], v[220:223], v[102:105]
	v_mfma_f32_16x16x32_bf16 v[98:101], v[158:161], v[220:223], v[98:101]
	v_mfma_f32_16x16x32_bf16 v[60:63], v[162:165], v[180:183], v[60:63]
	v_mfma_f32_16x16x32_bf16 v[56:59], v[170:173], v[180:183], v[56:59]
	v_mfma_f32_16x16x32_bf16 v[52:55], v[162:165], v[200:203], v[52:55]
	v_mfma_f32_16x16x32_bf16 v[48:51], v[170:173], v[200:203], v[48:51]
	v_mfma_f32_16x16x32_bf16 v[44:47], v[162:165], v[208:211], v[44:47]
	v_mfma_f32_16x16x32_bf16 v[40:43], v[170:173], v[208:211], v[40:43]
	v_mfma_f32_16x16x32_bf16 v[36:39], v[162:165], v[216:219], v[36:39]
	v_mfma_f32_16x16x32_bf16 v[32:35], v[170:173], v[216:219], v[32:35]
	v_mfma_f32_16x16x32_bf16 v[60:63], v[166:169], v[196:199], v[60:63]
	v_mfma_f32_16x16x32_bf16 v[56:59], v[174:177], v[196:199], v[56:59]
	v_mfma_f32_16x16x32_bf16 v[52:55], v[166:169], v[204:207], v[52:55]
	v_mfma_f32_16x16x32_bf16 v[48:51], v[174:177], v[204:207], v[48:51]
	v_mfma_f32_16x16x32_bf16 v[44:47], v[166:169], v[212:215], v[44:47]
	v_mfma_f32_16x16x32_bf16 v[40:43], v[174:177], v[212:215], v[40:43]
	v_mfma_f32_16x16x32_bf16 v[36:39], v[166:169], v[220:223], v[36:39]
	v_mfma_f32_16x16x32_bf16 v[32:35], v[174:177], v[220:223], v[32:35]
	s_setprio 0
	s_barrier
	s_add_i32 s8, s8, s37
	s_mov_b32 m0, s8
	ds_read_b128 v[180:183], v149 offset:49152
	ds_read_b128 v[196:199], v149 offset:50176
	ds_read_b128 v[200:203], v149 offset:51200
	ds_read_b128 v[204:207], v149 offset:52224
	ds_read_b128 v[208:211], v149 offset:53248
	ds_read_b128 v[212:215], v149 offset:54272
	ds_read_b128 v[216:219], v149 offset:55296
	ds_read_b128 v[220:223], v149 offset:56320
	global_load_lds_dwordx4 v189, s[78:79]
	s_add_i32 m0, s8, 0x2000
	s_add_i32 s8, s9, s37
	global_load_lds_dwordx4 v194, s[78:79]
	s_mov_b32 m0, s8
	s_nop 0
	global_load_lds_dwordx4 v195, s[78:79]
	s_add_i32 m0, s8, 0x2000
	s_nop 0
	global_load_lds_dwordx4 v224, s[78:79]
	s_mov_b32 m0, s26
	s_nop 0
	global_load_lds_dwordx4 v225, s[22:23]
	s_mov_b32 m0, s50
	s_nop 0
	global_load_lds_dwordx4 v226, s[22:23]
	s_waitcnt vmcnt(8)
	s_waitcnt lgkmcnt(0)
	s_barrier
	s_setprio 1
	s_waitcnt lgkmcnt(0)
	v_mfma_f32_16x16x32_bf16 v[92:95], v[130:133], v[180:183], v[92:95]
	v_mfma_f32_16x16x32_bf16 v[88:91], v[154:157], v[180:183], v[88:91]
	v_mfma_f32_16x16x32_bf16 v[84:87], v[130:133], v[200:203], v[84:87]
	v_mfma_f32_16x16x32_bf16 v[80:83], v[154:157], v[200:203], v[80:83]
	v_mfma_f32_16x16x32_bf16 v[76:79], v[130:133], v[208:211], v[76:79]
	v_mfma_f32_16x16x32_bf16 v[72:75], v[154:157], v[208:211], v[72:75]
	v_mfma_f32_16x16x32_bf16 v[68:71], v[130:133], v[216:219], v[68:71]
	v_mfma_f32_16x16x32_bf16 v[64:67], v[154:157], v[216:219], v[64:67]
	v_mfma_f32_16x16x32_bf16 v[92:95], v[134:137], v[196:199], v[92:95]
	v_mfma_f32_16x16x32_bf16 v[88:91], v[158:161], v[196:199], v[88:91]
	v_mfma_f32_16x16x32_bf16 v[84:87], v[134:137], v[204:207], v[84:87]
	v_mfma_f32_16x16x32_bf16 v[80:83], v[158:161], v[204:207], v[80:83]
	v_mfma_f32_16x16x32_bf16 v[76:79], v[134:137], v[212:215], v[76:79]
	v_mfma_f32_16x16x32_bf16 v[72:75], v[158:161], v[212:215], v[72:75]
	v_mfma_f32_16x16x32_bf16 v[68:71], v[134:137], v[220:223], v[68:71]
	v_mfma_f32_16x16x32_bf16 v[64:67], v[158:161], v[220:223], v[64:67]
	v_mfma_f32_16x16x32_bf16 v[28:31], v[162:165], v[180:183], v[28:31]
	v_mfma_f32_16x16x32_bf16 v[24:27], v[170:173], v[180:183], v[24:27]
	v_mfma_f32_16x16x32_bf16 v[20:23], v[162:165], v[200:203], v[20:23]
	v_mfma_f32_16x16x32_bf16 v[16:19], v[170:173], v[200:203], v[16:19]
	v_mfma_f32_16x16x32_bf16 v[12:15], v[162:165], v[208:211], v[12:15]
	v_mfma_f32_16x16x32_bf16 v[8:11], v[170:173], v[208:211], v[8:11]
	v_mfma_f32_16x16x32_bf16 v[4:7], v[162:165], v[216:219], v[4:7]
	v_mfma_f32_16x16x32_bf16 v[0:3], v[170:173], v[216:219], v[0:3]
	v_mfma_f32_16x16x32_bf16 v[28:31], v[166:169], v[196:199], v[28:31]
	v_mfma_f32_16x16x32_bf16 v[24:27], v[174:177], v[196:199], v[24:27]
	v_mfma_f32_16x16x32_bf16 v[20:23], v[166:169], v[204:207], v[20:23]
	v_mfma_f32_16x16x32_bf16 v[16:19], v[174:177], v[204:207], v[16:19]
	v_mfma_f32_16x16x32_bf16 v[12:15], v[166:169], v[212:215], v[12:15]
	v_mfma_f32_16x16x32_bf16 v[8:11], v[174:177], v[212:215], v[8:11]
	v_mfma_f32_16x16x32_bf16 v[4:7], v[166:169], v[220:223], v[4:7]
	v_mfma_f32_16x16x32_bf16 v[0:3], v[174:177], v[220:223], v[0:3]
	s_setprio 0
	s_barrier
	s_add_u32 vcc_lo, vcc_lo, 0x100
	s_addc_u32 vcc_hi, vcc_hi, 0
	s_add_u32 s20, s20, 0x100
	s_addc_u32 s21, s21, 0
	s_cmp_ge_i32 s84, s51
	s_mov_b32 s22, s84
	s_cbranch_scc0 .LBB0_1276
	v_readlane_b32 s78, v255, 54
	v_readlane_b32 s79, v255, 55

; __device__ __forceinline__ void tile_body(bool DIAG, const LAS unsigned char* kb, const LAS unsigned char* vb, int krow, int jm, int hh, int rr, float d00, float m2, float sm2, float M0,
;                                           const bf16x8 (&qf)[4], f32x16 (&O)[4], float& ls) {
;     ...
;     if (!DIAG) { const float base0 = -M0 - sm2 * d00, base1 = base0 + sm2 * 32.0f;
; #pragma unroll
;         for (int r = 0; r < 16; ++r) { const float cr = (float)(16 * (r >> 3) + (r & 7)); s0[r] = fmaf(sm2, cr, base0); s1[r] = fmaf(sm2, cr, base1); }
; __device__ __forceinline__ void attn_phase(LAS unsigned char* lds, const bf16_t* Z, const bf16_t* VT, bf16_t* Y, const float* subln, float lam, float lam_init, float M0, unsigned* ctr, LAS int* s_unit, int wid_s_) {
;     ...
;                     const bool left = (k0 + 63 <= qw), right = (k0 >= qw + 31);
;                     tile_body(!(left || right), kb, vb, krow, jm, hh, rr, d00, m2, right ? -m2 : m2, M0, qf, O, ls);
.Llin0:
	v_cndmask_b32_e64 v78, -v171, v171, s[16:17]
	v_fma_f32 v80, -v78, v184, -v201
	v_fmamk_f32 v64, v78, 0x42000000, v80
	v_add_f32_e32 v81, v78, v80
	v_add_f32_e32 v65, v78, v64
	v_fma_f32 v82, v78, s80, v80
	v_fma_f32 v83, v78, s81, v80
	v_fma_f32 v66, v78, s80, v64
	v_fma_f32 v67, v78, s81, v64
	v_fma_f32 v84, v78, s66, v80
	v_fma_f32 v85, v78, s67, v80
	v_fma_f32 v68, v78, s66, v64
	v_fma_f32 v69, v78, s67, v64
	v_fma_f32 v86, v78, s74, v80
	v_fma_f32 v87, v78, s75, v80
	v_fma_f32 v70, v78, s74, v64
	v_fma_f32 v71, v78, s75, v64
	v_fma_f32 v88, v78, s34, v80
	v_fma_f32 v89, v78, s35, v80
	v_fma_f32 v72, v78, s34, v64
	v_fma_f32 v73, v78, s35, v64
	v_fma_f32 v90, v78, s96, v80
	v_fma_f32 v91, v78, s97, v80
	v_fma_f32 v74, v78, s96, v64
	v_fma_f32 v75, v78, s97, v64
	v_fma_f32 v92, v78, s52, v80
	v_fma_f32 v93, v78, s53, v80
	v_fma_f32 v76, v78, s52, v64
	v_fma_f32 v77, v78, s53, v64
	v_fma_f32 v95, v78, s55, v80
	v_fma_f32 v94, v78, s54, v80
	v_fma_f32 v79, v78, s55, v64
	v_fma_f32 v78, v78, s54, v64
	s_branch .LBB0_1308

; #define PG8_STAGE(bufoff, gbase, voff) do { _Pragma("unroll") for (int _i = 0; _i < 2; ++_i) \
;         __builtin_amdgcn_global_load_lds((const unsigned*)((const char*)(gbase) + (voff)[_i]), (PG8_LAS unsigned*)(lds + (bufoff) + ldsw + _i * 8192), 16, 0, 0); } while (0)
; #define PG8_LDA(dst, b, h) do { _Pragma("unroll") for (int m = 0; m < 4; ++m) _Pragma("unroll") for (int k = 0; k < 2; ++k) dst[m][k] = *(const PG8_LAS bf16x8*)(lds + PG8_SA(b, h) + aoff + m * 2048 + k * 1024); } while (0)
; #define PG8_LDB(dst, b, h) do { _Pragma("unroll") for (int n = 0; n < 2; ++n) _Pragma("unroll") for (int k = 0; k < 2; ++k) dst[n][k] = *(const PG8_LAS bf16x8*)(lds + PG8_SB(b, h) + boff + n * 2048 + k * 1024); } while (0)
; #define PG8_MMA(ai, bj, At, Bt) do { __builtin_amdgcn_s_setprio(1); _Pragma("unroll") for (int m = 0; m < 4; ++m) _Pragma("unroll") for (int n = 0; n < 2; ++n) _Pragma("unroll") for (int k = 0; k < 2; ++k) \
;         acc[ai][bj][m][n] = __builtin_amdgcn_mfma_f32_16x16x32_bf16(Bt[n][k], At[m][k], acc[ai][bj][m][n], 0, 0, 0); __builtin_amdgcn_s_setprio(0); } while (0)
; #define PG8_WAIT_V(n) asm volatile("s_waitcnt vmcnt(" #n ")" ::: "memory")
; #define PG8_WAIT_L(n) asm volatile("s_waitcnt lgkmcnt(" #n ")" ::: "memory")
; template <class Epi, class Sched, bool ALIGN_EPI = false, bool SP2 = false>
; __device__ __forceinline__ void gemm_phase(PG8_LAS unsigned char* lds, const Gemm g, const Sched& S, const Epi& E, int wid_s_) {
;     ...
;             const bool last = (t == nt - 2);
;             const char* a1 = cA + (size_t)(t + 1) * kstep;
;             const char* a2 = last ? nA : cA + (size_t)(t + 2) * kstep; const char* b2 = last ? nB : cB + (size_t)(t + 2) * kstep;
;             const char* a3 = a2 + kstep; const char* b3 = b2 + kstep;
;             if (last && has_next) S.a_ready(nxt);
;             if constexpr (SP2) {
;             PG8_LDB(B0, 0, 0); PG8_LDB(B1, 0, 1); PG8_SCHED; PG8_LDA(At, 0, 0); PG8_STAGE(PG8_SA(1, 1), a1 + hstep, voffA);
;             PG8_WAIT_V(8); PG8_WAIT_L(0); PG8_BAR; PG8_MMA(0, 0, At, B0); PG8_MMA(0, 1, At, B1); PG8_BAR; PG8_SCHED;
;             PG8_LDA(At, 0, 1); PG8_STAGE(PG8_SB(0, 0), b2, voffB); PG8_STAGE(PG8_SB(0, 1), b2 + hstep, voffB); PG8_STAGE(PG8_SA(0, 0), a2, voffA);
;             PG8_WAIT_V(8); PG8_WAIT_L(0); PG8_BAR; PG8_MMA(1, 0, At, B0); PG8_MMA(1, 1, At, B1); PG8_BAR; PG8_SCHED;
.LBB0_1393:
	s_add_i32 vcc_lo, s22, 2
	s_add_u32 s78, s20, 0x80
	s_addc_u32 s23, s21, 0
	s_add_i32 vcc_hi, 16, 0x10000
	s_cmp_eq_u32 s83, s22
	s_cselect_b32 s23, s3, s23
	s_cselect_b32 s22, s2, s78
	v_add_u32_e32 v150, vcc_hi, v147
	s_cselect_b32 s79, s19, s91
	s_cselect_b32 s78, s18, s90
	s_add_i32 s10, 16, 0x14000
	ds_read_b128 v[130:133], v150
	ds_read_b128 v[134:137], v150 offset:1024
	ds_read_b128 v[154:157], v150 offset:2048
	ds_read_b128 v[158:161], v150 offset:3072
	v_add_u32_e32 v150, s10, v147
	ds_read_b128 v[162:165], v150
	ds_read_b128 v[166:169], v150 offset:1024
	ds_read_b128 v[170:173], v150 offset:2048
	ds_read_b128 v[174:177], v150 offset:3072
	s_add_i32 m0, s48, 0xc000
	ds_read_b128 v[180:183], v149
	ds_read_b128 v[196:199], v149 offset:1024
	ds_read_b128 v[200:203], v149 offset:2048
	ds_read_b128 v[204:207], v149 offset:3072
	ds_read_b128 v[208:211], v149 offset:4096
	ds_read_b128 v[212:215], v149 offset:5120
	ds_read_b128 v[216:219], v149 offset:6144
	ds_read_b128 v[220:223], v149 offset:7168
	global_load_lds_dwordx4 v152, s[20:21]
	s_add_i32 m0, s48, 0xe000
	s_nop 0
	global_load_lds_dwordx4 v144, s[20:21]
	s_waitcnt vmcnt(8)
	s_waitcnt lgkmcnt(0)
	s_barrier
	s_setprio 1
	s_waitcnt lgkmcnt(0)
	v_mfma_f32_16x16x32_bf16 v[126:129], v[130:133], v[180:183], v[126:129]
	v_mfma_f32_16x16x32_bf16 v[122:125], v[154:157], v[180:183], v[122:125]
	v_mfma_f32_16x16x32_bf16 v[118:121], v[130:133], v[200:203], v[118:121]
	v_mfma_f32_16x16x32_bf16 v[114:117], v[154:157], v[200:203], v[114:117]
	v_mfma_f32_16x16x32_bf16 v[110:113], v[130:133], v[208:211], v[110:113]
	v_mfma_f32_16x16x32_bf16 v[106:109], v[154:157], v[208:211], v[106:109]
	v_mfma_f32_16x16x32_bf16 v[102:105], v[130:133], v[216:219], v[102:105]
	v_mfma_f32_16x16x32_bf16 v[98:101], v[154:157], v[216:219], v[98:101]
	v_mfma_f32_16x16x32_bf16 v[126:129], v[134:137], v[196:199], v[126:129]
	v_mfma_f32_16x16x32_bf16 v[122:125], v[158:161], v[196:199], v[122:125]
	v_mfma_f32_16x16x32_bf16 v[118:121], v[134:137], v[204:207], v[118:121]
	v_mfma_f32_16x16x32_bf16 v[114:117], v[158:161], v[204:207], v[114:117]
	v_mfma_f32_16x16x32_bf16 v[110:113], v[134:137], v[212:215], v[110:113]
	v_mfma_f32_16x16x32_bf16 v[106:109], v[158:161], v[212:215], v[106:109]
	v_mfma_f32_16x16x32_bf16 v[102:105], v[134:137], v[220:223], v[102:105]
	v_mfma_f32_16x16x32_bf16 v[98:101], v[158:161], v[220:223], v[98:101]
	v_mfma_f32_16x16x32_bf16 v[60:63], v[162:165], v[180:183], v[60:63]
	v_mfma_f32_16x16x32_bf16 v[56:59], v[170:173], v[180:183], v[56:59]
	v_mfma_f32_16x16x32_bf16 v[52:55], v[162:165], v[200:203], v[52:55]
	v_mfma_f32_16x16x32_bf16 v[48:51], v[170:173], v[200:203], v[48:51]
	v_mfma_f32_16x16x32_bf16 v[44:47], v[162:165], v[208:211], v[44:47]
	v_mfma_f32_16x16x32_bf16 v[40:43], v[170:173], v[208:211], v[40:43]
	v_mfma_f32_16x16x32_bf16 v[36:39], v[162:165], v[216:219], v[36:39]
	v_mfma_f32_16x16x32_bf16 v[32:35], v[170:173], v[216:219], v[32:35]
	v_mfma_f32_16x16x32_bf16 v[60:63], v[166:169], v[196:199], v[60:63]
	v_mfma_f32_16x16x32_bf16 v[56:59], v[174:177], v[196:199], v[56:59]
	v_mfma_f32_16x16x32_bf16 v[52:55], v[166:169], v[204:207], v[52:55]
	v_mfma_f32_16x16x32_bf16 v[48:51], v[174:177], v[204:207], v[48:51]
	v_mfma_f32_16x16x32_bf16 v[44:47], v[166:169], v[212:215], v[44:47]
	v_mfma_f32_16x16x32_bf16 v[40:43], v[174:177], v[212:215], v[40:43]
	v_mfma_f32_16x16x32_bf16 v[36:39], v[166:169], v[220:223], v[36:39]
	v_mfma_f32_16x16x32_bf16 v[32:35], v[174:177], v[220:223], v[32:35]
	s_setprio 0
	s_barrier
	s_add_i32 s11, vcc_hi, s41
	s_mov_b32 m0, s11
	ds_read_b128 v[180:183], v149 offset:16384
	ds_read_b128 v[196:199], v149 offset:17408
	ds_read_b128 v[200:203], v149 offset:18432
	ds_read_b128 v[204:207], v149 offset:19456
	ds_read_b128 v[208:211], v149 offset:20480
	ds_read_b128 v[212:215], v149 offset:21504
	ds_read_b128 v[216:219], v149 offset:22528
	ds_read_b128 v[220:223], v149 offset:23552
	global_load_lds_dwordx4 v96, s[78:79]
	s_add_i32 m0, s11, 0x2000
	s_add_i32 s10, s10, s41
	global_load_lds_dwordx4 v142, s[78:79]
	s_mov_b32 m0, s10
	s_nop 0
	global_load_lds_dwordx4 v151, s[78:79]
	s_add_i32 m0, s10, 0x2000
	s_nop 0
	global_load_lds_dwordx4 v178, s[78:79]
	s_mov_b32 m0, s48
	s_nop 0
	global_load_lds_dwordx4 v138, s[22:23]
	s_mov_b32 m0, s49
	s_nop 0
	global_load_lds_dwordx4 v140, s[22:23]
	s_waitcnt vmcnt(8)
	s_waitcnt lgkmcnt(0)
	s_barrier
	s_setprio 1
	s_waitcnt lgkmcnt(0)
	v_mfma_f32_16x16x32_bf16 v[92:95], v[130:133], v[180:183], v[92:95]
	v_mfma_f32_16x16x32_bf16 v[88:91], v[154:157], v[180:183], v[88:91]
	v_mfma_f32_16x16x32_bf16 v[84:87], v[130:133], v[200:203], v[84:87]
	v_mfma_f32_16x16x32_bf16 v[80:83], v[154:157], v[200:203], v[80:83]
	v_mfma_f32_16x16x32_bf16 v[76:79], v[130:133], v[208:211], v[76:79]
	v_mfma_f32_16x16x32_bf16 v[72:75], v[154:157], v[208:211], v[72:75]
	v_mfma_f32_16x16x32_bf16 v[68:71], v[130:133], v[216:219], v[68:71]
	v_mfma_f32_16x16x32_bf16 v[64:67], v[154:157], v[216:219], v[64:67]
	v_mfma_f32_16x16x32_bf16 v[92:95], v[134:137], v[196:199], v[92:95]
	v_mfma_f32_16x16x32_bf16 v[88:91], v[158:161], v[196:199], v[88:91]
	v_mfma_f32_16x16x32_bf16 v[84:87], v[134:137], v[204:207], v[84:87]
	v_mfma_f32_16x16x32_bf16 v[80:83], v[158:161], v[204:207], v[80:83]
	v_mfma_f32_16x16x32_bf16 v[76:79], v[134:137], v[212:215], v[76:79]
	v_mfma_f32_16x16x32_bf16 v[72:75], v[158:161], v[212:215], v[72:75]
	v_mfma_f32_16x16x32_bf16 v[68:71], v[134:137], v[220:223], v[68:71]
	v_mfma_f32_16x16x32_bf16 v[64:67], v[158:161], v[220:223], v[64:67]
	v_mfma_f32_16x16x32_bf16 v[28:31], v[162:165], v[180:183], v[28:31]
	v_mfma_f32_16x16x32_bf16 v[24:27], v[170:173], v[180:183], v[24:27]
	v_mfma_f32_16x16x32_bf16 v[20:23], v[162:165], v[200:203], v[20:23]
	v_mfma_f32_16x16x32_bf16 v[16:19], v[170:173], v[200:203], v[16:19]
	v_mfma_f32_16x16x32_bf16 v[12:15], v[162:165], v[208:211], v[12:15]
	v_mfma_f32_16x16x32_bf16 v[8:11], v[170:173], v[208:211], v[8:11]
	v_mfma_f32_16x16x32_bf16 v[4:7], v[162:165], v[216:219], v[4:7]
	v_mfma_f32_16x16x32_bf16 v[0:3], v[170:173], v[216:219], v[0:3]
	v_mfma_f32_16x16x32_bf16 v[28:31], v[166:169], v[196:199], v[28:31]
	v_mfma_f32_16x16x32_bf16 v[24:27], v[174:177], v[196:199], v[24:27]
	v_mfma_f32_16x16x32_bf16 v[20:23], v[166:169], v[204:207], v[20:23]
	v_mfma_f32_16x16x32_bf16 v[16:19], v[174:177], v[204:207], v[16:19]
	v_mfma_f32_16x16x32_bf16 v[12:15], v[166:169], v[212:215], v[12:15]
	v_mfma_f32_16x16x32_bf16 v[8:11], v[174:177], v[212:215], v[8:11]
	v_mfma_f32_16x16x32_bf16 v[4:7], v[166:169], v[220:223], v[4:7]
	v_mfma_f32_16x16x32_bf16 v[0:3], v[174:177], v[220:223], v[0:3]
	s_setprio 0
	s_barrier
; #define PG8_STAGE(bufoff, gbase, voff) do { _Pragma("unroll") for (int _i = 0; _i < 2; ++_i) \
;         __builtin_amdgcn_global_load_lds((const unsigned*)((const char*)(gbase) + (voff)[_i]), (PG8_LAS unsigned*)(lds + (bufoff) + ldsw + _i * 8192), 16, 0, 0); } while (0)
; #define PG8_LDA(dst, b, h) do { _Pragma("unroll") for (int m = 0; m < 4; ++m) _Pragma("unroll") for (int k = 0; k < 2; ++k) dst[m][k] = *(const PG8_LAS bf16x8*)(lds + PG8_SA(b, h) + aoff + m * 2048 + k * 1024); } while (0)
; #define PG8_LDB(dst, b, h) do { _Pragma("unroll") for (int n = 0; n < 2; ++n) _Pragma("unroll") for (int k = 0; k < 2; ++k) dst[n][k] = *(const PG8_LAS bf16x8*)(lds + PG8_SB(b, h) + boff + n * 2048 + k * 1024); } while (0)
; #define PG8_MMA(ai, bj, At, Bt) do { __builtin_amdgcn_s_setprio(1); _Pragma("unroll") for (int m = 0; m < 4; ++m) _Pragma("unroll") for (int n = 0; n < 2; ++n) _Pragma("unroll") for (int k = 0; k < 2; ++k) \
;         acc[ai][bj][m][n] = __builtin_amdgcn_mfma_f32_16x16x32_bf16(Bt[n][k], At[m][k], acc[ai][bj][m][n], 0, 0, 0); __builtin_amdgcn_s_setprio(0); } while (0)
; #define PG8_WAIT_V(n) asm volatile("s_waitcnt vmcnt(" #n ")" ::: "memory")
; #define PG8_WAIT_L(n) asm volatile("s_waitcnt lgkmcnt(" #n ")" ::: "memory")
; #define PG8_BAR __builtin_amdgcn_s_barrier()
; #define PG8_SCHED __builtin_amdgcn_sched_barrier(0)
; template <class Epi, class Sched, bool ALIGN_EPI = false, bool SP2 = false>
; __device__ __forceinline__ void gemm_phase(PG8_LAS unsigned char* lds, const Gemm g, const Sched& S, const Epi& E, int wid_s_) {
;     ...
;             PG8_LDB(B0, 1, 0); PG8_LDB(B1, 1, 1); PG8_SCHED; PG8_LDA(At, 1, 0); PG8_STAGE(PG8_SA(0, 1), a2 + hstep, voffA);
;             PG8_WAIT_V(8); PG8_WAIT_L(0); PG8_BAR; PG8_MMA(0, 0, At, B0); PG8_MMA(0, 1, At, B1); PG8_BAR; PG8_SCHED;
;             PG8_LDA(At, 1, 1); PG8_STAGE(PG8_SB(1, 0), b3, voffB); PG8_STAGE(PG8_SB(1, 1), b3 + hstep, voffB); PG8_STAGE(PG8_SA(1, 0), a3, voffA);
;             PG8_WAIT_V(8); PG8_WAIT_L(0); PG8_BAR; PG8_MMA(1, 0, At, B0); PG8_MMA(1, 1, At, B1); PG8_BAR; PG8_SCHED;
	s_add_i32 s10, 16, 0x18000
	s_add_i32 s11, 16, 0x1c000
	v_add_u32_e32 v158, s10, v147
	v_add_u32_e32 v174, s11, v147
	ds_read_b128 v[130:133], v158
	ds_read_b128 v[134:137], v158 offset:1024
	ds_read_b128 v[154:157], v158 offset:2048
	ds_read_b128 v[158:161], v158 offset:3072
	ds_read_b128 v[162:165], v174
	ds_read_b128 v[166:169], v174 offset:1024
	ds_read_b128 v[170:173], v174 offset:2048
	ds_read_b128 v[174:177], v174 offset:3072
	s_mov_b32 m0, s50
	ds_read_b128 v[180:183], v149 offset:32768
	ds_read_b128 v[196:199], v149 offset:33792
	ds_read_b128 v[200:203], v149 offset:34816
	ds_read_b128 v[204:207], v149 offset:35840
	ds_read_b128 v[208:211], v149 offset:36864
	ds_read_b128 v[212:215], v149 offset:37888
	ds_read_b128 v[216:219], v149 offset:38912
	ds_read_b128 v[220:223], v149 offset:39936
	global_load_lds_dwordx4 v179, s[22:23]
	s_mov_b32 m0, s51
	s_nop 0
	global_load_lds_dwordx4 v188, s[22:23]
	s_waitcnt vmcnt(8)
	s_waitcnt lgkmcnt(0)
	s_barrier
	s_setprio 1
	s_waitcnt lgkmcnt(0)
	v_mfma_f32_16x16x32_bf16 v[126:129], v[130:133], v[180:183], v[126:129]
	v_mfma_f32_16x16x32_bf16 v[122:125], v[154:157], v[180:183], v[122:125]
	v_mfma_f32_16x16x32_bf16 v[118:121], v[130:133], v[200:203], v[118:121]
	v_mfma_f32_16x16x32_bf16 v[114:117], v[154:157], v[200:203], v[114:117]
	v_mfma_f32_16x16x32_bf16 v[110:113], v[130:133], v[208:211], v[110:113]
	v_mfma_f32_16x16x32_bf16 v[106:109], v[154:157], v[208:211], v[106:109]
	v_mfma_f32_16x16x32_bf16 v[102:105], v[130:133], v[216:219], v[102:105]
	v_mfma_f32_16x16x32_bf16 v[98:101], v[154:157], v[216:219], v[98:101]
	v_mfma_f32_16x16x32_bf16 v[126:129], v[134:137], v[196:199], v[126:129]
	v_mfma_f32_16x16x32_bf16 v[122:125], v[158:161], v[196:199], v[122:125]
	v_mfma_f32_16x16x32_bf16 v[118:121], v[134:137], v[204:207], v[118:121]
	v_mfma_f32_16x16x32_bf16 v[114:117], v[158:161], v[204:207], v[114:117]
	v_mfma_f32_16x16x32_bf16 v[110:113], v[134:137], v[212:215], v[110:113]
	v_mfma_f32_16x16x32_bf16 v[106:109], v[158:161], v[212:215], v[106:109]
	v_mfma_f32_16x16x32_bf16 v[102:105], v[134:137], v[220:223], v[102:105]
	v_mfma_f32_16x16x32_bf16 v[98:101], v[158:161], v[220:223], v[98:101]
	v_mfma_f32_16x16x32_bf16 v[60:63], v[162:165], v[180:183], v[60:63]
	v_mfma_f32_16x16x32_bf16 v[56:59], v[170:173], v[180:183], v[56:59]
	v_mfma_f32_16x16x32_bf16 v[52:55], v[162:165], v[200:203], v[52:55]
	v_mfma_f32_16x16x32_bf16 v[48:51], v[170:173], v[200:203], v[48:51]
	v_mfma_f32_16x16x32_bf16 v[44:47], v[162:165], v[208:211], v[44:47]
	v_mfma_f32_16x16x32_bf16 v[40:43], v[170:173], v[208:211], v[40:43]
	v_mfma_f32_16x16x32_bf16 v[36:39], v[162:165], v[216:219], v[36:39]
	v_mfma_f32_16x16x32_bf16 v[32:35], v[170:173], v[216:219], v[32:35]
	v_mfma_f32_16x16x32_bf16 v[60:63], v[166:169], v[196:199], v[60:63]
	v_mfma_f32_16x16x32_bf16 v[56:59], v[174:177], v[196:199], v[56:59]
	v_mfma_f32_16x16x32_bf16 v[52:55], v[166:169], v[204:207], v[52:55]
	v_mfma_f32_16x16x32_bf16 v[48:51], v[174:177], v[204:207], v[48:51]
	v_mfma_f32_16x16x32_bf16 v[44:47], v[166:169], v[212:215], v[44:47]
	v_mfma_f32_16x16x32_bf16 v[40:43], v[174:177], v[212:215], v[40:43]
	v_mfma_f32_16x16x32_bf16 v[36:39], v[166:169], v[220:223], v[36:39]
	v_mfma_f32_16x16x32_bf16 v[32:35], v[174:177], v[220:223], v[32:35]
	s_setprio 0
	s_barrier
	s_add_i32 s10, s10, s41
	s_mov_b32 m0, s10
	ds_read_b128 v[180:183], v149 offset:49152
	ds_read_b128 v[196:199], v149 offset:50176
	ds_read_b128 v[200:203], v149 offset:51200
	ds_read_b128 v[204:207], v149 offset:52224
	ds_read_b128 v[208:211], v149 offset:53248
	ds_read_b128 v[212:215], v149 offset:54272
	ds_read_b128 v[216:219], v149 offset:55296
	ds_read_b128 v[220:223], v149 offset:56320
	global_load_lds_dwordx4 v189, s[78:79]
	s_add_i32 m0, s10, 0x2000
	s_add_i32 s10, s11, s41
	global_load_lds_dwordx4 v194, s[78:79]
	s_mov_b32 m0, s10
	s_nop 0
	global_load_lds_dwordx4 v195, s[78:79]
	s_add_i32 m0, s10, 0x2000
	s_nop 0
	global_load_lds_dwordx4 v224, s[78:79]
	s_mov_b32 m0, s81
	s_nop 0
	global_load_lds_dwordx4 v225, s[22:23]
	s_mov_b32 m0, s82
	s_nop 0
	global_load_lds_dwordx4 v226, s[22:23]
	s_waitcnt vmcnt(8)
	s_waitcnt lgkmcnt(0)
	s_barrier
	s_setprio 1
	s_waitcnt lgkmcnt(0)
	v_mfma_f32_16x16x32_bf16 v[92:95], v[130:133], v[180:183], v[92:95]
	v_mfma_f32_16x16x32_bf16 v[88:91], v[154:157], v[180:183], v[88:91]
	v_mfma_f32_16x16x32_bf16 v[84:87], v[130:133], v[200:203], v[84:87]
	v_mfma_f32_16x16x32_bf16 v[80:83], v[154:157], v[200:203], v[80:83]
	v_mfma_f32_16x16x32_bf16 v[76:79], v[130:133], v[208:211], v[76:79]
	v_mfma_f32_16x16x32_bf16 v[72:75], v[154:157], v[208:211], v[72:75]
	v_mfma_f32_16x16x32_bf16 v[68:71], v[130:133], v[216:219], v[68:71]
	v_mfma_f32_16x16x32_bf16 v[64:67], v[154:157], v[216:219], v[64:67]
	v_mfma_f32_16x16x32_bf16 v[92:95], v[134:137], v[196:199], v[92:95]
	v_mfma_f32_16x16x32_bf16 v[88:91], v[158:161], v[196:199], v[88:91]
	v_mfma_f32_16x16x32_bf16 v[84:87], v[134:137], v[204:207], v[84:87]
	v_mfma_f32_16x16x32_bf16 v[80:83], v[158:161], v[204:207], v[80:83]
	v_mfma_f32_16x16x32_bf16 v[76:79], v[134:137], v[212:215], v[76:79]
	v_mfma_f32_16x16x32_bf16 v[72:75], v[158:161], v[212:215], v[72:75]
	v_mfma_f32_16x16x32_bf16 v[68:71], v[134:137], v[220:223], v[68:71]
	v_mfma_f32_16x16x32_bf16 v[64:67], v[158:161], v[220:223], v[64:67]
	v_mfma_f32_16x16x32_bf16 v[28:31], v[162:165], v[180:183], v[28:31]
	v_mfma_f32_16x16x32_bf16 v[24:27], v[170:173], v[180:183], v[24:27]
	v_mfma_f32_16x16x32_bf16 v[20:23], v[162:165], v[200:203], v[20:23]
	v_mfma_f32_16x16x32_bf16 v[16:19], v[170:173], v[200:203], v[16:19]
	v_mfma_f32_16x16x32_bf16 v[12:15], v[162:165], v[208:211], v[12:15]
	v_mfma_f32_16x16x32_bf16 v[8:11], v[170:173], v[208:211], v[8:11]
	v_mfma_f32_16x16x32_bf16 v[4:7], v[162:165], v[216:219], v[4:7]
	v_mfma_f32_16x16x32_bf16 v[0:3], v[170:173], v[216:219], v[0:3]
	v_mfma_f32_16x16x32_bf16 v[28:31], v[166:169], v[196:199], v[28:31]
	v_mfma_f32_16x16x32_bf16 v[24:27], v[174:177], v[196:199], v[24:27]
	v_mfma_f32_16x16x32_bf16 v[20:23], v[166:169], v[204:207], v[20:23]
	v_mfma_f32_16x16x32_bf16 v[16:19], v[174:177], v[204:207], v[16:19]
	v_mfma_f32_16x16x32_bf16 v[12:15], v[166:169], v[212:215], v[12:15]
	v_mfma_f32_16x16x32_bf16 v[8:11], v[174:177], v[212:215], v[8:11]
	v_mfma_f32_16x16x32_bf16 v[4:7], v[166:169], v[220:223], v[4:7]
	v_mfma_f32_16x16x32_bf16 v[0:3], v[174:177], v[220:223], v[0:3]
	s_setprio 0
	s_barrier
	s_add_u32 s90, s90, 0x100
	s_addc_u32 s91, s91, 0
	s_add_u32 s20, s20, 0x100
	s_addc_u32 s21, s21, 0
	s_cmp_ge_i32 vcc_lo, s80
	s_mov_b32 s22, vcc_lo
	s_cbranch_scc0 .LBB0_1393
